# de-serialized load-wait-store chains: C/S item epilogues, A/B item param preload + no drains, GEMM2 residual epilogue loads hoisted
# speedup vs baseline: 1.4458x; 1.4458x over previous
.LBB0_779:
	v_mov_b32_e32 v43, v0
	s_ashr_i32 s5, s3, 31
	v_ashrrev_i32_e32 v44, 7, v43
	s_waitcnt vmcnt(2)
	v_add_u32_e32 v164, s2, v44
	v_ashrrev_i32_e32 v165, 31, v164
	v_and_b32_e32 v168, 31, v43
	s_waitcnt vmcnt(0)
	v_lshlrev_b64 v[2:3], 15, v[164:165]
	v_bfe_u32 v169, v43, 5, 1
	v_lshl_add_u64 v[2:3], s[56:57], 0, v[2:3]
	v_lshlrev_b32_e32 v154, 8, v168
	v_lshl_add_u64 v[2:3], v[2:3], 0, v[154:155]
	v_lshlrev_b32_e32 v154, 4, v169
	v_lshl_add_u64 v[18:19], v[2:3], 0, v[154:155]
	v_add_co_u32_e32 v20, vcc, s14, v18
	v_ashrrev_i32_e32 v45, 2, v43
	s_nop 0
	v_addc_co_u32_e32 v21, vcc, 0, v19, vcc
	v_add_co_u32_e32 v22, vcc, s17, v18
	global_load_dwordx4 v[2:5], v[18:19], off
	global_load_dwordx4 v[6:9], v[20:21], off
	v_addc_co_u32_e32 v23, vcc, 0, v19, vcc
	v_add_co_u32_e32 v24, vcc, s30, v18
	global_load_dwordx4 v[10:13], v[22:23], off
	s_nop 0
	v_addc_co_u32_e32 v25, vcc, 0, v19, vcc
	global_load_dwordx4 v[14:17], v[24:25], off
	global_load_dwordx4 v[138:141], v[18:19], off offset:32
	global_load_dwordx4 v[142:145], v[20:21], off offset:32
	global_load_dwordx4 v[146:149], v[22:23], off offset:32
	global_load_dwordx4 v[150:153], v[24:25], off offset:32
	global_load_dwordx4 v[126:129], v[20:21], off offset:64
	global_load_dwordx4 v[130:133], v[22:23], off offset:64
	global_load_dwordx4 v[134:137], v[24:25], off offset:64
	global_load_dwordx4 v[114:117], v[20:21], off offset:96
	global_load_dwordx4 v[118:121], v[22:23], off offset:96
	global_load_dwordx4 v[122:125], v[24:25], off offset:96
	global_load_dwordx4 v[106:109], v[22:23], off offset:128
	global_load_dwordx4 v[110:113], v[24:25], off offset:128
	global_load_dwordx4 v[98:101], v[22:23], off offset:160
	global_load_dwordx4 v[102:105], v[24:25], off offset:160
	global_load_dwordx4 v[94:97], v[24:25], off offset:192
	global_load_dwordx4 v[90:93], v[24:25], off offset:224
	v_add_u32_e32 v18, s3, v45
	v_ashrrev_i32_e32 v19, 31, v18
	v_lshlrev_b32_e32 v20, 6, v43
	v_lshlrev_b64 v[18:19], 12, v[18:19]
	v_and_b32_e32 v46, 0xc0, v20
	v_lshl_add_u64 v[18:19], s[60:61], 0, v[18:19]
	v_lshlrev_b32_e32 v20, 1, v46
	v_mov_b32_e32 v21, v155
	v_lshl_add_u64 v[34:35], v[18:19], 0, v[20:21]
	global_load_dwordx4 v[18:21], v[34:35], off offset:3632
	global_load_dwordx4 v[22:25], v[34:35], off offset:3616
	global_load_dwordx4 v[26:29], v[34:35], off offset:3600
	global_load_dwordx4 v[30:33], v[34:35], off offset:3584
	global_load_dwordx4 v[36:39], v[34:35], off offset:3680
	global_load_dwordx4 v[202:205], v[34:35], off offset:3664
	global_load_dwordx4 v[48:51], v[34:35], off offset:3648
	global_load_dwordx4 v[206:209], v[34:35], off offset:3696
	v_lshrrev_b32_e32 v42, 5, v43
	s_add_i32 s4, s4, s46
	s_waitcnt vmcnt(7)
	v_lshlrev_b32_e32 v178, 16, v18
	s_waitcnt vmcnt(6)
	v_lshlrev_b32_e32 v186, 16, v22
	s_waitcnt vmcnt(5)
	v_lshlrev_b32_e32 v194, 16, v26
	s_waitcnt vmcnt(4)
	v_lshlrev_b32_e32 v200, 16, v30
	v_and_b32_e32 v199, 0xffff0000, v30
	v_add_f32_e32 v30, 0, v200
	v_lshlrev_b32_e32 v198, 16, v31
	v_add_f32_e32 v30, v30, v199
	v_and_b32_e32 v197, 0xffff0000, v31
	v_mul_f32_e32 v31, v199, v199
	v_add_f32_e32 v30, v30, v198
	v_lshlrev_b32_e32 v196, 16, v32
	v_fmac_f32_e32 v31, v200, v200
	v_add_f32_e32 v30, v30, v197
	v_and_b32_e32 v195, 0xffff0000, v32
	v_fmac_f32_e32 v31, v198, v198
	v_add_f32_e32 v30, v30, v196
	v_lshlrev_b32_e32 v193, 16, v33
	v_fmac_f32_e32 v31, v197, v197
	v_add_f32_e32 v30, v30, v195
	v_and_b32_e32 v191, 0xffff0000, v33
	v_fmac_f32_e32 v31, v196, v196
	v_add_f32_e32 v30, v30, v193
	v_fmac_f32_e32 v31, v195, v195
	v_add_f32_e32 v30, v30, v191
	v_fmac_f32_e32 v31, v193, v193
	v_and_b32_e32 v192, 0xffff0000, v26
	v_add_f32_e32 v26, v30, v194
	v_fmac_f32_e32 v31, v191, v191
	v_lshlrev_b32_e32 v190, 16, v27
	v_add_f32_e32 v26, v26, v192
	v_and_b32_e32 v189, 0xffff0000, v27
	v_fmac_f32_e32 v31, v194, v194
	v_add_f32_e32 v26, v26, v190
	v_lshlrev_b32_e32 v188, 16, v28
	v_fmac_f32_e32 v31, v192, v192
	v_add_f32_e32 v26, v26, v189
	v_and_b32_e32 v187, 0xffff0000, v28
	v_fmac_f32_e32 v31, v190, v190
	v_add_f32_e32 v26, v26, v188
	v_lshlrev_b32_e32 v184, 16, v29
	v_fmac_f32_e32 v31, v189, v189
	v_add_f32_e32 v26, v26, v187
	v_and_b32_e32 v182, 0xffff0000, v29
	v_fmac_f32_e32 v31, v188, v188
	v_add_f32_e32 v26, v26, v184
	v_fmac_f32_e32 v31, v187, v187
	v_add_f32_e32 v26, v26, v182
	v_fmac_f32_e32 v31, v184, v184
	v_and_b32_e32 v185, 0xffff0000, v22
	v_add_f32_e32 v22, v26, v186
	v_fmac_f32_e32 v31, v182, v182
	v_lshlrev_b32_e32 v183, 16, v23
	v_add_f32_e32 v22, v22, v185
	v_and_b32_e32 v179, 0xffff0000, v23
	v_fmac_f32_e32 v31, v186, v186
	v_add_f32_e32 v22, v22, v183
	v_lshlrev_b32_e32 v177, 16, v24
	v_fmac_f32_e32 v31, v185, v185
	v_add_f32_e32 v22, v22, v179
	v_and_b32_e32 v175, 0xffff0000, v24
	v_fmac_f32_e32 v31, v183, v183
	v_add_f32_e32 v22, v22, v177
	v_lshlrev_b32_e32 v173, 16, v25
	v_fmac_f32_e32 v31, v179, v179
	v_add_f32_e32 v22, v22, v175
	v_and_b32_e32 v171, 0xffff0000, v25
	v_fmac_f32_e32 v31, v177, v177
	v_add_f32_e32 v22, v22, v173
	v_fmac_f32_e32 v31, v175, v175
	v_add_f32_e32 v22, v22, v171
	v_fmac_f32_e32 v31, v173, v173
	v_and_b32_e32 v176, 0xffff0000, v18
	v_add_f32_e32 v18, v22, v178
	v_fmac_f32_e32 v31, v171, v171
	v_lshlrev_b32_e32 v174, 16, v19
	v_add_f32_e32 v18, v18, v176
	v_and_b32_e32 v172, 0xffff0000, v19
	v_fmac_f32_e32 v31, v178, v178
	v_add_f32_e32 v18, v18, v174
	v_lshlrev_b32_e32 v167, 16, v20
	v_fmac_f32_e32 v31, v176, v176
	v_add_f32_e32 v18, v18, v172
	v_and_b32_e32 v165, 0xffff0000, v20
	v_fmac_f32_e32 v31, v174, v174
	v_add_f32_e32 v18, v18, v167
	v_lshlrev_b32_e32 v64, 16, v21
	v_fmac_f32_e32 v31, v172, v172
	v_add_f32_e32 v18, v18, v165
	v_and_b32_e32 v62, 0xffff0000, v21
	v_fmac_f32_e32 v31, v167, v167
	v_add_f32_e32 v18, v18, v64
	v_fmac_f32_e32 v31, v165, v165
	v_add_f32_e32 v18, v18, v62
	s_waitcnt vmcnt(1)
	v_lshlrev_b32_e32 v170, 16, v48
	v_fmac_f32_e32 v31, v64, v64
	v_and_b32_e32 v166, 0xffff0000, v48
	v_add_f32_e32 v18, v18, v170
	v_fmac_f32_e32 v31, v62, v62
	v_lshlrev_b32_e32 v65, 16, v49
	v_add_f32_e32 v18, v18, v166
	v_and_b32_e32 v63, 0xffff0000, v49
	v_fmac_f32_e32 v31, v170, v170
	v_add_f32_e32 v18, v18, v65
	v_lshlrev_b32_e32 v60, 16, v50
	v_fmac_f32_e32 v31, v166, v166
	v_add_f32_e32 v18, v18, v63
	v_and_b32_e32 v59, 0xffff0000, v50
	v_fmac_f32_e32 v31, v65, v65
	v_add_f32_e32 v18, v18, v60
	v_lshlrev_b32_e32 v57, 16, v51
	v_fmac_f32_e32 v31, v63, v63
	v_add_f32_e32 v18, v18, v59
	v_and_b32_e32 v55, 0xffff0000, v51
	v_fmac_f32_e32 v31, v60, v60
	v_add_f32_e32 v18, v18, v57
	v_fmac_f32_e32 v31, v59, v59
	v_add_f32_e32 v18, v18, v55
	v_lshlrev_b32_e32 v61, 16, v202
	v_fmac_f32_e32 v31, v57, v57
	v_and_b32_e32 v58, 0xffff0000, v202
	v_add_f32_e32 v18, v18, v61
	v_fmac_f32_e32 v31, v55, v55
	v_lshlrev_b32_e32 v56, 16, v203
	v_add_f32_e32 v18, v18, v58
	v_and_b32_e32 v54, 0xffff0000, v203
	v_fmac_f32_e32 v31, v61, v61
	v_add_f32_e32 v18, v18, v56
	v_lshlrev_b32_e32 v53, 16, v204
	v_fmac_f32_e32 v31, v58, v58
	v_add_f32_e32 v18, v18, v54
	v_and_b32_e32 v51, 0xffff0000, v204
	v_fmac_f32_e32 v31, v56, v56
	v_add_f32_e32 v18, v18, v53
	v_lshlrev_b32_e32 v49, 16, v205
	v_fmac_f32_e32 v31, v54, v54
	v_add_f32_e32 v18, v18, v51
	v_and_b32_e32 v47, 0xffff0000, v205
	v_fmac_f32_e32 v31, v53, v53
	v_add_f32_e32 v18, v18, v49
	v_fmac_f32_e32 v31, v51, v51
	v_add_f32_e32 v18, v18, v47
	v_lshlrev_b32_e32 v52, 16, v36
	v_fmac_f32_e32 v31, v49, v49
	v_and_b32_e32 v50, 0xffff0000, v36
	v_add_f32_e32 v18, v18, v52
	v_fmac_f32_e32 v31, v47, v47
	v_lshlrev_b32_e32 v48, 16, v37
	v_add_f32_e32 v18, v18, v50
	v_fmac_f32_e32 v31, v52, v52
	v_add_f32_e32 v18, v18, v48
	v_and_b32_e32 v37, 0xffff0000, v37
	v_fmac_f32_e32 v31, v50, v50
	v_lshlrev_b32_e32 v34, 16, v38
	v_mov_b32_e32 v35, v37
	v_add_f32_e32 v20, v18, v37
	v_fmac_f32_e32 v31, v48, v48
	v_and_b32_e32 v24, 0xffff0000, v38
	v_pk_mul_f32 v[18:19], v[34:35], v[34:35]
	v_add_f32_e32 v20, v20, v34
	v_lshlrev_b32_e32 v25, 16, v39
	v_add_f32_e32 v19, v19, v31
	v_add_f32_e32 v20, v20, v24
	v_add_f32_e32 v21, v18, v19
	v_pk_mul_f32 v[18:19], v[24:25], v[24:25]
	v_add_f32_e32 v20, v20, v25
	v_and_b32_e32 v33, 0xffff0000, v39
	v_add_f32_e32 v18, v18, v21
	s_waitcnt vmcnt(0)
	v_lshlrev_b32_e32 v28, 16, v206
	v_mov_b32_e32 v29, v33
	v_add_f32_e32 v20, v20, v33
	v_add_f32_e32 v21, v19, v18
	v_and_b32_e32 v22, 0xffff0000, v206
	v_pk_mul_f32 v[18:19], v[28:29], v[28:29]
	v_add_f32_e32 v20, v20, v28
	v_lshlrev_b32_e32 v23, 16, v207
	v_add_f32_e32 v19, v19, v21
	v_add_f32_e32 v20, v20, v22
	v_add_f32_e32 v21, v18, v19
	v_pk_mul_f32 v[18:19], v[22:23], v[22:23]
	v_add_f32_e32 v29, v20, v23
	v_and_b32_e32 v31, 0xffff0000, v207
	v_add_f32_e32 v18, v18, v21
	v_lshlrev_b32_e32 v26, 16, v208
	v_mov_b32_e32 v27, v31
	v_add_f32_e32 v29, v29, v31
	v_and_b32_e32 v36, s0, v38
	v_add_f32_e32 v18, v19, v18
	v_and_b32_e32 v20, 0xffff0000, v208
	v_pk_mul_f32 v[38:39], v[26:27], v[26:27]
	v_add_f32_e32 v27, v29, v26
	v_lshlrev_b32_e32 v21, 16, v209
	v_add_f32_e32 v18, v39, v18
	v_add_f32_e32 v27, v27, v20
	v_and_b32_e32 v29, 64, v181
	v_add_f32_e32 v18, v38, v18
	v_pk_mul_f32 v[40:41], v[20:21], v[20:21]
	v_add_f32_e32 v39, v27, v21
	v_xor_b32_e32 v27, 1, v181
	v_add_u32_e32 v29, 64, v29
	v_and_b32_e32 v19, 0xffff0000, v209
	v_add_f32_e32 v18, v40, v18
	v_cmp_lt_i32_e32 vcc, v27, v29
	v_add_f32_e32 v18, v41, v18
	v_mul_f32_e32 v38, v19, v19
	v_cndmask_b32_e32 v27, v181, v27, vcc
	v_lshlrev_b32_e32 v27, 2, v27
	v_pk_add_f32 v[38:39], v[38:39], v[18:19]
	ds_bpermute_b32 v41, v27, v39
	ds_bpermute_b32 v40, v27, v38
	v_xor_b32_e32 v35, 2, v181
	v_cmp_lt_i32_e32 vcc, v35, v29
	v_and_b32_e32 v30, s0, v206
	v_mov_b32_e32 v32, v36
	v_cndmask_b32_e32 v29, v181, v35, vcc
	v_lshlrev_b32_e32 v29, 2, v29
	s_waitcnt lgkmcnt(0)
	v_pk_add_f32 v[38:39], v[38:39], v[40:41]
	ds_bpermute_b32 v41, v29, v39
	ds_bpermute_b32 v40, v29, v38
	s_waitcnt lgkmcnt(0)
	v_pk_add_f32 v[40:41], v[38:39], v[40:41]
	s_nop 0
	v_pk_mul_f32 v[38:39], v[40:41], s[22:23] op_sel_hi:[1,0]
	v_pk_fma_f32 v[36:37], v[40:41], s[22:23], v[36:37] op_sel_hi:[1,0,1] neg_lo:[1,0,0] neg_hi:[1,0,0]
	v_fma_f32 v18, -v39, v39, v38
	v_max_f32_e32 v18, 0, v18
	v_add_f32_e32 v18, 0x358637bd, v18
	v_cmp_gt_f32_e32 vcc, s33, v18
	v_mul_f32_e32 v27, 0x4b800000, v18
	v_sub_f32_e32 v29, v200, v39
	v_cndmask_b32_e32 v18, v18, v27, vcc
	v_rsq_f32_e32 v18, v18
	v_sub_f32_e32 v19, v19, v39
	v_mul_f32_e32 v27, 0x45800000, v18
	v_cndmask_b32_e32 v18, v18, v27, vcc
	v_mul_f32_e32 v29, v29, v18
	v_lshlrev_b32_e32 v27, 1, v45
	v_bfe_u32 v35, v29, 16, 1
	v_ashrrev_i32_e32 v45, 1, v43
	v_and_b32_e32 v27, 14, v27
	v_add3_u32 v29, v29, v35, s15
	v_lshl_add_u32 v35, v46, 8, 32
	v_and_b32_e32 v46, -16, v45
	v_add3_u32 v200, v35, v46, v27
	ds_write_b16_d16_hi v200, v29 offset:55296
	v_sub_f32_e32 v29, v199, v39
	v_mul_f32_e32 v29, v29, v18
	v_bfe_u32 v199, v29, 16, 1
	v_add3_u32 v29, v29, v199, s15
	v_bitop3_b32 v199, v45, 16, -16 bitop3:0x6c
	v_add3_u32 v201, v35, v199, v27
	ds_write_b16_d16_hi v201, v29 offset:55552
	v_sub_f32_e32 v29, v198, v39
	v_mul_f32_e32 v29, v29, v18
	v_bfe_u32 v198, v29, 16, 1
	v_add3_u32 v29, v29, v198, s15
	v_bitop3_b32 v198, v45, 32, -16 bitop3:0x6c
	v_add3_u32 v202, v35, v198, v27
	ds_write_b16_d16_hi v202, v29 offset:55808
	v_sub_f32_e32 v29, v197, v39
	v_mul_f32_e32 v29, v29, v18
	v_bfe_u32 v197, v29, 16, 1
	v_add3_u32 v29, v29, v197, s15
	v_bitop3_b32 v197, v45, 48, -16 bitop3:0x6c
	v_add3_u32 v203, v35, v197, v27
	ds_write_b16_d16_hi v203, v29 offset:56064
	v_sub_f32_e32 v29, v196, v39
	v_mul_f32_e32 v29, v29, v18
	v_bfe_u32 v196, v29, 16, 1
	v_add3_u32 v29, v29, v196, s15
	v_bitop3_b32 v196, v45, 64, -16 bitop3:0x6c
	v_add3_u32 v204, v35, v196, v27
	ds_write_b16_d16_hi v204, v29 offset:56320
	v_sub_f32_e32 v29, v195, v39
	v_mul_f32_e32 v29, v29, v18
	v_bfe_u32 v195, v29, 16, 1
	v_add3_u32 v29, v29, v195, s15
	v_bitop3_b32 v195, v45, s34, -16 bitop3:0x6c
	v_add3_u32 v205, v35, v195, v27
	ds_write_b16_d16_hi v205, v29 offset:56576
	v_sub_f32_e32 v29, v193, v39
	v_mul_f32_e32 v29, v29, v18
	v_bfe_u32 v193, v29, 16, 1
	v_add3_u32 v29, v29, v193, s15
	v_bitop3_b32 v193, v45, s31, -16 bitop3:0x6c
	v_add3_u32 v206, v35, v193, v27
	ds_write_b16_d16_hi v206, v29 offset:56832
	v_sub_f32_e32 v29, v191, v39
	v_mul_f32_e32 v29, v29, v18
	v_bfe_u32 v191, v29, 16, 1
	v_add3_u32 v29, v29, v191, s15
	v_bitop3_b32 v191, v45, s13, -16 bitop3:0x6c
	v_add3_u32 v207, v35, v191, v27
	ds_write_b16_d16_hi v207, v29 offset:57088
	v_sub_f32_e32 v29, v194, v39
	v_mul_f32_e32 v29, v29, v18
	v_bfe_u32 v194, v29, 16, 1
	v_add3_u32 v29, v29, v194, s15
	v_bitop3_b32 v194, v45, s12, -16 bitop3:0x6c
	v_add3_u32 v208, v35, v194, v27
	ds_write_b16_d16_hi v208, v29 offset:57344
	v_sub_f32_e32 v29, v192, v39
	v_mul_f32_e32 v29, v29, v18
	v_bfe_u32 v192, v29, 16, 1
	v_add3_u32 v29, v29, v192, s15
	v_bitop3_b32 v192, v45, s35, -16 bitop3:0x6c
	v_add3_u32 v209, v35, v192, v27
	ds_write_b16_d16_hi v209, v29 offset:57600
	v_sub_f32_e32 v29, v190, v39
	v_mul_f32_e32 v29, v29, v18
	v_bfe_u32 v190, v29, 16, 1
	v_add3_u32 v29, v29, v190, s15
	v_bitop3_b32 v190, v45, s36, -16 bitop3:0x6c
	v_add3_u32 v210, v35, v190, v27
	ds_write_b16_d16_hi v210, v29 offset:57856
	v_sub_f32_e32 v29, v189, v39
	v_mul_f32_e32 v29, v29, v18
	v_bfe_u32 v189, v29, 16, 1
	v_add3_u32 v29, v29, v189, s15
	v_bitop3_b32 v189, v45, s37, -16 bitop3:0x6c
	v_add3_u32 v211, v35, v189, v27
	ds_write_b16_d16_hi v211, v29 offset:58112
	v_sub_f32_e32 v29, v188, v39
	v_mul_f32_e32 v29, v29, v18
	v_bfe_u32 v188, v29, 16, 1
	v_add3_u32 v29, v29, v188, s15
	v_bitop3_b32 v188, v45, s16, -16 bitop3:0x6c
	v_add3_u32 v212, v35, v188, v27
	ds_write_b16_d16_hi v212, v29 offset:58368
	v_sub_f32_e32 v29, v187, v39
	v_mul_f32_e32 v29, v29, v18
	v_bfe_u32 v187, v29, 16, 1
	v_add3_u32 v29, v29, v187, s15
	v_bitop3_b32 v187, v45, s42, -16 bitop3:0x6c
	v_add3_u32 v213, v35, v187, v27
	ds_write_b16_d16_hi v213, v29 offset:58624
	v_sub_f32_e32 v29, v184, v39
	v_mul_f32_e32 v29, v29, v18
	v_bfe_u32 v184, v29, 16, 1
	v_add3_u32 v29, v29, v184, s15
	v_bitop3_b32 v184, v45, s43, -16 bitop3:0x6c
	v_add3_u32 v214, v35, v184, v27
	ds_write_b16_d16_hi v214, v29 offset:58880
	v_sub_f32_e32 v29, v182, v39
	v_mul_f32_e32 v29, v29, v18
	v_bfe_u32 v182, v29, 16, 1
	v_bitop3_b32 v45, v45, s94, -16 bitop3:0x6c
	v_add_u32_e32 v38, 0xd800, v35
	v_add3_u32 v29, v29, v182, s15
	v_add3_u32 v35, v35, v45, v27
	ds_write_b16_d16_hi v35, v29 offset:59136
	v_sub_f32_e32 v29, v186, v39
	v_mul_f32_e32 v29, v29, v18
	v_bfe_u32 v182, v29, 16, 1
	v_add3_u32 v29, v29, v182, s15
	ds_write_b16_d16_hi v200, v29 offset:59392
	v_sub_f32_e32 v29, v185, v39
	v_mul_f32_e32 v29, v29, v18
	v_bfe_u32 v182, v29, 16, 1
	v_add3_u32 v29, v29, v182, s15
	ds_write_b16_d16_hi v201, v29 offset:59648
	v_sub_f32_e32 v29, v183, v39
	v_mul_f32_e32 v29, v29, v18
	v_bfe_u32 v182, v29, 16, 1
	v_add3_u32 v29, v29, v182, s15
	ds_write_b16_d16_hi v202, v29 offset:59904
	v_sub_f32_e32 v29, v179, v39
	v_mul_f32_e32 v29, v29, v18
	v_bfe_u32 v179, v29, 16, 1
	v_add3_u32 v29, v29, v179, s15
	ds_write_b16_d16_hi v203, v29 offset:60160
	v_sub_f32_e32 v29, v177, v39
	v_mul_f32_e32 v29, v29, v18
	v_bfe_u32 v177, v29, 16, 1
	v_add3_u32 v29, v29, v177, s15
	ds_write_b16_d16_hi v204, v29 offset:60416
	v_sub_f32_e32 v29, v175, v39
	v_mul_f32_e32 v29, v29, v18
	v_bfe_u32 v175, v29, 16, 1
	v_add3_u32 v29, v29, v175, s15
	ds_write_b16_d16_hi v205, v29 offset:60672
	v_sub_f32_e32 v29, v173, v39
	v_mul_f32_e32 v29, v29, v18
	v_bfe_u32 v173, v29, 16, 1
	v_add3_u32 v29, v29, v173, s15
	ds_write_b16_d16_hi v206, v29 offset:60928
	v_sub_f32_e32 v29, v171, v39
	v_mul_f32_e32 v29, v29, v18
	v_bfe_u32 v171, v29, 16, 1
	v_add3_u32 v29, v29, v171, s15
	ds_write_b16_d16_hi v207, v29 offset:61184
	v_sub_f32_e32 v29, v178, v39
	v_mul_f32_e32 v29, v29, v18
	v_bfe_u32 v171, v29, 16, 1
	v_add3_u32 v29, v29, v171, s15
	ds_write_b16_d16_hi v208, v29 offset:61440
	v_sub_f32_e32 v29, v176, v39
	v_mul_f32_e32 v29, v29, v18
	v_bfe_u32 v171, v29, 16, 1
	v_add3_u32 v29, v29, v171, s15
	ds_write_b16_d16_hi v209, v29 offset:61696
	v_sub_f32_e32 v29, v174, v39
	v_mul_f32_e32 v29, v29, v18
	v_bfe_u32 v171, v29, 16, 1
	v_add3_u32 v29, v29, v171, s15
	ds_write_b16_d16_hi v210, v29 offset:61952
	v_sub_f32_e32 v29, v172, v39
	v_mul_f32_e32 v29, v29, v18
	v_bfe_u32 v171, v29, 16, 1
	v_add3_u32 v29, v29, v171, s15
	ds_write_b16_d16_hi v211, v29 offset:62208
	v_sub_f32_e32 v29, v167, v39
	v_mul_f32_e32 v29, v29, v18
	v_bfe_u32 v167, v29, 16, 1
	v_add3_u32 v29, v29, v167, s15
	ds_write_b16_d16_hi v212, v29 offset:62464
	v_sub_f32_e32 v29, v165, v39
	v_mul_f32_e32 v29, v29, v18
	v_bfe_u32 v165, v29, 16, 1
	v_add3_u32 v29, v29, v165, s15
	ds_write_b16_d16_hi v213, v29 offset:62720
	v_sub_f32_e32 v29, v64, v39
	v_mul_f32_e32 v29, v29, v18
	v_bfe_u32 v64, v29, 16, 1
	v_add3_u32 v29, v29, v64, s15
	ds_write_b16_d16_hi v214, v29 offset:62976
	v_sub_f32_e32 v29, v62, v39
	v_mul_f32_e32 v29, v29, v18
	v_bfe_u32 v62, v29, 16, 1
	v_add3_u32 v29, v29, v62, s15
	ds_write_b16_d16_hi v35, v29 offset:63232
	v_sub_f32_e32 v29, v170, v39
	v_mul_f32_e32 v29, v29, v18
	v_bfe_u32 v35, v29, 16, 1
	v_add3_u32 v29, v29, v35, s15
	ds_write_b16_d16_hi v200, v29 offset:63488
	v_sub_f32_e32 v29, v166, v39
	v_mul_f32_e32 v29, v29, v18
	v_bfe_u32 v35, v29, 16, 1
	v_add3_u32 v29, v29, v35, s15
	ds_write_b16_d16_hi v201, v29 offset:63744
	v_sub_f32_e32 v29, v65, v39
	v_mul_f32_e32 v29, v29, v18
	v_bfe_u32 v35, v29, 16, 1
	v_add3_u32 v29, v29, v35, s15
	ds_write_b16_d16_hi v202, v29 offset:64000
	v_sub_f32_e32 v29, v63, v39
	v_mul_f32_e32 v29, v29, v18
	v_bfe_u32 v35, v29, 16, 1
	v_add3_u32 v29, v29, v35, s15
	ds_write_b16_d16_hi v203, v29 offset:64256
	v_sub_f32_e32 v29, v60, v39
	v_mul_f32_e32 v29, v29, v18
	v_bfe_u32 v35, v29, 16, 1
	v_add3_u32 v29, v29, v35, s15
	ds_write_b16_d16_hi v204, v29 offset:64512
	v_sub_f32_e32 v29, v59, v39
	v_mul_f32_e32 v29, v29, v18
	v_bfe_u32 v35, v29, 16, 1
	v_add3_u32 v29, v29, v35, s15
	ds_write_b16_d16_hi v205, v29 offset:64768
	v_sub_f32_e32 v29, v57, v39
	v_mul_f32_e32 v29, v29, v18
	v_bfe_u32 v35, v29, 16, 1
	v_add3_u32 v29, v29, v35, s15
	ds_write_b16_d16_hi v206, v29 offset:65024
	v_sub_f32_e32 v29, v55, v39
	v_mul_f32_e32 v29, v29, v18
	v_bfe_u32 v35, v29, 16, 1
	v_add3_u32 v29, v29, v35, s15
	ds_write_b16_d16_hi v207, v29 offset:65280
	v_sub_f32_e32 v29, v61, v39
	v_mul_f32_e32 v29, v29, v18
	v_bfe_u32 v35, v29, 16, 1
	v_add3_u32 v29, v29, v35, s15
	v_add3_u32 v35, v38, v194, v27
	ds_write_b16_d16_hi v35, v29 offset:10240
	v_sub_f32_e32 v29, v58, v39
	v_mul_f32_e32 v29, v29, v18
	v_bfe_u32 v55, v29, 16, 1
	v_add3_u32 v29, v29, v55, s15
	v_add3_u32 v55, v38, v192, v27
	ds_write_b16_d16_hi v55, v29 offset:10496
	v_sub_f32_e32 v29, v56, v39
	v_mul_f32_e32 v29, v29, v18
	v_bfe_u32 v56, v29, 16, 1
	v_add3_u32 v29, v29, v56, s15
	v_add3_u32 v56, v38, v190, v27
	ds_write_b16_d16_hi v56, v29 offset:10752
	v_sub_f32_e32 v29, v54, v39
	v_mul_f32_e32 v29, v29, v18
	v_bfe_u32 v54, v29, 16, 1
	v_add3_u32 v29, v29, v54, s15
	v_add3_u32 v54, v38, v189, v27
	ds_write_b16_d16_hi v54, v29 offset:11008
	v_sub_f32_e32 v29, v53, v39
	v_mul_f32_e32 v29, v29, v18
	v_bfe_u32 v53, v29, 16, 1
	v_add3_u32 v29, v29, v53, s15
	v_add3_u32 v53, v38, v188, v27
	ds_write_b16_d16_hi v53, v29 offset:11264
	v_sub_f32_e32 v29, v51, v39
	v_mul_f32_e32 v29, v29, v18
	v_bfe_u32 v51, v29, 16, 1
	v_add3_u32 v29, v29, v51, s15
	v_add3_u32 v51, v38, v187, v27
	ds_write_b16_d16_hi v51, v29 offset:11520
	v_sub_f32_e32 v29, v49, v39
	v_mul_f32_e32 v29, v29, v18
	v_bfe_u32 v49, v29, 16, 1
	v_add3_u32 v29, v29, v49, s15
	v_add3_u32 v49, v38, v184, v27
	ds_write_b16_d16_hi v49, v29 offset:11776
	v_sub_f32_e32 v29, v47, v39
	v_mul_f32_e32 v29, v29, v18
	v_bfe_u32 v47, v29, 16, 1
	v_add3_u32 v29, v29, v47, s15
	v_add3_u32 v45, v38, v45, v27
	ds_write_b16_d16_hi v45, v29 offset:12032
	v_sub_f32_e32 v29, v52, v39
	v_mul_f32_e32 v29, v29, v18
	v_bfe_u32 v47, v29, 16, 1
	v_add3_u32 v29, v29, v47, s15
	v_add3_u32 v46, v38, v46, v27
	ds_write_b16_d16_hi v46, v29 offset:12288
	v_sub_f32_e32 v29, v50, v39
	v_mul_f32_e32 v29, v29, v18
	v_bfe_u32 v46, v29, 16, 1
	v_add3_u32 v29, v29, v46, s15
	v_add3_u32 v46, v38, v199, v27
	ds_write_b16_d16_hi v46, v29 offset:12544
	v_sub_f32_e32 v29, v48, v39
	v_mul_f32_e32 v29, v29, v18
	v_bfe_u32 v46, v29, 16, 1
	v_add3_u32 v29, v29, v46, s15
	v_add3_u32 v46, v38, v198, v27
	ds_write_b16_d16_hi v46, v29 offset:12800
	v_mul_f32_e32 v29, v37, v18
	v_bfe_u32 v36, v29, 16, 1
	v_add3_u32 v29, v29, v36, s15
	v_add3_u32 v36, v38, v197, v27
	ds_write_b16_d16_hi v36, v29 offset:13056
	v_sub_f32_e32 v29, v34, v39
	v_mul_f32_e32 v29, v29, v18
	v_bfe_u32 v34, v29, 16, 1
	v_add3_u32 v29, v29, v34, s15
	v_add3_u32 v34, v38, v196, v27
	ds_write_b16_d16_hi v34, v29 offset:13312
	v_sub_f32_e32 v29, v24, v39
	v_pk_fma_f32 v[24:25], v[40:41], s[22:23], v[24:25] op_sel_hi:[1,0,1] neg_lo:[1,0,0] neg_hi:[1,0,0]
	v_mul_f32_e32 v29, v29, v18
	v_mul_f32_e32 v24, v25, v18
	v_bfe_u32 v34, v29, 16, 1
	v_bfe_u32 v25, v24, 16, 1
	v_add3_u32 v29, v29, v34, s15
	v_add3_u32 v34, v38, v195, v27
	v_add3_u32 v24, v24, v25, s15
	v_add3_u32 v25, v38, v193, v27
	ds_write_b16_d16_hi v34, v29 offset:13568
	ds_write_b16_d16_hi v25, v24 offset:13824
	v_pk_fma_f32 v[24:25], v[40:41], s[22:23], v[32:33] op_sel_hi:[1,0,1] neg_lo:[1,0,0] neg_hi:[1,0,0]
	v_and_b32_e32 v167, 15, v43
	v_mul_f32_e32 v24, v25, v18
	v_bfe_u32 v25, v24, 16, 1
	v_add3_u32 v24, v24, v25, s15
	v_add3_u32 v25, v38, v191, v27
	ds_write_b16_d16_hi v25, v24 offset:14080
	v_sub_f32_e32 v24, v28, v39
	v_mul_f32_e32 v24, v24, v18
	v_bfe_u32 v25, v24, 16, 1
	v_add3_u32 v24, v24, v25, s15
	ds_write_b16_d16_hi v35, v24 offset:14336
	v_sub_f32_e32 v24, v22, v39
	v_pk_fma_f32 v[22:23], v[40:41], s[22:23], v[22:23] op_sel_hi:[1,0,1] neg_lo:[1,0,0] neg_hi:[1,0,0]
	v_mul_f32_e32 v24, v24, v18
	v_mul_f32_e32 v22, v23, v18
	v_bfe_u32 v25, v24, 16, 1
	v_bfe_u32 v23, v22, 16, 1
	v_add3_u32 v24, v24, v25, s15
	v_add3_u32 v22, v22, v23, s15
	ds_write_b16_d16_hi v55, v24 offset:14592
	ds_write_b16_d16_hi v56, v22 offset:14848
	v_pk_fma_f32 v[22:23], v[40:41], s[22:23], v[30:31] op_sel_hi:[1,0,1] neg_lo:[1,0,0] neg_hi:[1,0,0]
	s_nop 0
	v_mul_f32_e32 v22, v23, v18
	v_bfe_u32 v23, v22, 16, 1
	v_add3_u32 v22, v22, v23, s15
	ds_write_b16_d16_hi v54, v22 offset:15104
	v_sub_f32_e32 v22, v26, v39
	v_mul_f32_e32 v22, v22, v18
	v_bfe_u32 v23, v22, 16, 1
	v_add3_u32 v22, v22, v23, s15
	ds_write_b16_d16_hi v53, v22 offset:15360
	v_sub_f32_e32 v22, v20, v39
	v_pk_fma_f32 v[20:21], v[40:41], s[22:23], v[20:21] op_sel_hi:[1,0,1] neg_lo:[1,0,0] neg_hi:[1,0,0]
	v_mul_f32_e32 v22, v22, v18
	v_mul_f32_e32 v20, v21, v18
	v_mul_f32_e32 v18, v19, v18
	v_bfe_u32 v23, v22, 16, 1
	v_bfe_u32 v21, v20, 16, 1
	v_bfe_u32 v19, v18, 16, 1
	v_add3_u32 v22, v22, v23, s15
	v_add3_u32 v20, v20, v21, s15
	v_add3_u32 v18, v18, v19, s15
	ds_write_b16_d16_hi v51, v22 offset:15616
	ds_write_b16_d16_hi v49, v20 offset:15872
	ds_write_b16_d16_hi v45, v18 offset:16128
	v_lshrrev_b32_e32 v18, 1, v43
	v_and_b32_e32 v18, 32, v18
	v_lshl_or_b32 v166, v44, 6, v18
	v_or_b32_e32 v18, v166, v168
	v_lshl_add_u32 v165, v18, 8, 32
	v_bitop3_b32 v18, v42, v167, 1 bitop3:0x6c
	v_lshl_add_u32 v18, v18, 4, v165
	s_waitcnt lgkmcnt(0)
	s_barrier
	ds_read_b128 v[170:173], v18 offset:55296
	s_waitcnt lgkmcnt(0)
	v_mfma_f32_32x32x16_bf16 v[50:65], v[170:173], v[2:5], 0
	v_mfma_f32_32x32x16_bf16 v[34:49], v[170:173], v[6:9], 0
	v_mfma_f32_32x32x16_bf16 v[18:33], v[170:173], v[10:13], 0
	v_mfma_f32_32x32x16_bf16 v[2:17], v[170:173], v[14:17], 0
	v_bitop3_b32 v170, v169, v167, 2 bitop3:0x36
	v_lshl_add_u32 v170, v170, 4, v165
	ds_read_b128 v[170:173], v170 offset:55296
	s_waitcnt lgkmcnt(0)
	v_mfma_f32_32x32x16_bf16 v[50:65], v[170:173], v[138:141], v[50:65]
	v_bitop3_b32 v138, v169, v167, 4 bitop3:0x36
	v_lshl_add_u32 v138, v138, 4, v165
	ds_read_b128 v[138:141], v138 offset:55296
	v_mfma_f32_32x32x16_bf16 v[34:49], v[170:173], v[142:145], v[34:49]
	v_mfma_f32_32x32x16_bf16 v[18:33], v[170:173], v[146:149], v[18:33]
	s_waitcnt lgkmcnt(0)
	v_mfma_f32_32x32x16_bf16 v[34:49], v[138:141], v[126:129], v[34:49]
	v_bitop3_b32 v126, v169, v167, 6 bitop3:0x36
	v_lshl_add_u32 v126, v126, 4, v165
	ds_read_b128 v[126:129], v126 offset:55296
	v_mfma_f32_32x32x16_bf16 v[2:17], v[170:173], v[150:153], v[2:17]
	v_mfma_f32_32x32x16_bf16 v[18:33], v[138:141], v[130:133], v[18:33]
	s_waitcnt lgkmcnt(0)
	v_mfma_f32_32x32x16_bf16 v[34:49], v[126:129], v[114:117], v[34:49]
	v_bitop3_b32 v114, v169, v167, 8 bitop3:0x36
	v_lshl_add_u32 v114, v114, 4, v165
	ds_read_b128 v[114:117], v114 offset:55296
	v_mfma_f32_32x32x16_bf16 v[2:17], v[138:141], v[134:137], v[2:17]
	v_mfma_f32_32x32x16_bf16 v[18:33], v[126:129], v[118:121], v[18:33]
	v_mfma_f32_32x32x16_bf16 v[2:17], v[126:129], v[122:125], v[2:17]
	v_lshlrev_b32_e32 v128, 7, v164
	v_or_b32_e32 v126, v128, v168
	v_ashrrev_i32_e32 v127, 31, v126
	v_lshlrev_b64 v[130:131], 2, v[126:127]
	v_lshl_or_b32 v122, v169, 2, v166
	v_or_b32_e32 v124, s3, v168
	v_mov_b32_e32 v125, s5
	s_waitcnt lgkmcnt(0)
	v_mfma_f32_32x32x16_bf16 v[18:33], v[114:117], v[106:109], v[18:33]
	v_bitop3_b32 v106, v169, v167, 10 bitop3:0x36
	v_lshl_add_u32 v106, v106, 4, v165
	ds_read_b128 v[106:109], v106 offset:55296
	v_lshl_add_u64 v[132:133], s[6:7], 0, v[130:131]
	v_lshl_add_u64 v[130:131], s[92:93], 0, v[130:131]
	v_ashrrev_i32_e32 v123, 31, v122
	v_lshlrev_b64 v[122:123], 1, v[122:123]
	v_mfma_f32_32x32x16_bf16 v[2:17], v[114:117], v[110:113], v[2:17]
	s_add_i32 s3, s3, s18
	s_cmpk_gt_i32 s4, 0x7f
	s_waitcnt lgkmcnt(0)
	v_mfma_f32_32x32x16_bf16 v[18:33], v[106:109], v[98:101], v[18:33]
	v_bitop3_b32 v98, v169, v167, 12 bitop3:0x36
	v_lshl_add_u32 v98, v98, 4, v165
	ds_read_b128 v[98:101], v98 offset:55296
	v_mfma_f32_32x32x16_bf16 v[2:17], v[106:109], v[102:105], v[2:17]
	s_waitcnt lgkmcnt(0)
	v_mfma_f32_32x32x16_bf16 v[2:17], v[98:101], v[94:97], v[2:17]
	v_bitop3_b32 v94, v169, v167, 14 bitop3:0x36
	v_lshl_add_u32 v94, v94, 4, v165
	ds_read_b128 v[94:97], v94 offset:55296
	v_ashrrev_i32_e32 v167, 31, v166
	s_waitcnt lgkmcnt(0)
	v_mfma_f32_32x32x16_bf16 v[2:17], v[94:97], v[90:93], v[2:17]
	v_lshlrev_b64 v[90:91], 2, v[166:167]
	v_lshl_add_u64 v[92:93], s[10:11], 0, v[90:91]
	v_lshl_add_u64 v[90:91], s[40:41], 0, v[90:91]
	v_lshl_add_u64 v[92:93], v[92:93], 0, v[154:155]
	v_lshl_add_u64 v[94:95], v[90:91], 0, v[154:155]
	global_load_dwordx4 v[114:117], v[92:93], off
	global_load_dwordx4 v[118:121], v[94:95], off
	global_load_dwordx4 v[106:109], v[92:93], off offset:32
	global_load_dwordx4 v[110:113], v[94:95], off offset:32
	global_load_dwordx4 v[98:101], v[92:93], off offset:64
	global_load_dwordx4 v[102:105], v[94:95], off offset:64
	s_nop 0
	global_load_dwordx4 v[90:93], v[92:93], off offset:96
	s_nop 0
	global_load_dwordx4 v[94:97], v[94:95], off offset:96
	s_nop 0
	global_load_dword v186, v[132:133], off
	global_load_dword v187, v[132:133], off offset:128
	global_load_dword v188, v[132:133], off offset:256
	global_load_dword v189, v[132:133], off offset:384
	global_load_dword v190, v[130:131], off
	global_load_dword v191, v[130:131], off offset:128
	global_load_dword v192, v[130:131], off offset:256
	global_load_dword v193, v[130:131], off offset:384
	v_lshlrev_b64 v[176:177], 12, v[124:125]
	v_lshl_add_u64 v[176:177], s[60:61], 0, v[176:177]
	v_lshl_add_u64 v[176:177], v[176:177], 0, v[122:123]
	v_add_co_u32_e32 v178, vcc, 0x20000, v176
	s_nop 1
	v_addc_co_u32_e32 v179, vcc, 0, v177, vcc
	v_add_co_u32_e32 v182, vcc, 0x40000, v176
	s_nop 1
	v_addc_co_u32_e32 v183, vcc, 0, v177, vcc
	v_add_co_u32_e32 v184, vcc, 0x60000, v176
	s_nop 1
	v_addc_co_u32_e32 v185, vcc, 0, v177, vcc
	global_load_dwordx2 v[134:135], v[176:177], off offset:3072
	global_load_dwordx2 v[136:137], v[176:177], off offset:3088
	global_load_dwordx2 v[138:139], v[176:177], off offset:3104
	global_load_dwordx2 v[140:141], v[176:177], off offset:3120
	global_load_dwordx2 v[142:143], v[178:179], off offset:3072
	global_load_dwordx2 v[144:145], v[178:179], off offset:3088
	global_load_dwordx2 v[146:147], v[178:179], off offset:3104
	global_load_dwordx2 v[148:149], v[178:179], off offset:3120
	global_load_dwordx2 v[150:151], v[182:183], off offset:3072
	global_load_dwordx2 v[152:153], v[182:183], off offset:3088
	global_load_dwordx2 v[164:165], v[182:183], off offset:3104
	global_load_dwordx2 v[166:167], v[182:183], off offset:3120
	global_load_dwordx2 v[168:169], v[184:185], off offset:3072
	global_load_dwordx2 v[170:171], v[184:185], off offset:3088
	global_load_dwordx2 v[172:173], v[184:185], off offset:3104
	global_load_dwordx2 v[174:175], v[184:185], off offset:3120
	v_lshlrev_b64 v[176:177], 11, v[124:125]
	v_lshl_add_u64 v[176:177], s[62:63], 0, v[176:177]
	v_lshl_add_u64 v[176:177], v[176:177], 0, v[122:123]
	v_add_co_u32_e32 v178, vcc, 0x10000, v176
	s_nop 1
	v_addc_co_u32_e32 v179, vcc, 0, v177, vcc
	v_add_co_u32_e32 v182, vcc, 0x20000, v176
	s_nop 1
	v_addc_co_u32_e32 v183, vcc, 0, v177, vcc
	v_add_co_u32_e32 v184, vcc, 0x30000, v176
	s_nop 1
	v_addc_co_u32_e32 v185, vcc, 0, v177, vcc
	s_waitcnt vmcnt(0)
	v_mul_f32_e32 v194, v118, v186
	v_fmac_f32_e32 v194, v50, v114
	v_add_f32_e32 v50, v190, v194
	v_lshlrev_b32_e32 v195, 16, v134
	v_mul_f32_e32 v50, v50, v195
	v_mul_f32_e32 v194, v119, v186
	v_fmac_f32_e32 v194, v51, v115
	v_add_f32_e32 v51, v190, v194
	v_and_b32_e32 v195, 0xffff0000, v134
	v_mul_f32_e32 v51, v51, v195
	v_mul_f32_e32 v194, v120, v186
	v_fmac_f32_e32 v194, v52, v116
	v_add_f32_e32 v52, v190, v194
	v_lshlrev_b32_e32 v195, 16, v135
	v_mul_f32_e32 v52, v52, v195
	v_mul_f32_e32 v194, v121, v186
	v_fmac_f32_e32 v194, v53, v117
	v_add_f32_e32 v53, v190, v194
	v_and_b32_e32 v195, 0xffff0000, v135
	v_mul_f32_e32 v53, v53, v195
	v_cvt_pk_bf16_f32 v50, v50, v51
	v_cvt_pk_bf16_f32 v51, v52, v53
	global_store_dwordx2 v[176:177], v[50:51], off offset:1536
	v_mul_f32_e32 v194, v110, v186
	v_fmac_f32_e32 v194, v54, v106
	v_add_f32_e32 v54, v190, v194
	v_lshlrev_b32_e32 v195, 16, v136
	v_mul_f32_e32 v54, v54, v195
	v_mul_f32_e32 v194, v111, v186
	v_fmac_f32_e32 v194, v55, v107
	v_add_f32_e32 v55, v190, v194
	v_and_b32_e32 v195, 0xffff0000, v136
	v_mul_f32_e32 v55, v55, v195
	v_mul_f32_e32 v194, v112, v186
	v_fmac_f32_e32 v194, v56, v108
	v_add_f32_e32 v56, v190, v194
	v_lshlrev_b32_e32 v195, 16, v137
	v_mul_f32_e32 v56, v56, v195
	v_mul_f32_e32 v194, v113, v186
	v_fmac_f32_e32 v194, v57, v109
	v_add_f32_e32 v57, v190, v194
	v_and_b32_e32 v195, 0xffff0000, v137
	v_mul_f32_e32 v57, v57, v195
	v_cvt_pk_bf16_f32 v54, v54, v55
	v_cvt_pk_bf16_f32 v55, v56, v57
	global_store_dwordx2 v[176:177], v[54:55], off offset:1552
	v_mul_f32_e32 v194, v102, v186
	v_fmac_f32_e32 v194, v58, v98
	v_add_f32_e32 v58, v190, v194
	v_lshlrev_b32_e32 v195, 16, v138
	v_mul_f32_e32 v58, v58, v195
	v_mul_f32_e32 v194, v103, v186
	v_fmac_f32_e32 v194, v59, v99
	v_add_f32_e32 v59, v190, v194
	v_and_b32_e32 v195, 0xffff0000, v138
	v_mul_f32_e32 v59, v59, v195
	v_mul_f32_e32 v194, v104, v186
	v_fmac_f32_e32 v194, v60, v100
	v_add_f32_e32 v60, v190, v194
	v_lshlrev_b32_e32 v195, 16, v139
	v_mul_f32_e32 v60, v60, v195
	v_mul_f32_e32 v194, v105, v186
	v_fmac_f32_e32 v194, v61, v101
	v_add_f32_e32 v61, v190, v194
	v_and_b32_e32 v195, 0xffff0000, v139
	v_mul_f32_e32 v61, v61, v195
	v_cvt_pk_bf16_f32 v58, v58, v59
	v_cvt_pk_bf16_f32 v59, v60, v61
	global_store_dwordx2 v[176:177], v[58:59], off offset:1568
	v_mul_f32_e32 v194, v94, v186
	v_fmac_f32_e32 v194, v62, v90
	v_add_f32_e32 v62, v190, v194
	v_lshlrev_b32_e32 v195, 16, v140
	v_mul_f32_e32 v62, v62, v195
	v_mul_f32_e32 v194, v95, v186
	v_fmac_f32_e32 v194, v63, v91
	v_add_f32_e32 v63, v190, v194
	v_and_b32_e32 v195, 0xffff0000, v140
	v_mul_f32_e32 v63, v63, v195
	v_mul_f32_e32 v194, v96, v186
	v_fmac_f32_e32 v194, v64, v92
	v_add_f32_e32 v64, v190, v194
	v_lshlrev_b32_e32 v195, 16, v141
	v_mul_f32_e32 v64, v64, v195
	v_mul_f32_e32 v194, v97, v186
	v_fmac_f32_e32 v194, v65, v93
	v_add_f32_e32 v65, v190, v194
	v_and_b32_e32 v195, 0xffff0000, v141
	v_mul_f32_e32 v65, v65, v195
	v_cvt_pk_bf16_f32 v62, v62, v63
	v_cvt_pk_bf16_f32 v63, v64, v65
	global_store_dwordx2 v[176:177], v[62:63], off offset:1584
	v_mul_f32_e32 v194, v118, v187
	v_fmac_f32_e32 v194, v34, v114
	v_add_f32_e32 v34, v191, v194
	v_lshlrev_b32_e32 v195, 16, v142
	v_mul_f32_e32 v34, v34, v195
	v_mul_f32_e32 v194, v119, v187
	v_fmac_f32_e32 v194, v35, v115
	v_add_f32_e32 v35, v191, v194
	v_and_b32_e32 v195, 0xffff0000, v142
	v_mul_f32_e32 v35, v35, v195
	v_mul_f32_e32 v194, v120, v187
	v_fmac_f32_e32 v194, v36, v116
	v_add_f32_e32 v36, v191, v194
	v_lshlrev_b32_e32 v195, 16, v143
	v_mul_f32_e32 v36, v36, v195
	v_mul_f32_e32 v194, v121, v187
	v_fmac_f32_e32 v194, v37, v117
	v_add_f32_e32 v37, v191, v194
	v_and_b32_e32 v195, 0xffff0000, v143
	v_mul_f32_e32 v37, v37, v195
	v_cvt_pk_bf16_f32 v34, v34, v35
	v_cvt_pk_bf16_f32 v35, v36, v37
	global_store_dwordx2 v[178:179], v[34:35], off offset:1536
	v_mul_f32_e32 v194, v110, v187
	v_fmac_f32_e32 v194, v38, v106
	v_add_f32_e32 v38, v191, v194
	v_lshlrev_b32_e32 v195, 16, v144
	v_mul_f32_e32 v38, v38, v195
	v_mul_f32_e32 v194, v111, v187
	v_fmac_f32_e32 v194, v39, v107
	v_add_f32_e32 v39, v191, v194
	v_and_b32_e32 v195, 0xffff0000, v144
	v_mul_f32_e32 v39, v39, v195
	v_mul_f32_e32 v194, v112, v187
	v_fmac_f32_e32 v194, v40, v108
	v_add_f32_e32 v40, v191, v194
	v_lshlrev_b32_e32 v195, 16, v145
	v_mul_f32_e32 v40, v40, v195
	v_mul_f32_e32 v194, v113, v187
	v_fmac_f32_e32 v194, v41, v109
	v_add_f32_e32 v41, v191, v194
	v_and_b32_e32 v195, 0xffff0000, v145
	v_mul_f32_e32 v41, v41, v195
	v_cvt_pk_bf16_f32 v38, v38, v39
	v_cvt_pk_bf16_f32 v39, v40, v41
	global_store_dwordx2 v[178:179], v[38:39], off offset:1552
	v_mul_f32_e32 v194, v102, v187
	v_fmac_f32_e32 v194, v42, v98
	v_add_f32_e32 v42, v191, v194
	v_lshlrev_b32_e32 v195, 16, v146
	v_mul_f32_e32 v42, v42, v195
	v_mul_f32_e32 v194, v103, v187
	v_fmac_f32_e32 v194, v43, v99
	v_add_f32_e32 v43, v191, v194
	v_and_b32_e32 v195, 0xffff0000, v146
	v_mul_f32_e32 v43, v43, v195
	v_mul_f32_e32 v194, v104, v187
	v_fmac_f32_e32 v194, v44, v100
	v_add_f32_e32 v44, v191, v194
	v_lshlrev_b32_e32 v195, 16, v147
	v_mul_f32_e32 v44, v44, v195
	v_mul_f32_e32 v194, v105, v187
	v_fmac_f32_e32 v194, v45, v101
	v_add_f32_e32 v45, v191, v194
	v_and_b32_e32 v195, 0xffff0000, v147
	v_mul_f32_e32 v45, v45, v195
	v_cvt_pk_bf16_f32 v42, v42, v43
	v_cvt_pk_bf16_f32 v43, v44, v45
	global_store_dwordx2 v[178:179], v[42:43], off offset:1568
	v_mul_f32_e32 v194, v94, v187
	v_fmac_f32_e32 v194, v46, v90
	v_add_f32_e32 v46, v191, v194
	v_lshlrev_b32_e32 v195, 16, v148
	v_mul_f32_e32 v46, v46, v195
	v_mul_f32_e32 v194, v95, v187
	v_fmac_f32_e32 v194, v47, v91
	v_add_f32_e32 v47, v191, v194
	v_and_b32_e32 v195, 0xffff0000, v148
	v_mul_f32_e32 v47, v47, v195
	v_mul_f32_e32 v194, v96, v187
	v_fmac_f32_e32 v194, v48, v92
	v_add_f32_e32 v48, v191, v194
	v_lshlrev_b32_e32 v195, 16, v149
	v_mul_f32_e32 v48, v48, v195
	v_mul_f32_e32 v194, v97, v187
	v_fmac_f32_e32 v194, v49, v93
	v_add_f32_e32 v49, v191, v194
	v_and_b32_e32 v195, 0xffff0000, v149
	v_mul_f32_e32 v49, v49, v195
	v_cvt_pk_bf16_f32 v46, v46, v47
	v_cvt_pk_bf16_f32 v47, v48, v49
	global_store_dwordx2 v[178:179], v[46:47], off offset:1584
	v_mul_f32_e32 v194, v118, v188
	v_fmac_f32_e32 v194, v18, v114
	v_add_f32_e32 v18, v192, v194
	v_lshlrev_b32_e32 v195, 16, v150
	v_mul_f32_e32 v18, v18, v195
	v_mul_f32_e32 v194, v119, v188
	v_fmac_f32_e32 v194, v19, v115
	v_add_f32_e32 v19, v192, v194
	v_and_b32_e32 v195, 0xffff0000, v150
	v_mul_f32_e32 v19, v19, v195
	v_mul_f32_e32 v194, v120, v188
	v_fmac_f32_e32 v194, v20, v116
	v_add_f32_e32 v20, v192, v194
	v_lshlrev_b32_e32 v195, 16, v151
	v_mul_f32_e32 v20, v20, v195
	v_mul_f32_e32 v194, v121, v188
	v_fmac_f32_e32 v194, v21, v117
	v_add_f32_e32 v21, v192, v194
	v_and_b32_e32 v195, 0xffff0000, v151
	v_mul_f32_e32 v21, v21, v195
	v_cvt_pk_bf16_f32 v18, v18, v19
	v_cvt_pk_bf16_f32 v19, v20, v21
	global_store_dwordx2 v[182:183], v[18:19], off offset:1536
	v_mul_f32_e32 v194, v110, v188
	v_fmac_f32_e32 v194, v22, v106
	v_add_f32_e32 v22, v192, v194
	v_lshlrev_b32_e32 v195, 16, v152
	v_mul_f32_e32 v22, v22, v195
	v_mul_f32_e32 v194, v111, v188
	v_fmac_f32_e32 v194, v23, v107
	v_add_f32_e32 v23, v192, v194
	v_and_b32_e32 v195, 0xffff0000, v152
	v_mul_f32_e32 v23, v23, v195
	v_mul_f32_e32 v194, v112, v188
	v_fmac_f32_e32 v194, v24, v108
	v_add_f32_e32 v24, v192, v194
	v_lshlrev_b32_e32 v195, 16, v153
	v_mul_f32_e32 v24, v24, v195
	v_mul_f32_e32 v194, v113, v188
	v_fmac_f32_e32 v194, v25, v109
	v_add_f32_e32 v25, v192, v194
	v_and_b32_e32 v195, 0xffff0000, v153
	v_mul_f32_e32 v25, v25, v195
	v_cvt_pk_bf16_f32 v22, v22, v23
	v_cvt_pk_bf16_f32 v23, v24, v25
	global_store_dwordx2 v[182:183], v[22:23], off offset:1552
	v_mul_f32_e32 v194, v102, v188
	v_fmac_f32_e32 v194, v26, v98
	v_add_f32_e32 v26, v192, v194
	v_lshlrev_b32_e32 v195, 16, v164
	v_mul_f32_e32 v26, v26, v195
	v_mul_f32_e32 v194, v103, v188
	v_fmac_f32_e32 v194, v27, v99
	v_add_f32_e32 v27, v192, v194
	v_and_b32_e32 v195, 0xffff0000, v164
	v_mul_f32_e32 v27, v27, v195
	v_mul_f32_e32 v194, v104, v188
	v_fmac_f32_e32 v194, v28, v100
	v_add_f32_e32 v28, v192, v194
	v_lshlrev_b32_e32 v195, 16, v165
	v_mul_f32_e32 v28, v28, v195
	v_mul_f32_e32 v194, v105, v188
	v_fmac_f32_e32 v194, v29, v101
	v_add_f32_e32 v29, v192, v194
	v_and_b32_e32 v195, 0xffff0000, v165
	v_mul_f32_e32 v29, v29, v195
	v_cvt_pk_bf16_f32 v26, v26, v27
	v_cvt_pk_bf16_f32 v27, v28, v29
	global_store_dwordx2 v[182:183], v[26:27], off offset:1568
	v_mul_f32_e32 v194, v94, v188
	v_fmac_f32_e32 v194, v30, v90
	v_add_f32_e32 v30, v192, v194
	v_lshlrev_b32_e32 v195, 16, v166
	v_mul_f32_e32 v30, v30, v195
	v_mul_f32_e32 v194, v95, v188
	v_fmac_f32_e32 v194, v31, v91
	v_add_f32_e32 v31, v192, v194
	v_and_b32_e32 v195, 0xffff0000, v166
	v_mul_f32_e32 v31, v31, v195
	v_mul_f32_e32 v194, v96, v188
	v_fmac_f32_e32 v194, v32, v92
	v_add_f32_e32 v32, v192, v194
	v_lshlrev_b32_e32 v195, 16, v167
	v_mul_f32_e32 v32, v32, v195
	v_mul_f32_e32 v194, v97, v188
	v_fmac_f32_e32 v194, v33, v93
	v_add_f32_e32 v33, v192, v194
	v_and_b32_e32 v195, 0xffff0000, v167
	v_mul_f32_e32 v33, v33, v195
	v_cvt_pk_bf16_f32 v30, v30, v31
	v_cvt_pk_bf16_f32 v31, v32, v33
	global_store_dwordx2 v[182:183], v[30:31], off offset:1584
	v_mul_f32_e32 v194, v118, v189
	v_fmac_f32_e32 v194, v2, v114
	v_add_f32_e32 v2, v193, v194
	v_lshlrev_b32_e32 v195, 16, v168
	v_mul_f32_e32 v2, v2, v195
	v_mul_f32_e32 v194, v119, v189
	v_fmac_f32_e32 v194, v3, v115
	v_add_f32_e32 v3, v193, v194
	v_and_b32_e32 v195, 0xffff0000, v168
	v_mul_f32_e32 v3, v3, v195
	v_mul_f32_e32 v194, v120, v189
	v_fmac_f32_e32 v194, v4, v116
	v_add_f32_e32 v4, v193, v194
	v_lshlrev_b32_e32 v195, 16, v169
	v_mul_f32_e32 v4, v4, v195
	v_mul_f32_e32 v194, v121, v189
	v_fmac_f32_e32 v194, v5, v117
	v_add_f32_e32 v5, v193, v194
	v_and_b32_e32 v195, 0xffff0000, v169
	v_mul_f32_e32 v5, v5, v195
	v_cvt_pk_bf16_f32 v2, v2, v3
	v_cvt_pk_bf16_f32 v3, v4, v5
	global_store_dwordx2 v[184:185], v[2:3], off offset:1536
	v_mul_f32_e32 v194, v110, v189
	v_fmac_f32_e32 v194, v6, v106
	v_add_f32_e32 v6, v193, v194
	v_lshlrev_b32_e32 v195, 16, v170
	v_mul_f32_e32 v6, v6, v195
	v_mul_f32_e32 v194, v111, v189
	v_fmac_f32_e32 v194, v7, v107
	v_add_f32_e32 v7, v193, v194
	v_and_b32_e32 v195, 0xffff0000, v170
	v_mul_f32_e32 v7, v7, v195
	v_mul_f32_e32 v194, v112, v189
	v_fmac_f32_e32 v194, v8, v108
	v_add_f32_e32 v8, v193, v194
	v_lshlrev_b32_e32 v195, 16, v171
	v_mul_f32_e32 v8, v8, v195
	v_mul_f32_e32 v194, v113, v189
	v_fmac_f32_e32 v194, v9, v109
	v_add_f32_e32 v9, v193, v194
	v_and_b32_e32 v195, 0xffff0000, v171
	v_mul_f32_e32 v9, v9, v195
	v_cvt_pk_bf16_f32 v6, v6, v7
	v_cvt_pk_bf16_f32 v7, v8, v9
	global_store_dwordx2 v[184:185], v[6:7], off offset:1552
	v_mul_f32_e32 v194, v102, v189
	v_fmac_f32_e32 v194, v10, v98
	v_add_f32_e32 v10, v193, v194
	v_lshlrev_b32_e32 v195, 16, v172
	v_mul_f32_e32 v10, v10, v195
	v_mul_f32_e32 v194, v103, v189
	v_fmac_f32_e32 v194, v11, v99
	v_add_f32_e32 v11, v193, v194
	v_and_b32_e32 v195, 0xffff0000, v172
	v_mul_f32_e32 v11, v11, v195
	v_mul_f32_e32 v194, v104, v189
	v_fmac_f32_e32 v194, v12, v100
	v_add_f32_e32 v12, v193, v194
	v_lshlrev_b32_e32 v195, 16, v173
	v_mul_f32_e32 v12, v12, v195
	v_mul_f32_e32 v194, v105, v189
	v_fmac_f32_e32 v194, v13, v101
	v_add_f32_e32 v13, v193, v194
	v_and_b32_e32 v195, 0xffff0000, v173
	v_mul_f32_e32 v13, v13, v195
	v_cvt_pk_bf16_f32 v10, v10, v11
	v_cvt_pk_bf16_f32 v11, v12, v13
	global_store_dwordx2 v[184:185], v[10:11], off offset:1568
	v_mul_f32_e32 v194, v94, v189
	v_fmac_f32_e32 v194, v14, v90
	v_add_f32_e32 v14, v193, v194
	v_lshlrev_b32_e32 v195, 16, v174
	v_mul_f32_e32 v14, v14, v195
	v_mul_f32_e32 v194, v95, v189
	v_fmac_f32_e32 v194, v15, v91
	v_add_f32_e32 v15, v193, v194
	v_and_b32_e32 v195, 0xffff0000, v174
	v_mul_f32_e32 v15, v15, v195
	v_mul_f32_e32 v194, v96, v189
	v_fmac_f32_e32 v194, v16, v92
	v_add_f32_e32 v16, v193, v194
	v_lshlrev_b32_e32 v195, 16, v175
	v_mul_f32_e32 v16, v16, v195
	v_mul_f32_e32 v194, v97, v189
	v_fmac_f32_e32 v194, v17, v93
	v_add_f32_e32 v17, v193, v194
	v_and_b32_e32 v195, 0xffff0000, v175
	v_mul_f32_e32 v17, v17, v195
	v_cvt_pk_bf16_f32 v14, v14, v15
	v_cvt_pk_bf16_f32 v15, v16, v17
	global_store_dwordx2 v[184:185], v[14:15], off offset:1584
	s_barrier
	s_cbranch_scc0 .LBB0_779

.LBB0_787:
	s_or_b64 exec, exec, s[2:3]
	s_mov_b32 s98, 0xffffd000
	s_mov_b32 s99, -1
	v_lshl_add_u64 v[200:201], v[164:165], 1, s[30:31]
	v_lshl_add_u64 v[202:203], v[200:201], 0, s[98:99]
	s_mov_b32 s98, 0xfffff000
	v_lshl_add_u64 v[200:201], v[200:201], 0, s[98:99]
	global_load_ushort v192, v[202:203], off offset:-2816
	global_load_ushort v193, v[202:203], off offset:-1280
	global_load_ushort v194, v[202:203], off offset:1280
	global_load_ushort v195, v[202:203], off offset:2816
	global_load_ushort v196, v[200:201], off offset:-2816
	global_load_ushort v197, v[200:201], off offset:-1280
	global_load_ushort v198, v[200:201], off offset:1280
	global_load_ushort v199, v[200:201], off offset:2816
	s_mov_b64 s[100:101], exec
	s_mov_b64 exec, s[40:41]
	s_cbranch_execz .Ls_hoist_skip_c1
	global_load_ushort v220, v[202:203], off offset:-512
	global_load_ushort v221, v[202:203], off offset:3584
	global_load_ushort v222, v[200:201], off offset:-512
	global_load_ushort v223, v[200:201], off offset:3584
	v_add_u32_e32 v232, s5, v164
	v_ashrrev_i32_e32 v233, 31, v232
	v_lshlrev_b64 v[232:233], 2, v[232:233]
	v_lshl_add_u64 v[234:235], s[86:87], 0, v[232:233]
	v_lshl_add_u64 v[232:233], s[88:89], 0, v[232:233]
	global_load_dword v204, v[234:235], off
	global_load_dword v205, v[232:233], off
	v_ashrrev_i32_e32 v232, 6, v164
	v_add_u32_e32 v232, s6, v232
	v_lshlrev_b32_e32 v234, 7, v232
	v_ashrrev_i32_e32 v233, 31, v232
	v_ashrrev_i32_e32 v235, 31, v234
	v_lshlrev_b64 v[232:233], 16, v[232:233]
	v_lshl_add_u64 v[234:235], v[234:235], 2, s[92:93]
	v_lshl_add_u64 v[232:233], s[90:91], 0, v[232:233]
	global_load_dwordx4 v[206:209], v[234:235], off
	global_load_dword v210, v[232:233], off
	global_load_dwordx2 v[212:213], v[232:233], off offset:512
	global_load_dwordx3 v[224:226], v[232:233], off offset:1024
	global_load_dwordx4 v[228:231], v[232:233], off offset:1536
.Ls_hoist_skip_c1:
	s_mov_b64 exec, s[100:101]
	v_and_b32_e32 v10, 64, v181
	v_add_u32_e32 v16, 64, v10
	v_xor_b32_e32 v10, 32, v181
	v_cmp_lt_i32_e32 vcc, v10, v16
	v_xor_b32_e32 v11, 16, v181
	v_xor_b32_e32 v12, 8, v181
	v_cndmask_b32_e32 v10, v181, v10, vcc
	v_cmp_lt_i32_e32 vcc, v11, v16
	v_lshlrev_b32_e32 v34, 2, v10
	ds_bpermute_b32 v10, v34, v174
	v_cndmask_b32_e32 v11, v181, v11, vcc
	v_lshlrev_b32_e32 v35, 2, v11
	ds_bpermute_b32 v11, v34, v175
	v_cmp_lt_i32_e32 vcc, v12, v16
	v_xor_b32_e32 v14, 4, v181
	v_xor_b32_e32 v17, 1, v181
	v_cndmask_b32_e32 v12, v181, v12, vcc
	s_waitcnt lgkmcnt(0)
	v_pk_add_f32 v[10:11], v[174:175], v[10:11]
	v_lshlrev_b32_e32 v36, 2, v12
	ds_bpermute_b32 v12, v35, v10
	ds_bpermute_b32 v13, v35, v11
	v_cmp_lt_i32_e32 vcc, v14, v16
	ds_bpermute_b32 v18, v34, v8
	ds_bpermute_b32 v19, v34, v9
	v_cndmask_b32_e32 v14, v181, v14, vcc
	s_waitcnt lgkmcnt(2)
	v_pk_add_f32 v[10:11], v[10:11], v[12:13]
	ds_bpermute_b32 v12, v36, v10
	ds_bpermute_b32 v13, v36, v11
	v_lshlrev_b32_e32 v37, 2, v14
	v_xor_b32_e32 v14, 2, v181
	v_cmp_lt_i32_e32 vcc, v14, v16
	ds_bpermute_b32 v20, v34, v6
	s_waitcnt lgkmcnt(1)
	v_pk_add_f32 v[10:11], v[10:11], v[12:13]
	ds_bpermute_b32 v12, v37, v10
	ds_bpermute_b32 v13, v37, v11
	v_cndmask_b32_e32 v14, v181, v14, vcc
	v_cmp_lt_i32_e32 vcc, v17, v16
	v_lshlrev_b32_e32 v38, 2, v14
	ds_bpermute_b32 v21, v34, v7
	v_cndmask_b32_e32 v16, v181, v17, vcc
	s_waitcnt lgkmcnt(1)
	v_pk_add_f32 v[10:11], v[10:11], v[12:13]
	v_lshlrev_b32_e32 v39, 2, v16
	ds_bpermute_b32 v16, v38, v10
	ds_bpermute_b32 v17, v38, v11
	s_waitcnt lgkmcnt(2)
	v_pk_add_f32 v[20:21], v[6:7], v[20:21]
	ds_bpermute_b32 v22, v35, v20
	ds_bpermute_b32 v23, v35, v21
	ds_bpermute_b32 v14, v34, v170
	s_waitcnt lgkmcnt(3)
	v_pk_add_f32 v[10:11], v[10:11], v[16:17]
	v_pk_add_f32 v[16:17], v[8:9], v[18:19]
	ds_bpermute_b32 v18, v35, v16
	ds_bpermute_b32 v19, v35, v17
	s_waitcnt lgkmcnt(3)
	v_pk_add_f32 v[20:21], v[20:21], v[22:23]
	ds_bpermute_b32 v22, v36, v20
	ds_bpermute_b32 v23, v36, v21
	ds_bpermute_b32 v15, v34, v171
	s_waitcnt lgkmcnt(3)
	v_pk_add_f32 v[16:17], v[16:17], v[18:19]
	ds_bpermute_b32 v18, v36, v16
	ds_bpermute_b32 v19, v36, v17
	s_waitcnt lgkmcnt(3)
	v_pk_add_f32 v[20:21], v[20:21], v[22:23]
	ds_bpermute_b32 v22, v37, v20
	ds_bpermute_b32 v23, v37, v21
	s_waitcnt lgkmcnt(4)
	v_pk_add_f32 v[12:13], v[170:171], v[14:15]
	s_waitcnt lgkmcnt(2)
	v_pk_add_f32 v[16:17], v[16:17], v[18:19]
	ds_bpermute_b32 v18, v37, v16
	ds_bpermute_b32 v19, v37, v17
	s_waitcnt lgkmcnt(2)
	v_pk_add_f32 v[20:21], v[20:21], v[22:23]
	ds_bpermute_b32 v22, v34, v168
	ds_bpermute_b32 v23, v34, v169
	ds_bpermute_b32 v26, v38, v20
	s_waitcnt lgkmcnt(3)
	v_pk_add_f32 v[16:17], v[16:17], v[18:19]
	ds_bpermute_b32 v18, v38, v16
	ds_bpermute_b32 v19, v38, v17
	s_waitcnt lgkmcnt(3)
	v_pk_add_f32 v[22:23], v[168:169], v[22:23]
	ds_bpermute_b32 v28, v35, v22
	ds_bpermute_b32 v29, v35, v23
	ds_bpermute_b32 v27, v38, v21
	s_waitcnt lgkmcnt(3)
	v_pk_add_f32 v[6:7], v[16:17], v[18:19]
	ds_bpermute_b32 v18, v34, v166
	ds_bpermute_b32 v19, v34, v167
	s_waitcnt lgkmcnt(3)
	v_pk_add_f32 v[28:29], v[22:23], v[28:29]
	ds_bpermute_b32 v32, v36, v28
	ds_bpermute_b32 v33, v36, v29
	ds_bpermute_b32 v14, v35, v12
	s_waitcnt lgkmcnt(3)
	v_pk_add_f32 v[18:19], v[166:167], v[18:19]
	ds_bpermute_b32 v24, v35, v18
	ds_bpermute_b32 v25, v35, v19
	ds_bpermute_b32 v15, v35, v13
	ds_bpermute_b32 v8, v39, v10
	ds_bpermute_b32 v9, v39, v11
	ds_bpermute_b32 v16, v39, v6
	s_waitcnt lgkmcnt(4)
	v_pk_add_f32 v[18:19], v[18:19], v[24:25]
	ds_bpermute_b32 v24, v36, v18
	ds_bpermute_b32 v25, v36, v19
	s_waitcnt lgkmcnt(5)
	v_pk_add_f32 v[12:13], v[12:13], v[14:15]
	ds_bpermute_b32 v14, v36, v12
	ds_bpermute_b32 v15, v36, v13
	ds_bpermute_b32 v17, v39, v7
	s_waitcnt lgkmcnt(3)
	v_pk_add_f32 v[18:19], v[18:19], v[24:25]
	ds_bpermute_b32 v24, v37, v18
	ds_bpermute_b32 v25, v37, v19
	s_waitcnt lgkmcnt(3)
	v_pk_add_f32 v[12:13], v[12:13], v[14:15]
	ds_bpermute_b32 v14, v37, v12
	ds_bpermute_b32 v15, v37, v13
	s_waitcnt lgkmcnt(2)
	v_pk_add_f32 v[24:25], v[18:19], v[24:25]
	v_pk_add_f32 v[18:19], v[20:21], v[26:27]
	v_pk_add_f32 v[26:27], v[28:29], v[32:33]
	ds_bpermute_b32 v30, v38, v24
	ds_bpermute_b32 v31, v38, v25
	ds_bpermute_b32 v28, v37, v26
	ds_bpermute_b32 v29, v37, v27
	s_waitcnt lgkmcnt(4)
	v_pk_add_f32 v[12:13], v[12:13], v[14:15]
	ds_bpermute_b32 v14, v38, v12
	s_waitcnt lgkmcnt(3)
	v_pk_add_f32 v[20:21], v[24:25], v[30:31]
	ds_bpermute_b32 v30, v34, v2
	ds_bpermute_b32 v31, v34, v3
	s_waitcnt lgkmcnt(3)
	v_pk_add_f32 v[26:27], v[26:27], v[28:29]
	ds_bpermute_b32 v28, v34, v4
	ds_bpermute_b32 v29, v34, v5
	ds_bpermute_b32 v32, v38, v26
	s_waitcnt lgkmcnt(3)
	v_pk_add_f32 v[2:3], v[2:3], v[30:31]
	ds_bpermute_b32 v30, v35, v2
	ds_bpermute_b32 v31, v35, v3
	s_waitcnt lgkmcnt(3)
	v_pk_add_f32 v[4:5], v[4:5], v[28:29]
	ds_bpermute_b32 v28, v35, v4
	ds_bpermute_b32 v29, v35, v5
	ds_bpermute_b32 v33, v38, v27
	s_waitcnt lgkmcnt(3)
	v_pk_add_f32 v[30:31], v[2:3], v[30:31]
	ds_bpermute_b32 v34, v36, v30
	ds_bpermute_b32 v35, v36, v31
	s_waitcnt lgkmcnt(3)
	v_pk_add_f32 v[4:5], v[4:5], v[28:29]
	ds_bpermute_b32 v28, v36, v4
	ds_bpermute_b32 v29, v36, v5
	s_waitcnt lgkmcnt(4)
	v_pk_add_f32 v[2:3], v[26:27], v[32:33]
	s_waitcnt lgkmcnt(2)
	v_pk_add_f32 v[26:27], v[30:31], v[34:35]
	ds_bpermute_b32 v30, v37, v26
	ds_bpermute_b32 v31, v37, v27
	s_waitcnt lgkmcnt(2)
	v_pk_add_f32 v[28:29], v[4:5], v[28:29]
	ds_bpermute_b32 v32, v37, v28
	ds_bpermute_b32 v33, v37, v29
	ds_bpermute_b32 v15, v38, v13
	s_waitcnt lgkmcnt(3)
	v_pk_add_f32 v[26:27], v[26:27], v[30:31]
	ds_bpermute_b32 v30, v38, v26
	ds_bpermute_b32 v31, v38, v27
	s_waitcnt lgkmcnt(3)
	v_pk_add_f32 v[32:33], v[28:29], v[32:33]
	ds_bpermute_b32 v34, v38, v32
	ds_bpermute_b32 v35, v38, v33
	s_waitcnt lgkmcnt(4)
	v_pk_add_f32 v[12:13], v[12:13], v[14:15]
	s_waitcnt lgkmcnt(2)
	v_pk_add_f32 v[26:27], v[26:27], v[30:31]
	ds_bpermute_b32 v14, v39, v12
	ds_bpermute_b32 v15, v39, v13
	s_waitcnt lgkmcnt(2)
	v_pk_add_f32 v[30:31], v[32:33], v[34:35]
	ds_bpermute_b32 v22, v39, v18
	ds_bpermute_b32 v23, v39, v19
	ds_bpermute_b32 v24, v39, v20
	ds_bpermute_b32 v25, v39, v21
	ds_bpermute_b32 v4, v39, v2
	ds_bpermute_b32 v5, v39, v3
	ds_bpermute_b32 v28, v39, v26
	ds_bpermute_b32 v29, v39, v27
	ds_bpermute_b32 v32, v39, v30
	ds_bpermute_b32 v33, v39, v31
	v_and_b32_e32 v34, 63, v164
	v_cmp_eq_u32_e32 vcc, 0, v34
	s_and_saveexec_b64 s[2:3], vcc
	s_cbranch_execz .LBB0_789
	v_add_u32_e32 v34, 32, v164
	v_add_u32_e32 v34, 0x16000, v34
	v_pk_add_f32 v[6:7], v[6:7], v[16:17]
	s_waitcnt lgkmcnt(4)
	v_pk_add_f32 v[2:3], v[2:3], v[4:5]
	v_pk_add_f32 v[8:9], v[10:11], v[8:9]
	ds_write2_b32 v34, v6, v7 offset0:4 offset1:5
	v_pk_add_f32 v[6:7], v[18:19], v[22:23]
	ds_write2_b32 v34, v2, v3 offset0:10 offset1:11
	s_waitcnt lgkmcnt(4)
	v_pk_add_f32 v[2:3], v[26:27], v[28:29]
	ds_write2_b32 v34, v8, v9 offset1:1
	v_pk_add_f32 v[8:9], v[12:13], v[14:15]
	ds_write2_b32 v34, v6, v7 offset0:6 offset1:7
	v_pk_add_f32 v[6:7], v[20:21], v[24:25]
	ds_write2_b32 v34, v2, v3 offset0:12 offset1:13
	s_waitcnt lgkmcnt(5)
	v_pk_add_f32 v[2:3], v[30:31], v[32:33]
	ds_write2_b32 v34, v8, v9 offset0:2 offset1:3
	ds_write2_b32 v34, v6, v7 offset0:8 offset1:9
	ds_write2_b32 v34, v2, v3 offset0:14 offset1:15
.LBB0_789:
	s_or_b64 exec, exec, s[2:3]
	v_readlane_b32 s2, v242, 9
	s_waitcnt lgkmcnt(0)
	s_barrier
	v_mov_b32_e32 v2, s2
	v_readlane_b32 s2, v242, 10
	s_nop 1
	v_mov_b32_e32 v3, s2
	v_readlane_b32 s2, v242, 11
	ds_read_b128 v[6:9], v2
	ds_read_b128 v[2:5], v3
	v_mov_b32_e32 v10, s2
	v_readlane_b32 s2, v242, 12
	s_nop 1
	v_mov_b32_e32 v11, s2
	v_readlane_b32 s2, v242, 13
	ds_read_b128 v[14:17], v10
	ds_read_b128 v[10:13], v11
	v_mov_b32_e32 v18, s2
	v_readlane_b32 s2, v242, 14
	s_nop 1
	v_mov_b32_e32 v19, s2
	v_readlane_b32 s2, v242, 15
	ds_read_b128 v[22:25], v18
	ds_read_b128 v[18:21], v19
	v_mov_b32_e32 v26, s2
	v_readlane_b32 s2, v242, 16
	s_nop 1
	v_mov_b32_e32 v27, s2
	v_readlane_b32 s2, v242, 17
	ds_read_b128 v[30:33], v26
	ds_read_b128 v[26:29], v27
	v_mov_b32_e32 v34, s2
	v_readlane_b32 s2, v242, 18
	s_nop 1
	v_mov_b32_e32 v35, s2
	v_readlane_b32 s2, v242, 19
	ds_read_b128 v[38:41], v34
	ds_read_b128 v[34:37], v35
	v_mov_b32_e32 v42, s2
	v_readlane_b32 s2, v242, 20
	s_nop 1
	v_mov_b32_e32 v43, s2
	v_readlane_b32 s2, v242, 21
	ds_read_b128 v[46:49], v42
	ds_read_b128 v[42:45], v43
	v_mov_b32_e32 v50, s2
	v_readlane_b32 s2, v242, 22
	s_nop 1
	v_mov_b32_e32 v51, s2
	v_readlane_b32 s2, v242, 23
	ds_read_b128 v[54:57], v50
	ds_read_b128 v[50:53], v51
	v_mov_b32_e32 v58, s2
	v_readlane_b32 s2, v242, 24
	s_nop 1
	v_mov_b32_e32 v59, s2
	ds_read_b128 v[62:65], v58
	ds_read_b128 v[58:61], v59
	s_and_saveexec_b64 s[34:35], s[42:43]
	s_cbranch_execz .LBB0_791
	v_lshlrev_b64 v[176:177], 2, v[172:173]
	v_lshl_add_u64 v[178:179], s[80:81], 0, v[176:177]
	v_lshl_add_u64 v[176:177], s[82:83], 0, v[176:177]
	global_load_dword v190, v[178:179], off
	global_load_dword v189, v[176:177], off
	v_readlane_b32 s2, v242, 25
	s_mov_b32 s12, 0x3b2aaaab
	s_nop 0
	v_mov_b32_e32 v90, s2
	v_readlane_b32 s2, v242, 26
	ds_read_b128 v[90:93], v90
	s_nop 0
	v_mov_b32_e32 v94, s2
	v_readlane_b32 s2, v242, 27
	ds_read_b128 v[94:97], v94
	s_waitcnt lgkmcnt(0)
	v_mov_b32_e32 v176, v94
	v_mov_b32_e32 v98, s2
	v_readlane_b32 s2, v242, 28
	ds_read_b128 v[98:101], v98
	s_nop 0
	v_mov_b32_e32 v102, s2
	v_readlane_b32 s2, v242, 29
	ds_read_b128 v[102:105], v102
	s_nop 0
	v_mov_b32_e32 v106, s2
	v_readlane_b32 s2, v242, 30
	ds_read_b128 v[106:109], v106
	s_nop 0
	v_mov_b32_e32 v110, s2
	v_readlane_b32 s2, v242, 31
	ds_read_b128 v[110:113], v110
	s_nop 0
	v_mov_b32_e32 v114, s2
	v_readlane_b32 s2, v242, 32
	ds_read_b128 v[114:117], v114
	s_nop 0
	v_mov_b32_e32 v118, s2
	s_add_i32 s2, 32, 0x16000
	v_mov_b32_e32 v122, s2
	v_readlane_b32 s2, v242, 33
	ds_read_b128 v[122:125], v122
	ds_read_b128 v[118:121], v118
	v_mov_b32_e32 v126, s2
	v_readlane_b32 s2, v242, 34
	ds_read_b128 v[126:129], v126
	s_waitcnt lgkmcnt(0)
	v_mov_b32_e32 v177, v126
	v_mov_b32_e32 v130, s2
	v_readlane_b32 s2, v242, 35
	ds_read_b128 v[130:133], v130
	v_mov_b32_e32 v126, v95
	v_mov_b32_e32 v134, s2
	v_readlane_b32 s2, v242, 36
	ds_read_b128 v[134:137], v134
	s_nop 0
	v_mov_b32_e32 v138, s2
	v_readlane_b32 s2, v242, 37
	ds_read_b128 v[138:141], v138
	s_nop 0
	v_mov_b32_e32 v142, s2
	v_readlane_b32 s2, v242, 38
	ds_read_b128 v[142:145], v142
	s_nop 0
	v_mov_b32_e32 v146, s2
	v_readlane_b32 s2, v242, 39
	ds_read_b128 v[146:149], v146
	s_nop 0
	v_mov_b32_e32 v150, s2
	v_readlane_b32 s2, v242, 40
	s_mulk_i32 s2, 0x300
	ds_read_b128 v[150:153], v150
	v_add_u32_e32 v172, s2, v172
	v_ashrrev_i32_e32 v173, 31, v172
	v_lshl_add_u64 v[172:173], v[172:173], 2, s[84:85]
	global_load_dword v186, v[172:173], off
	global_load_dword v188, v[172:173], off offset:1536
	global_load_dword v187, v[172:173], off offset:3072
	v_mov_b32_e32 v172, v90
	v_mov_b32_e32 v173, v122
	v_pk_add_f32 v[172:173], v[172:173], 0 op_sel_hi:[1,0]
	s_movk_i32 s2, 0xd000
	v_pk_add_f32 v[172:173], v[172:173], v[176:177]
	v_mov_b32_e32 v176, v98
	s_waitcnt lgkmcnt(5)
	v_mov_b32_e32 v177, v130
	v_pk_add_f32 v[172:173], v[172:173], v[176:177]
	v_mov_b32_e32 v176, v102
	s_waitcnt lgkmcnt(4)
	v_mov_b32_e32 v177, v134
	v_pk_add_f32 v[172:173], v[172:173], v[176:177]
	v_mov_b32_e32 v176, v106
	s_waitcnt lgkmcnt(3)
	v_mov_b32_e32 v177, v138
	v_pk_add_f32 v[172:173], v[172:173], v[176:177]
	v_mov_b32_e32 v176, v110
	s_waitcnt lgkmcnt(2)
	v_mov_b32_e32 v177, v142
	v_pk_add_f32 v[172:173], v[172:173], v[176:177]
	v_mov_b32_e32 v176, v114
	s_waitcnt lgkmcnt(1)
	v_mov_b32_e32 v177, v146
	v_pk_add_f32 v[172:173], v[172:173], v[176:177]
	v_mov_b32_e32 v176, v118
	s_waitcnt lgkmcnt(0)
	v_mov_b32_e32 v177, v150
	v_pk_add_f32 v[172:173], v[172:173], v[176:177]
	v_lshlrev_b64 v[176:177], 1, v[164:165]
	v_pk_mul_f32 v[172:173], v[172:173], s[12:13] op_sel_hi:[1,0]
	v_mov_b32_e32 v122, v91
	v_fma_f32 v90, -v173, v173, v172
	v_max_f32_e32 v90, 0, v90
	v_add_f32_e32 v90, 0x358637bd, v90
	v_cmp_gt_f32_e32 vcc, s33, v90
	v_mul_f32_e32 v94, 0x4b800000, v90
	v_mov_b32_e32 v130, v99
	v_cndmask_b32_e32 v90, v90, v94, vcc
	v_rsq_f32_e32 v90, v90
	v_mov_b32_e32 v134, v103
	v_mov_b32_e32 v138, v107
	v_mov_b32_e32 v142, v111
	v_mul_f32_e32 v94, 0x45800000, v90
	v_cndmask_b32_e32 v90, v90, v94, vcc
	v_sub_f32_e32 v94, v174, v173
	v_mul_f32_e32 v90, v94, v90
	s_waitcnt vmcnt(3)
	v_fma_f32 v90, v190, v90, v189
	v_mul_f32_e32 v94, 0xbfb8aa3b, v90
	v_exp_f32_e32 v94, v94
	v_lshl_add_u64 v[172:173], s[30:31], 0, v[176:177]
	v_add_co_u32_e32 v178, vcc, s2, v172
	v_add_f32_e32 v94, 1.0, v94
	v_rcp_f32_e32 v94, v94
	v_addc_co_u32_e32 v179, vcc, -1, v173, vcc
	v_lshl_add_u64 v[176:177], s[10:11], 0, v[176:177]
	v_mul_f32_e32 v90, v90, v94
	v_mov_b32_e32 v146, v115
	v_mov_b32_e32 v150, v119
	s_movk_i32 s2, 0xe000
	s_waitcnt vmcnt(0)
	v_lshlrev_b32_e32 v94, 16, v192
	v_mul_f32_e32 v90, v90, v94
	v_bfe_u32 v94, v90, 16, 1
	v_add3_u32 v90, v90, v94, s15
	global_store_short_d16_hi v[176:177], v90, off
	v_mul_f32_e32 v90, v185, v188
	v_fmac_f32_e32 v90, v191, v186
	v_fmac_f32_e32 v90, v184, v187
	v_lshlrev_b32_e32 v94, 16, v193
	v_mul_f32_e32 v90, v90, v94
	v_bfe_u32 v94, v90, 16, 1
	v_add3_u32 v90, v90, v94, s15
	global_store_short_d16_hi v[176:177], v90, off offset:768
	v_pk_add_f32 v[90:91], v[122:123], 0 op_sel_hi:[1,0]
	s_nop 0
	v_pk_add_f32 v[90:91], v[90:91], v[126:127]
	s_nop 0
	v_pk_add_f32 v[90:91], v[90:91], v[130:131]
	s_nop 0
	v_pk_add_f32 v[90:91], v[90:91], v[134:135]
	s_nop 0
	v_pk_add_f32 v[90:91], v[90:91], v[138:139]
	s_nop 0
	v_pk_add_f32 v[90:91], v[90:91], v[142:143]
	s_nop 0
	v_pk_add_f32 v[90:91], v[90:91], v[146:147]
	s_nop 0
	v_pk_add_f32 v[90:91], v[90:91], v[150:151]
	s_nop 0
	v_pk_mul_f32 v[90:91], v[90:91], s[12:13] op_sel_hi:[1,0]
	s_nop 0
	v_fma_f32 v90, -v91, v91, v90
	v_max_f32_e32 v90, 0, v90
	v_add_f32_e32 v90, 0x358637bd, v90
	v_cmp_gt_f32_e32 vcc, s33, v90
	v_mul_f32_e32 v94, 0x4b800000, v90
	v_sub_f32_e32 v91, v175, v91
	v_cndmask_b32_e32 v90, v90, v94, vcc
	v_rsq_f32_e32 v90, v90
	s_nop 0
	v_mul_f32_e32 v94, 0x45800000, v90
	v_cndmask_b32_e32 v90, v90, v94, vcc
	v_mul_f32_e32 v90, v91, v90
	v_fma_f32 v90, v190, v90, v189
	v_mul_f32_e32 v91, 0xbfb8aa3b, v90
	v_exp_f32_e32 v91, v91
	s_nop 0
	v_add_f32_e32 v91, 1.0, v91
	v_rcp_f32_e32 v91, v91
	s_nop 0
	v_mul_f32_e32 v94, v90, v91
	v_add_co_u32_e32 v90, vcc, s2, v172
	s_movk_i32 s2, 0xf000
	s_nop 0
	v_addc_co_u32_e32 v91, vcc, -1, v173, vcc
	v_lshlrev_b32_e32 v95, 16, v194
	v_mul_f32_e32 v94, v94, v95
	v_bfe_u32 v95, v94, 16, 1
	v_add3_u32 v94, v94, v95, s15
	global_store_short_d16_hi v[176:177], v94, off offset:2048
	v_mul_f32_e32 v94, v184, v188
	v_fmac_f32_e32 v94, v185, v186
	v_fmac_f32_e32 v94, v183, v187
	v_mov_b32_e32 v95, v128
	v_mov_b32_e32 v128, v97
	v_lshlrev_b32_e32 v90, 16, v195
	v_mul_f32_e32 v90, v94, v90
	v_bfe_u32 v91, v90, 16, 1
	v_add3_u32 v90, v90, v91, s15
	global_store_short_d16_hi v[176:177], v90, off offset:2816
	v_mov_b32_e32 v90, v92
	v_mov_b32_e32 v91, v124
	v_pk_add_f32 v[90:91], v[90:91], 0 op_sel_hi:[1,0]
	v_mov_b32_e32 v94, v96
	v_pk_add_f32 v[90:91], v[90:91], v[94:95]
	v_mov_b32_e32 v94, v100
	v_mov_b32_e32 v95, v132
	v_pk_add_f32 v[90:91], v[90:91], v[94:95]
	v_mov_b32_e32 v94, v104
	v_mov_b32_e32 v95, v136
	v_pk_add_f32 v[90:91], v[90:91], v[94:95]
	v_mov_b32_e32 v94, v108
	v_mov_b32_e32 v95, v140
	v_pk_add_f32 v[90:91], v[90:91], v[94:95]
	v_mov_b32_e32 v94, v112
	v_mov_b32_e32 v95, v144
	v_pk_add_f32 v[90:91], v[90:91], v[94:95]
	v_mov_b32_e32 v94, v116
	v_mov_b32_e32 v95, v148
	v_pk_add_f32 v[90:91], v[90:91], v[94:95]
	v_mov_b32_e32 v94, v120
	v_mov_b32_e32 v95, v152
	v_pk_add_f32 v[90:91], v[90:91], v[94:95]
	v_mov_b32_e32 v124, v93
	v_pk_mul_f32 v[90:91], v[90:91], s[12:13] op_sel_hi:[1,0]
	v_mov_b32_e32 v132, v101
	v_fma_f32 v90, -v91, v91, v90
	v_max_f32_e32 v90, 0, v90
	v_add_f32_e32 v90, 0x358637bd, v90
	v_cmp_gt_f32_e32 vcc, s33, v90
	v_mul_f32_e32 v92, 0x4b800000, v90
	v_sub_f32_e32 v91, v170, v91
	v_cndmask_b32_e32 v90, v90, v92, vcc
	v_rsq_f32_e32 v90, v90
	v_mov_b32_e32 v136, v105
	v_mov_b32_e32 v140, v109
	v_mov_b32_e32 v144, v113
	v_mul_f32_e32 v92, 0x45800000, v90
	v_cndmask_b32_e32 v90, v90, v92, vcc
	v_mul_f32_e32 v90, v91, v90
	v_fma_f32 v90, v90, v190, v189
	v_mul_f32_e32 v91, 0xbfb8aa3b, v90
	v_exp_f32_e32 v91, v91
	v_add_co_u32_e32 v94, vcc, s2, v172
	s_movk_i32 s2, 0x1000
	v_add_f32_e32 v91, 1.0, v91
	v_rcp_f32_e32 v91, v91
	v_addc_co_u32_e32 v95, vcc, -1, v173, vcc
	v_mov_b32_e32 v148, v117
	v_mul_f32_e32 v90, v90, v91
	v_mov_b32_e32 v152, v121
	v_lshlrev_b32_e32 v91, 16, v196
	v_mul_f32_e32 v90, v90, v91
	v_bfe_u32 v91, v90, 16, 1
	v_add3_u32 v92, v90, v91, s15
	v_add_co_u32_e32 v90, vcc, s2, v176
	s_add_i32 s2, s4, s7
	s_nop 0
	v_addc_co_u32_e32 v91, vcc, 0, v177, vcc
	global_store_short_d16_hi v[90:91], v92, off
	v_mul_f32_e32 v92, v183, v188
	v_fmac_f32_e32 v92, v184, v186
	v_fmac_f32_e32 v92, v182, v187
	s_mul_hi_i32 s3, s2, 0xc00
	s_mulk_i32 s2, 0xc00
	s_add_u32 s2, s50, s2
	s_addc_u32 s3, s51, s3
	v_lshlrev_b32_e32 v94, 16, v197
	v_mul_f32_e32 v92, v92, v94
	v_bfe_u32 v94, v92, 16, 1
	v_add3_u32 v92, v92, v94, s15
	global_store_short_d16_hi v[90:91], v92, off offset:768
	v_pk_add_f32 v[92:93], v[124:125], 0 op_sel_hi:[1,0]
	s_nop 0
	v_pk_add_f32 v[92:93], v[92:93], v[128:129]
	s_nop 0
	v_pk_add_f32 v[92:93], v[92:93], v[132:133]
	s_nop 0
	v_pk_add_f32 v[92:93], v[92:93], v[136:137]
	s_nop 0
	v_pk_add_f32 v[92:93], v[92:93], v[140:141]
	s_nop 0
	v_pk_add_f32 v[92:93], v[92:93], v[144:145]
	s_nop 0
	v_pk_add_f32 v[92:93], v[92:93], v[148:149]
	s_nop 0
	v_pk_add_f32 v[92:93], v[92:93], v[152:153]
	s_nop 0
	v_pk_mul_f32 v[92:93], v[92:93], s[12:13] op_sel_hi:[1,0]
	s_nop 0
	v_fma_f32 v92, -v93, v93, v92
	v_max_f32_e32 v92, 0, v92
	v_add_f32_e32 v92, 0x358637bd, v92
	v_cmp_gt_f32_e32 vcc, s33, v92
	v_mul_f32_e32 v94, 0x4b800000, v92
	v_sub_f32_e32 v93, v171, v93
	v_cndmask_b32_e32 v92, v92, v94, vcc
	v_rsq_f32_e32 v92, v92
	s_nop 0
	v_mul_f32_e32 v94, 0x45800000, v92
	v_cndmask_b32_e32 v92, v92, v94, vcc
	v_mul_f32_e32 v92, v93, v92
	v_fmac_f32_e32 v189, v92, v190
	v_mul_f32_e32 v92, 0xbfb8aa3b, v189
	v_exp_f32_e32 v92, v92
	v_lshlrev_b32_e32 v93, 16, v198
	v_add_f32_e32 v92, 1.0, v92
	v_rcp_f32_e32 v92, v92
	s_nop 0
	v_mul_f32_e32 v92, v189, v92
	v_mul_f32_e32 v92, v92, v93
	v_bfe_u32 v93, v92, 16, 1
	v_add3_u32 v92, v92, v93, s15
	global_store_short_d16_hi v[90:91], v92, off offset:2048
	v_mul_f32_e32 v92, v182, v188
	v_fmac_f32_e32 v92, v183, v186
	v_fmac_f32_e32 v92, v154, v187
	v_lshlrev_b32_e32 v93, 16, v199
	v_mul_f32_e32 v92, v92, v93
	v_bfe_u32 v93, v92, 16, 1
	v_add3_u32 v92, v92, v93, s15
	global_store_short_d16_hi v[90:91], v92, off offset:2816
	v_lshl_add_u64 v[90:91], v[164:165], 2, s[2:3]
	v_add_co_u32_e32 v90, vcc, 0x4e00000, v90
	s_nop 1
	v_addc_co_u32_e32 v91, vcc, 0, v91, vcc
	global_store_dword v[90:91], v182, off
	global_store_dword v[90:91], v154, off offset:1536
.LBB0_791:
	s_or_b64 exec, exec, s[34:35]
	s_and_saveexec_b64 s[12:13], s[40:41]
	s_cbranch_execz .LBB0_782
	s_waitcnt lgkmcnt(7)
	v_mov_b32_e32 v90, v38
	v_mov_b32_e32 v91, v6
	v_mov_b32_e32 v6, v39
	v_pk_add_f32 v[90:91], v[90:91], 0 op_sel_hi:[1,0]
	s_waitcnt lgkmcnt(6)
	v_mov_b32_e32 v92, v34
	v_mov_b32_e32 v93, v2
	v_pk_add_f32 v[6:7], v[6:7], 0 op_sel_hi:[1,0]
	v_mov_b32_e32 v2, v35
	v_pk_add_f32 v[90:91], v[90:91], v[92:93]
	s_waitcnt lgkmcnt(5)
	v_mov_b32_e32 v92, v46
	v_mov_b32_e32 v93, v14
	v_pk_add_f32 v[2:3], v[6:7], v[2:3]
	v_mov_b32_e32 v14, v47
	v_pk_add_f32 v[90:91], v[90:91], v[92:93]
	s_waitcnt lgkmcnt(4)
	v_mov_b32_e32 v92, v42
	v_mov_b32_e32 v93, v10
	v_pk_add_f32 v[2:3], v[2:3], v[14:15]
	v_mov_b32_e32 v10, v43
	v_pk_add_f32 v[90:91], v[90:91], v[92:93]
	s_waitcnt lgkmcnt(3)
	v_mov_b32_e32 v92, v54
	v_mov_b32_e32 v93, v22
	v_pk_add_f32 v[2:3], v[2:3], v[10:11]
	v_mov_b32_e32 v22, v55
	v_pk_add_f32 v[90:91], v[90:91], v[92:93]
	s_waitcnt lgkmcnt(2)
	v_mov_b32_e32 v92, v50
	v_mov_b32_e32 v93, v18
	v_pk_add_f32 v[2:3], v[2:3], v[22:23]
	v_mov_b32_e32 v18, v51
	v_pk_add_f32 v[90:91], v[90:91], v[92:93]
	s_waitcnt lgkmcnt(1)
	v_mov_b32_e32 v92, v62
	v_mov_b32_e32 v93, v30
	v_pk_add_f32 v[2:3], v[2:3], v[18:19]
	v_mov_b32_e32 v30, v63
	v_pk_add_f32 v[90:91], v[90:91], v[92:93]
	v_mov_b32_e32 v93, v26
	v_pk_add_f32 v[2:3], v[2:3], v[30:31]
	s_waitcnt lgkmcnt(0)
	v_mov_b32_e32 v26, v59
	v_pk_add_f32 v[10:11], v[2:3], v[26:27]
	v_mov_b32_e32 v2, v40
	v_mov_b32_e32 v3, v8
	v_pk_add_f32 v[2:3], v[2:3], 0 op_sel_hi:[1,0]
	v_mov_b32_e32 v6, v36
	v_mov_b32_e32 v7, v4
	v_pk_add_f32 v[2:3], v[2:3], v[6:7]
	v_mov_b32_e32 v6, v48
	v_mov_b32_e32 v7, v16
	v_pk_add_f32 v[2:3], v[2:3], v[6:7]
	v_mov_b32_e32 v6, v44
	v_mov_b32_e32 v7, v12
	v_pk_add_f32 v[2:3], v[2:3], v[6:7]
	v_mov_b32_e32 v6, v56
	v_mov_b32_e32 v7, v24
	v_pk_add_f32 v[2:3], v[2:3], v[6:7]
	v_mov_b32_e32 v6, v52
	v_mov_b32_e32 v7, v20
	v_pk_add_f32 v[2:3], v[2:3], v[6:7]
	v_mov_b32_e32 v6, v64
	v_mov_b32_e32 v7, v32
	v_pk_add_f32 v[2:3], v[2:3], v[6:7]
	v_mov_b32_e32 v6, v60
	v_mov_b32_e32 v7, v28
	v_mov_b32_e32 v8, v41
	v_pk_add_f32 v[6:7], v[2:3], v[6:7]
	v_pk_add_f32 v[2:3], v[8:9], 0 op_sel_hi:[1,0]
	v_mov_b32_e32 v4, v37
	v_add_u32_e32 v8, s5, v164
	v_pk_add_f32 v[2:3], v[2:3], v[4:5]
	v_mov_b32_e32 v16, v49
	v_ashrrev_i32_e32 v9, 31, v8
	v_pk_add_f32 v[2:3], v[2:3], v[16:17]
	v_mov_b32_e32 v12, v45
	v_lshlrev_b64 v[8:9], 2, v[8:9]
	v_pk_add_f32 v[2:3], v[2:3], v[12:13]
	v_lshl_add_u64 v[12:13], s[86:87], 0, v[8:9]
	v_lshl_add_u64 v[8:9], s[88:89], 0, v[8:9]
	s_waitcnt vmcnt(10)
	v_mov_b32_e32 v5, v204
	v_mov_b32_e32 v92, v58
	v_mov_b32_e32 v8, v205
	v_pk_add_f32 v[90:91], v[90:91], v[92:93]
	s_mov_b32 s14, 0x3b800000
	v_pk_mul_f32 v[12:13], v[90:91], s[14:15] op_sel_hi:[1,0]
	s_add_i32 s2, s4, s7
	v_fma_f32 v9, -v13, v13, v12
	v_max_f32_e32 v9, 0, v9
	v_add_f32_e32 v9, 0x358637bd, v9
	v_cmp_gt_f32_e32 vcc, s33, v9
	v_mul_f32_e32 v12, 0x4b800000, v9
	s_ashr_i32 s3, s2, 31
	v_cndmask_b32_e32 v9, v9, v12, vcc
	v_rsq_f32_e32 v9, v9
	s_lshl_b64 s[2:3], s[2:3], 12
	s_add_u32 s2, s50, s2
	s_addc_u32 s3, s51, s3
	v_mul_f32_e32 v12, 0x45800000, v9
	v_cndmask_b32_e32 v9, v9, v12, vcc
	v_sub_f32_e32 v12, v166, v13
	v_pk_mul_f32 v[10:11], v[10:11], s[14:15] op_sel_hi:[1,0]
	v_mul_f32_e32 v9, v12, v9
	v_lshl_add_u64 v[12:13], v[164:165], 2, s[2:3]
	s_mov_b32 s2, 0x4ec0000
	v_fma_f32 v10, -v11, v11, v10
	v_add_co_u32_e32 v12, vcc, s2, v12
	v_max_f32_e32 v10, 0, v10
	s_nop 0
	v_addc_co_u32_e32 v13, vcc, 0, v13, vcc
	v_add_f32_e32 v10, 0x358637bd, v10
	v_cmp_gt_f32_e32 vcc, s33, v10
	v_mul_f32_e32 v14, 0x4b800000, v10
	v_pk_mul_f32 v[6:7], v[6:7], s[14:15] op_sel_hi:[1,0]
	v_cndmask_b32_e32 v10, v10, v14, vcc
	v_rsq_f32_e32 v10, v10
	v_fma_f32 v6, -v7, v7, v6
	v_sub_f32_e32 v11, v167, v11
	v_max_f32_e32 v6, 0, v6
	v_mul_f32_e32 v14, 0x45800000, v10
	v_cndmask_b32_e32 v10, v10, v14, vcc
	v_mul_f32_e32 v10, v11, v10
	v_add_f32_e32 v6, 0x358637bd, v6
	v_mov_b32_e32 v24, v57
	v_cmp_gt_f32_e32 vcc, s33, v6
	v_pk_add_f32 v[2:3], v[2:3], v[24:25]
	v_mov_b32_e32 v20, v53
	v_pk_add_f32 v[2:3], v[2:3], v[20:21]
	v_mov_b32_e32 v32, v65
	v_pk_add_f32 v[2:3], v[2:3], v[32:33]
	v_mov_b32_e32 v28, v61
	v_pk_add_f32 v[2:3], v[2:3], v[28:29]
	v_sub_f32_e32 v7, v168, v7
	v_pk_mul_f32 v[2:3], v[2:3], s[14:15] op_sel_hi:[1,0]
	v_ashrrev_i32_e32 v4, 6, v164
	v_fma_f32 v2, -v3, v3, v2
	v_max_f32_e32 v2, 0, v2
	v_add_f32_e32 v2, 0x358637bd, v2
	v_sub_f32_e32 v3, v169, v3
	s_movk_i32 s2, 0xd000
	v_fma_f32 v18, v10, v5, v8
	v_mul_f32_e32 v10, 0x4b800000, v6
	v_cndmask_b32_e32 v6, v6, v10, vcc
	v_rsq_f32_e32 v6, v6
	v_fma_f32 v9, v9, v5, v8
	global_store_dword v[12:13], v9, off
	global_store_dword v[12:13], v18, off offset:1024
	v_mul_f32_e32 v10, 0x45800000, v6
	v_cndmask_b32_e32 v6, v6, v10, vcc
	v_mul_f32_e32 v6, v7, v6
	v_fma_f32 v19, v6, v5, v8
	v_cmp_gt_f32_e32 vcc, s33, v2
	v_mul_f32_e32 v6, 0x4b800000, v2
	global_store_dword v[12:13], v19, off offset:2048
	v_cndmask_b32_e32 v2, v2, v6, vcc
	v_rsq_f32_e32 v2, v2
	v_lshlrev_b64 v[10:11], 1, v[164:165]
	v_lshl_add_u64 v[16:17], s[10:11], 0, v[10:11]
	v_mul_f32_e32 v6, 0x45800000, v2
	v_cndmask_b32_e32 v2, v2, v6, vcc
	v_mul_f32_e32 v2, v3, v2
	v_fmac_f32_e32 v8, v2, v5
	v_add_u32_e32 v2, s6, v4
	v_lshlrev_b32_e32 v4, 7, v2
	v_ashrrev_i32_e32 v3, 31, v2
	v_lshlrev_b64 v[2:3], 16, v[2:3]
	v_ashrrev_i32_e32 v5, 31, v4
	global_store_dword v[12:13], v8, off offset:3072
	v_lshl_add_u64 v[14:15], s[90:91], 0, v[2:3]
	v_lshl_add_u64 v[2:3], v[4:5], 2, s[92:93]
	v_mov_b32_e32 v2, v206
	v_mov_b32_e32 v3, v207
	v_mov_b32_e32 v4, v208
	v_mov_b32_e32 v5, v209
	s_nop 0
	v_mov_b32_e32 v6, v210
	v_fma_f32 v2, v9, v6, v2
	v_lshl_add_u64 v[6:7], s[30:31], 0, v[10:11]
	v_add_co_u32_e32 v12, vcc, s2, v6
	v_mov_b32_e32 v10, v212
	v_mov_b32_e32 v11, v213
	s_nop 0
	v_addc_co_u32_e32 v13, vcc, -1, v7, vcc
	v_mov_b32_e32 v12, v220
	s_movk_i32 s2, 0xe000
	v_fma_f32 v10, v9, v10, v3
	v_fmac_f32_e32 v10, v18, v11
	v_lshlrev_b32_e32 v12, 16, v12
	v_mul_f32_e32 v2, v2, v12
	v_bfe_u32 v12, v2, 16, 1
	v_add3_u32 v2, v2, v12, s15
	global_store_short_d16_hi v[16:17], v2, off offset:1536
	v_add_co_u32_e32 v2, vcc, s2, v6
	s_movk_i32 s2, 0xf000
	s_nop 0
	v_addc_co_u32_e32 v3, vcc, -1, v7, vcc
	v_mov_b32_e32 v2, v221
	v_lshlrev_b32_e32 v2, 16, v2
	v_mul_f32_e32 v2, v10, v2
	v_bfe_u32 v3, v2, 16, 1
	v_add3_u32 v2, v2, v3, s15
	global_store_short_d16_hi v[16:17], v2, off offset:3584
	v_mov_b32_e32 v10, v224
	v_mov_b32_e32 v11, v225
	v_mov_b32_e32 v12, v226
	v_add_co_u32_e32 v2, vcc, s2, v6
	s_movk_i32 s2, 0x1000
	s_nop 0
	v_addc_co_u32_e32 v3, vcc, -1, v7, vcc
	v_mov_b32_e32 v2, v222
	v_fma_f32 v4, v9, v10, v4
	v_fmac_f32_e32 v4, v18, v11
	v_fmac_f32_e32 v4, v19, v12
	v_mov_b32_e32 v10, v228
	v_mov_b32_e32 v11, v229
	v_mov_b32_e32 v12, v230
	v_mov_b32_e32 v13, v231
	v_lshlrev_b32_e32 v2, 16, v2
	v_mul_f32_e32 v2, v4, v2
	v_bfe_u32 v3, v2, 16, 1
	v_add3_u32 v4, v2, v3, s15
	v_add_co_u32_e32 v2, vcc, s2, v16
	v_fmac_f32_e32 v5, v9, v10
	v_addc_co_u32_e32 v3, vcc, 0, v17, vcc
	global_store_short_d16_hi v[2:3], v4, off offset:1536
	v_mov_b32_e32 v4, v223
	v_fmac_f32_e32 v5, v18, v11
	v_fmac_f32_e32 v5, v19, v12
	v_fmac_f32_e32 v5, v8, v13
	v_lshlrev_b32_e32 v4, 16, v4
	v_mul_f32_e32 v4, v5, v4
	v_bfe_u32 v5, v4, 16, 1
	v_add3_u32 v4, v4, v5, s15
	global_store_short_d16_hi v[2:3], v4, off offset:3584
	s_branch .LBB0_782

.LBB0_794:
	s_and_b64 vcc, exec, s[38:39]
	s_cbranch_vccnz .LBB0_846
	v_readlane_b32 s6, v242, 0
	v_readlane_b32 s5, v242, 40
	v_readlane_b32 s7, v242, 1
	s_mul_i32 s2, s5, 0x180
	s_mov_b32 s3, s7
	s_lshl_b32 s4, s5, 3
	s_lshl_b64 s[2:3], s[2:3], 2
	s_add_u32 s30, s78, s2
	s_addc_u32 s31, s79, s3
	s_add_u32 s40, s82, s2
	s_addc_u32 s41, s83, s3
	s_mul_i32 s6, s5, 0x480
	s_add_u32 s42, s80, s2
	s_addc_u32 s43, s81, s3
	s_lshl_b64 s[2:3], s[6:7], 2
	s_add_u32 s94, s84, s2
	s_addc_u32 s95, s85, s3
	s_mov_b32 s6, s24
	v_and_b32_e32 v240, 63, v0
	v_min_u32_e32 v240, 47, v240
	v_lshlrev_b32_e32 v240, 5, v240
	global_load_dwordx4 v[186:189], v240, s[30:31]
	global_load_dwordx4 v[190:193], v240, s[30:31] offset:16
	global_load_dwordx4 v[194:197], v240, s[40:41]
	global_load_dwordx4 v[198:201], v240, s[40:41] offset:16
	global_load_dwordx4 v[202:205], v240, s[42:43]
	global_load_dwordx4 v[206:209], v240, s[42:43] offset:16
	global_load_dwordx4 v[210:213], v240, s[94:95] offset:3072
	global_load_dwordx4 v[214:217], v240, s[94:95] offset:3088
	global_load_dwordx4 v[218:221], v240, s[94:95] offset:1536
	global_load_dwordx4 v[222:225], v240, s[94:95] offset:1552
	global_load_dwordx4 v[226:229], v240, s[94:95]
	global_load_dwordx4 v[230:233], v240, s[94:95] offset:16
	s_branch .LBB0_797

.LBB0_797:
	s_add_i32 s5, s6, s46
	v_mov_b32_e32 v26, v0
	s_cmpk_gt_i32 s5, 0x1ff
	s_cselect_b64 s[34:35], -1, 0
	s_cmpk_lt_i32 s5, 0x200
	v_lshl_add_u32 v26, v26, 4, 32
	s_cselect_b32 s2, s5, s6
	v_add_u32_e32 v27, 0xd800, v26
	s_waitcnt vmcnt(8)
	ds_write_b128 v26, v[2:5] offset:55296
	ds_write_b128 v26, v[6:9] offset:63488
	ds_write_b128 v27, v[10:13] offset:16384
	ds_write_b128 v27, v[14:17] offset:24576
	ds_write_b128 v27, v[18:21] offset:32768
	ds_write_b128 v27, v[22:25] offset:40960
	v_mov_b32_e32 v26, v0
	s_lshl_b32 s7, s2, 5
	s_movk_i32 s2, 0xba0
	s_waitcnt lgkmcnt(0)
	s_barrier
	s_and_b32 s12, s7, 0x7e0
	v_cmp_gt_i32_e32 vcc, s2, v26
	v_mov_b32_e32 v6, 0
	v_mov_b32_e32 v2, 0
	v_mov_b32_e32 v3, 0
	v_mov_b32_e32 v4, 0
	v_mov_b32_e32 v5, 0
	s_and_saveexec_b64 s[2:3], vcc
	s_cbranch_execz .LBB0_801
	s_mov_b32 s10, 0x2aaaaaab
	v_mul_hi_i32 v2, v26, s10
	v_lshrrev_b32_e32 v3, 31, v2
	v_ashrrev_i32_e32 v2, 3, v2
	v_add_u32_e32 v7, v2, v3
	v_subrev_u32_e32 v8, 30, v7
	v_add_u32_e32 v2, s12, v8
	v_cmp_lt_i32_e32 vcc, -1, v2
	v_mov_b32_e32 v5, 0
	v_mov_b32_e32 v4, 0
	v_mov_b32_e32 v3, 0
	v_mov_b32_e32 v2, 0
	s_and_saveexec_b64 s[10:11], vcc
	s_cbranch_execz .LBB0_800
	v_add_u32_e32 v2, s7, v8
	s_movk_i32 s13, 0xffd0
	v_ashrrev_i32_e32 v3, 31, v2
	v_mul_lo_u32 v4, v7, s13
	v_lshlrev_b64 v[2:3], 12, v[2:3]
	v_add_lshl_u32 v4, v4, v26, 3
	v_lshl_add_u64 v[2:3], s[60:61], 0, v[2:3]
	v_ashrrev_i32_e32 v5, 31, v4
	v_lshl_add_u64 v[2:3], v[4:5], 1, v[2:3]
	global_load_dwordx4 v[2:5], v[2:3], off

.LBB0_829:
	s_or_b64 exec, exec, s[2:3]
	v_cmp_lt_i32_e32 vcc, -3, v63
	v_mov_b32_e32 v62, 0
	v_mov_b32_e32 v66, 0
	v_mov_b32_e32 v149, 0
	v_mov_b32_e32 v67, 0
	v_mov_b32_e32 v153, 0
	v_mov_b32_e32 v68, 0
	v_mov_b32_e32 v164, 0
	v_mov_b32_e32 v69, 0
	v_mov_b32_e32 v165, 0
	s_and_saveexec_b64 s[2:3], vcc
	s_cbranch_execz .LBB0_831
	v_mov_b32_e32 v85, v155
	v_lshl_add_u64 v[64:65], v[82:83], 0, v[84:85]
	v_add_co_u32_e32 v64, vcc, 0x2000, v64
	s_nop 1
	v_addc_co_u32_e32 v65, vcc, 0, v65, vcc
	global_load_dwordx4 v[66:69], v[64:65], off offset:1536
.LBB0_831:
	s_or_b64 exec, exec, s[2:3]
	v_cmp_lt_i32_e32 vcc, -4, v63
	v_mov_b32_e32 v166, 0
	v_mov_b32_e32 v63, 0
	v_mov_b32_e32 v167, 0
	v_mov_b32_e32 v64, 0
	v_mov_b32_e32 v168, 0
	v_mov_b32_e32 v65, 0
	v_mov_b32_e32 v169, 0
	s_and_saveexec_b64 s[2:3], vcc
	s_cbranch_execz .LBB0_833
	v_mov_b32_e32 v85, v155
	v_lshl_add_u64 v[62:63], v[82:83], 0, v[84:85]
	v_add_co_u32_e32 v62, vcc, 0x3000, v62
	s_nop 1
	v_addc_co_u32_e32 v63, vcc, 0, v63, vcc
	global_load_dwordx4 v[62:65], v[62:63], off offset:1536
.LBB0_833:
	s_or_b64 exec, exec, s[2:3]
	v_lshlrev_b32_e32 v122, 2, v86
	v_mov_b64_e32 v[86:87], v[190:191]
	v_mov_b64_e32 v[88:89], v[192:193]
	v_mov_b64_e32 v[82:83], v[186:187]
	v_mov_b64_e32 v[84:85], v[188:189]
	s_movk_i32 s2, 0xc00
	v_mul_lo_u32 v123, v152, s2
	v_or_b32_e32 v90, v123, v154
	s_add_i32 s2, 32, 0xd800
	v_add_u32_e32 v170, s2, v90
	v_mov_b32_e32 v90, 0
	v_add_u32_e32 v151, 32, v154
	s_mov_b32 s2, -4
	v_mov_b32_e32 v91, v90
	v_mov_b32_e32 v92, v90
	v_mov_b32_e32 v93, v90
	v_mov_b32_e32 v94, v90
	v_mov_b32_e32 v95, v90
	v_mov_b32_e32 v96, v90
	v_mov_b32_e32 v97, v90
	v_mov_b32_e32 v98, v90
	v_mov_b32_e32 v99, v90
	v_mov_b32_e32 v100, v90
	v_mov_b32_e32 v101, v90
	v_mov_b32_e32 v102, v90
	v_mov_b32_e32 v103, v90
	v_mov_b32_e32 v104, v90
	v_mov_b32_e32 v105, v90
	v_mov_b32_e32 v106, v90
	v_mov_b32_e32 v107, v90
	v_mov_b32_e32 v108, v90
	v_mov_b32_e32 v109, v90
	v_mov_b32_e32 v110, v90
	v_mov_b32_e32 v111, v90
	v_mov_b32_e32 v112, v90
	v_mov_b32_e32 v113, v90
	v_mov_b64_e32 v[144:145], v[86:87]
	v_mov_b64_e32 v[140:141], v[82:83]
	v_mov_b64_e32 v[142:143], v[84:85]
	v_mov_b64_e32 v[146:147], v[88:89]
	v_mov_b64_e32 v[132:133], v[82:83]
	v_mov_b64_e32 v[134:135], v[84:85]
	v_mov_b64_e32 v[136:137], v[86:87]
	v_mov_b64_e32 v[138:139], v[88:89]
	v_mov_b64_e32 v[124:125], v[82:83]
	v_mov_b64_e32 v[126:127], v[84:85]
	v_mov_b64_e32 v[128:129], v[86:87]
	v_mov_b64_e32 v[130:131], v[88:89]
.LBB0_834:
	ds_read_b128 v[114:117], v170
	s_add_i32 s2, s2, 4
	s_cmp_gt_u32 s2, 31
	s_waitcnt lgkmcnt(0)
	v_lshlrev_b32_e32 v172, 16, v114
	v_and_b32_e32 v173, 0xffff0000, v114
	v_lshlrev_b32_e32 v174, 16, v115
	v_and_b32_e32 v175, 0xffff0000, v115
	v_lshlrev_b32_e32 v176, 16, v116
	v_and_b32_e32 v177, 0xffff0000, v116
	v_lshlrev_b32_e32 v178, 16, v117
	v_and_b32_e32 v179, 0xffff0000, v117
	ds_read_b128 v[114:117], v151
	ds_read_b128 v[118:121], v151 offset:768
	v_pk_fma_f32 v[124:125], v[90:91], v[172:173], v[124:125]
	v_pk_fma_f32 v[126:127], v[92:93], v[174:175], v[126:127]
	v_pk_fma_f32 v[128:129], v[94:95], v[176:177], v[128:129]
	s_waitcnt lgkmcnt(1)
	v_pk_fma_f32 v[182:183], v[114:115], v[172:173], v[82:83]
	v_pk_fma_f32 v[184:185], v[116:117], v[174:175], v[84:85]
	ds_read_b128 v[82:85], v170 offset:768
	v_pk_fma_f32 v[130:131], v[96:97], v[178:179], v[130:131]
	ds_read_b128 v[90:93], v151 offset:1536
	ds_read_b128 v[94:97], v151 offset:2304
	s_waitcnt lgkmcnt(3)
	v_pk_fma_f32 v[88:89], v[120:121], v[178:179], v[88:89]
	v_pk_fma_f32 v[140:141], v[106:107], v[172:173], v[140:141]
	v_pk_fma_f32 v[142:143], v[108:109], v[174:175], v[142:143]
	v_pk_fma_f32 v[146:147], v[112:113], v[178:179], v[146:147]
	v_pk_fma_f32 v[132:133], v[98:99], v[172:173], v[132:133]
	v_pk_fma_f32 v[134:135], v[100:101], v[174:175], v[134:135]
	v_pk_fma_f32 v[138:139], v[104:105], v[178:179], v[138:139]
	s_waitcnt lgkmcnt(2)
	v_lshlrev_b32_e32 v172, 16, v82
	v_and_b32_e32 v173, 0xffff0000, v82
	v_lshlrev_b32_e32 v82, 16, v83
	v_and_b32_e32 v83, 0xffff0000, v83
	v_lshlrev_b32_e32 v174, 16, v84
	v_and_b32_e32 v175, 0xffff0000, v84
	v_lshlrev_b32_e32 v84, 16, v85
	v_and_b32_e32 v85, 0xffff0000, v85
	s_waitcnt lgkmcnt(1)
	v_pk_fma_f32 v[178:179], v[92:93], v[82:83], v[184:185]
	s_waitcnt lgkmcnt(0)
	v_pk_fma_f32 v[88:89], v[96:97], v[84:85], v[88:89]
	v_pk_fma_f32 v[142:143], v[116:117], v[82:83], v[142:143]
	v_pk_fma_f32 v[146:147], v[120:121], v[84:85], v[146:147]
	v_pk_fma_f32 v[134:135], v[108:109], v[82:83], v[134:135]
	v_pk_fma_f32 v[138:139], v[112:113], v[84:85], v[138:139]
	v_pk_fma_f32 v[126:127], v[100:101], v[82:83], v[126:127]
	v_pk_fma_f32 v[130:131], v[104:105], v[84:85], v[130:131]
	ds_read_b128 v[82:85], v170 offset:1536
	v_pk_fma_f32 v[136:137], v[102:103], v[176:177], v[136:137]
	v_pk_fma_f32 v[124:125], v[98:99], v[172:173], v[124:125]
	v_pk_fma_f32 v[128:129], v[102:103], v[174:175], v[128:129]
	ds_read_b128 v[98:101], v151 offset:3072
	ds_read_b128 v[102:105], v151 offset:3840
	v_pk_fma_f32 v[86:87], v[118:119], v[176:177], v[86:87]
	v_pk_fma_f32 v[144:145], v[110:111], v[176:177], v[144:145]
	v_pk_fma_f32 v[176:177], v[90:91], v[172:173], v[182:183]
	v_pk_fma_f32 v[86:87], v[94:95], v[174:175], v[86:87]
	v_pk_fma_f32 v[140:141], v[114:115], v[172:173], v[140:141]
	v_pk_fma_f32 v[144:145], v[118:119], v[174:175], v[144:145]
	v_pk_fma_f32 v[132:133], v[106:107], v[172:173], v[132:133]
	v_pk_fma_f32 v[136:137], v[110:111], v[174:175], v[136:137]
	s_waitcnt lgkmcnt(2)
	v_lshlrev_b32_e32 v172, 16, v82
	v_and_b32_e32 v173, 0xffff0000, v82
	v_lshlrev_b32_e32 v82, 16, v83
	v_and_b32_e32 v83, 0xffff0000, v83
	v_lshlrev_b32_e32 v174, 16, v84
	v_and_b32_e32 v175, 0xffff0000, v84
	v_lshlrev_b32_e32 v84, 16, v85
	v_and_b32_e32 v85, 0xffff0000, v85
	s_waitcnt lgkmcnt(1)
	v_pk_fma_f32 v[178:179], v[100:101], v[82:83], v[178:179]
	s_waitcnt lgkmcnt(0)
	v_pk_fma_f32 v[88:89], v[104:105], v[84:85], v[88:89]
	v_pk_fma_f32 v[142:143], v[92:93], v[82:83], v[142:143]
	v_pk_fma_f32 v[146:147], v[96:97], v[84:85], v[146:147]
	v_pk_fma_f32 v[134:135], v[116:117], v[82:83], v[134:135]
	v_pk_fma_f32 v[138:139], v[120:121], v[84:85], v[138:139]
	v_pk_fma_f32 v[126:127], v[108:109], v[82:83], v[126:127]
	v_pk_fma_f32 v[130:131], v[112:113], v[84:85], v[130:131]
	ds_read_b128 v[82:85], v170 offset:2304
	v_pk_fma_f32 v[124:125], v[106:107], v[172:173], v[124:125]
	v_pk_fma_f32 v[128:129], v[110:111], v[174:175], v[128:129]
	ds_read_b128 v[106:109], v151 offset:4608
	ds_read_b128 v[110:113], v151 offset:5376
	v_pk_fma_f32 v[176:177], v[98:99], v[172:173], v[176:177]
	v_pk_fma_f32 v[86:87], v[102:103], v[174:175], v[86:87]
	v_pk_fma_f32 v[140:141], v[90:91], v[172:173], v[140:141]
	v_pk_fma_f32 v[144:145], v[94:95], v[174:175], v[144:145]
	v_pk_fma_f32 v[132:133], v[114:115], v[172:173], v[132:133]
	v_pk_fma_f32 v[136:137], v[118:119], v[174:175], v[136:137]
	s_waitcnt lgkmcnt(2)
	v_lshlrev_b32_e32 v172, 16, v82
	v_and_b32_e32 v173, 0xffff0000, v82
	v_lshlrev_b32_e32 v174, 16, v83
	v_and_b32_e32 v175, 0xffff0000, v83
	v_lshlrev_b32_e32 v182, 16, v84
	v_and_b32_e32 v183, 0xffff0000, v84
	v_lshlrev_b32_e32 v184, 16, v85
	v_and_b32_e32 v185, 0xffff0000, v85
	s_waitcnt lgkmcnt(1)
	v_pk_fma_f32 v[82:83], v[106:107], v[172:173], v[176:177]
	v_pk_fma_f32 v[84:85], v[108:109], v[174:175], v[178:179]
	s_waitcnt lgkmcnt(0)
	v_pk_fma_f32 v[86:87], v[110:111], v[182:183], v[86:87]
	v_pk_fma_f32 v[88:89], v[112:113], v[184:185], v[88:89]
	v_pk_fma_f32 v[140:141], v[98:99], v[172:173], v[140:141]
	v_pk_fma_f32 v[142:143], v[100:101], v[174:175], v[142:143]
	v_pk_fma_f32 v[144:145], v[102:103], v[182:183], v[144:145]
	v_pk_fma_f32 v[146:147], v[104:105], v[184:185], v[146:147]
	v_pk_fma_f32 v[132:133], v[90:91], v[172:173], v[132:133]
	v_pk_fma_f32 v[134:135], v[92:93], v[174:175], v[134:135]
	v_pk_fma_f32 v[136:137], v[94:95], v[182:183], v[136:137]
	v_pk_fma_f32 v[138:139], v[96:97], v[184:185], v[138:139]
	v_pk_fma_f32 v[124:125], v[114:115], v[172:173], v[124:125]
	v_pk_fma_f32 v[126:127], v[116:117], v[174:175], v[126:127]
	v_pk_fma_f32 v[128:129], v[118:119], v[182:183], v[128:129]
	v_pk_fma_f32 v[130:131], v[120:121], v[184:185], v[130:131]
	v_add_u32_e32 v151, 0x1800, v151
	v_add_u32_e32 v170, 0xc00, v170
	s_cbranch_scc0 .LBB0_834
	s_waitcnt vmcnt(0)
	v_mov_b32_e32 v149, v66
	v_mov_b32_e32 v153, v67
	v_mov_b32_e32 v164, v68
	v_mov_b32_e32 v165, v69
	v_mov_b32_e32 v166, v62
	v_mov_b32_e32 v167, v63
	v_mov_b32_e32 v168, v64
	v_mov_b32_e32 v169, v65
	s_ashr_i32 s6, s6, 6
	s_cmpk_eq_i32 s7, 0x7e0
	s_cselect_b64 s[36:37], -1, 0
	s_and_b64 s[2:3], s[36:37], s[38:39]
	s_and_saveexec_b64 s[10:11], s[2:3]
	s_cbranch_execz .LBB0_840
	v_add_u32_e32 v90, 32, v123
	s_mov_b32 s2, 0xd800
	v_add3_u32 v90, v90, v154, s2
	s_add_i32 s2, s6, s4
	s_mul_i32 s12, s2, 30
	s_ashr_i32 s13, s12, 31
	v_cmp_lt_i32_e32 vcc, 0, v152
	s_and_saveexec_b64 s[2:3], vcc
	s_cbranch_execz .LBB0_838
	v_readlane_b32 s16, v243, 31
	v_add_u32_e32 v92, -2, v150
	v_mov_b32_e32 v93, v155
	v_readlane_b32 s17, v243, 32
	v_lshl_add_u64 v[92:93], v[92:93], 0, s[12:13]
	s_movk_i32 s7, 0x600
	v_mov_b64_e32 v[104:105], s[16:17]
	v_mad_u64_u32 v[94:95], s[16:17], v92, s7, v[104:105]
	v_mad_i32_i24 v95, v93, s7, v95
	v_mov_b32_e32 v123, v155
	v_lshl_add_u64 v[106:107], v[94:95], 0, v[122:123]
	ds_read_b128 v[92:95], v90 offset:23040
	s_waitcnt lgkmcnt(0)
	v_lshlrev_b32_e32 v98, 16, v93
	v_lshlrev_b32_e32 v96, 16, v92
	v_and_b32_e32 v99, 0xffff0000, v93
	v_and_b32_e32 v97, 0xffff0000, v92
	v_add_u32_e32 v92, -1, v150
	v_mov_b32_e32 v93, v155
	v_lshl_add_u64 v[92:93], v[92:93], 0, s[12:13]
	v_lshlrev_b32_e32 v102, 16, v95
	v_lshlrev_b32_e32 v100, 16, v94
	v_and_b32_e32 v103, 0xffff0000, v95
	v_and_b32_e32 v101, 0xffff0000, v94
	v_mad_u64_u32 v[94:95], s[16:17], v92, s7, v[104:105]
	global_store_dwordx4 v[106:107], v[100:103], off offset:16
	global_store_dwordx4 v[106:107], v[96:99], off
	v_mad_i32_i24 v95, v93, s7, v95
	v_lshl_add_u64 v[104:105], v[94:95], 0, v[122:123]
	ds_read_b128 v[92:95], v90 offset:23808
	s_waitcnt lgkmcnt(0)
	v_lshlrev_b32_e32 v102, 16, v95
	v_lshlrev_b32_e32 v100, 16, v94
	v_and_b32_e32 v103, 0xffff0000, v95
	v_and_b32_e32 v101, 0xffff0000, v94
	v_lshlrev_b32_e32 v98, 16, v93
	v_lshlrev_b32_e32 v96, 16, v92
	v_and_b32_e32 v99, 0xffff0000, v93
	v_and_b32_e32 v97, 0xffff0000, v92
	global_store_dwordx4 v[104:105], v[100:103], off offset:16
	global_store_dwordx4 v[104:105], v[96:99], off

.LBB0_840:
	s_or_b64 exec, exec, s[10:11]
	s_nop 0
	v_mov_b32_e32 v94, v155
	v_mov_b32_e32 v95, v83
	v_pk_mul_f32 v[90:91], v[82:83], v[82:83]
	v_pk_add_f32 v[94:95], v[82:83], v[94:95]
	v_pk_mul_f32 v[92:93], v[84:85], v[84:85]
	v_pk_mov_b32 v[94:95], v[90:91], v[94:95] op_sel:[1,0]
	v_mov_b32_e32 v91, v83
	v_pk_add_f32 v[90:91], v[90:91], v[94:95]
	v_mov_b32_e32 v94, v92
	v_mov_b32_e32 v95, v84
	v_pk_add_f32 v[90:91], v[90:91], v[94:95]
	v_mov_b32_e32 v92, v93
	v_mov_b32_e32 v93, v85
	v_pk_add_f32 v[92:93], v[92:93], v[90:91]
	v_add_f32_e32 v90, 0, v140
	v_add_f32_e32 v90, v141, v90
	v_add_f32_e32 v99, v142, v90
	v_mov_b32_e32 v90, v140
	v_mov_b32_e32 v91, v142
	v_mul_f32_e32 v98, v141, v141
	v_pk_fma_f32 v[90:91], v[90:91], v[90:91], v[98:99] op_sel_hi:[1,1,0]
	v_mul_f32_e32 v98, v142, v142
	v_pk_add_f32 v[90:91], v[90:91], v[98:99] op_sel_hi:[1,0]
	v_add_f32_e32 v98, v143, v99
	v_add_f32_e32 v101, v144, v98
	v_mul_f32_e32 v100, v143, v143
	v_mov_b32_e32 v98, v144
	v_mov_b32_e32 v99, v143
	v_pk_add_f32 v[90:91], v[100:101], v[90:91] op_sel_hi:[0,1]
	v_pk_fma_f32 v[90:91], v[98:99], v[98:99], v[90:91]
	v_add_f32_e32 v98, v145, v101
	v_add_f32_e32 v99, v146, v98
	v_mul_f32_e32 v98, v145, v145
	v_mov_b32_e32 v100, v146
	v_mov_b32_e32 v101, v145
	v_pk_add_f32 v[90:91], v[98:99], v[90:91] op_sel_hi:[0,1]
	v_pk_fma_f32 v[100:101], v[100:101], v[100:101], v[90:91]
	v_add_f32_e32 v90, 0, v132
	v_add_f32_e32 v90, v133, v90
	v_add_f32_e32 v101, v134, v90
	v_mov_b32_e32 v90, v132
	v_mov_b32_e32 v91, v134
	v_mul_f32_e32 v98, v133, v133
	v_pk_fma_f32 v[90:91], v[90:91], v[90:91], v[98:99] op_sel_hi:[1,1,0]
	v_mul_f32_e32 v98, v134, v134
	v_pk_add_f32 v[90:91], v[90:91], v[98:99] op_sel_hi:[1,0]
	v_add_f32_e32 v98, v135, v101
	v_add_f32_e32 v101, v136, v98
	v_mul_f32_e32 v98, v135, v135
	v_mov_b32_e32 v102, v136
	v_mov_b32_e32 v103, v135
	v_pk_add_f32 v[90:91], v[98:99], v[90:91] op_sel_hi:[0,1]
	v_add_f32_e32 v98, v137, v101
	v_pk_fma_f32 v[90:91], v[102:103], v[102:103], v[90:91]
	v_add_f32_e32 v103, v138, v98
	v_mul_f32_e32 v98, v137, v137
	v_mov_b32_e32 v104, v138
	v_mov_b32_e32 v105, v137
	v_pk_add_f32 v[90:91], v[98:99], v[90:91] op_sel_hi:[0,1]
	v_pk_fma_f32 v[104:105], v[104:105], v[104:105], v[90:91]
	v_add_f32_e32 v90, 0, v124
	v_add_f32_e32 v90, v125, v90
	v_add_f32_e32 v101, v126, v90
	v_mov_b32_e32 v90, v124
	v_mov_b32_e32 v91, v126
	v_mul_f32_e32 v98, v125, v125
	v_pk_fma_f32 v[90:91], v[90:91], v[90:91], v[98:99] op_sel_hi:[1,1,0]
	v_mul_f32_e32 v98, v126, v126
	v_pk_add_f32 v[90:91], v[90:91], v[98:99] op_sel_hi:[1,0]
	v_add_f32_e32 v98, v127, v101
	v_add_f32_e32 v101, v128, v98
	v_mul_f32_e32 v98, v127, v127
	v_mov_b32_e32 v106, v128
	v_mov_b32_e32 v107, v127
	v_pk_add_f32 v[90:91], v[98:99], v[90:91] op_sel_hi:[0,1]
	v_pk_mul_f32 v[94:95], v[86:87], v[86:87]
	v_pk_fma_f32 v[106:107], v[106:107], v[106:107], v[90:91]
	v_add_f32_e32 v90, v129, v101
	v_add_f32_e32 v91, v130, v90
	v_mul_f32_e32 v90, v129, v129
	v_mov_b32_e32 v110, v94
	v_mov_b32_e32 v111, v86
	v_pk_mul_f32 v[96:97], v[88:89], v[88:89]
	v_pk_add_f32 v[106:107], v[90:91], v[106:107] op_sel_hi:[0,1]
	v_and_b32_e32 v90, 64, v181
	v_pk_add_f32 v[92:93], v[92:93], v[110:111]
	v_mov_b32_e32 v94, v95
	v_mov_b32_e32 v95, v87
	v_add_u32_e32 v90, 64, v90
	v_xor_b32_e32 v98, 32, v181
	v_pk_add_f32 v[92:93], v[94:95], v[92:93]
	v_mov_b32_e32 v94, v96
	v_mov_b32_e32 v95, v88
	v_cmp_lt_i32_e32 vcc, v98, v90
	v_pk_add_f32 v[92:93], v[92:93], v[94:95]
	v_mov_b32_e32 v94, v97
	v_mov_b32_e32 v95, v89
	v_cndmask_b32_e32 v98, v181, v98, vcc
	v_pk_add_f32 v[92:93], v[94:95], v[92:93]
	v_lshlrev_b32_e32 v112, 2, v98
	v_cndmask_b32_e64 v93, 0, v93, s[38:39]
	v_cndmask_b32_e64 v92, 0, v92, s[38:39]
	ds_bpermute_b32 v95, v112, v93
	ds_bpermute_b32 v94, v112, v92
	v_xor_b32_e32 v98, 16, v181
	v_cmp_lt_i32_e32 vcc, v98, v90
	v_mov_b32_e32 v101, v147
	v_xor_b32_e32 v102, 2, v181
	v_cndmask_b32_e32 v98, v181, v98, vcc
	v_lshlrev_b32_e32 v113, 2, v98
	v_xor_b32_e32 v98, 8, v181
	v_cmp_lt_i32_e32 vcc, v98, v90
	s_waitcnt lgkmcnt(0)
	v_pk_add_f32 v[92:93], v[92:93], v[94:95]
	ds_bpermute_b32 v95, v113, v93
	v_cndmask_b32_e32 v96, v181, v98, vcc
	ds_bpermute_b32 v94, v113, v92
	v_lshlrev_b32_e32 v110, 2, v96
	v_xor_b32_e32 v96, 4, v181
	v_cmp_lt_i32_e32 vcc, v96, v90
	v_mul_f32_e32 v98, v147, v147
	s_waitcnt lgkmcnt(0)
	v_pk_add_f32 v[92:93], v[92:93], v[94:95]
	v_cndmask_b32_e32 v96, v181, v96, vcc
	v_lshlrev_b32_e32 v111, 2, v96
	v_pk_add_f32 v[96:97], v[100:101], v[98:99]
	ds_bpermute_b32 v95, v110, v93
	v_cndmask_b32_e64 v97, 0, v97, s[38:39]
	v_cndmask_b32_e64 v96, 0, v96, s[38:39]
	ds_bpermute_b32 v94, v110, v92
	ds_bpermute_b32 v99, v112, v97
	ds_bpermute_b32 v98, v112, v96
	v_cmp_lt_i32_e32 vcc, v102, v90
	v_mov_b32_e32 v108, v130
	s_waitcnt lgkmcnt(2)
	v_pk_add_f32 v[92:93], v[92:93], v[94:95]
	ds_bpermute_b32 v95, v111, v93
	s_waitcnt lgkmcnt(1)
	v_pk_add_f32 v[96:97], v[96:97], v[98:99]
	ds_bpermute_b32 v94, v111, v92
	ds_bpermute_b32 v99, v113, v97
	ds_bpermute_b32 v98, v113, v96
	v_cndmask_b32_e32 v100, v181, v102, vcc
	v_lshlrev_b32_e32 v116, 2, v100
	s_waitcnt lgkmcnt(2)
	v_pk_add_f32 v[92:93], v[92:93], v[94:95]
	ds_bpermute_b32 v95, v116, v93
	s_waitcnt lgkmcnt(1)
	v_pk_add_f32 v[96:97], v[96:97], v[98:99]
	ds_bpermute_b32 v94, v116, v92
	ds_bpermute_b32 v99, v110, v97
	ds_bpermute_b32 v98, v110, v96
	v_mov_b32_e32 v109, v129
	v_pk_fma_f32 v[100:101], v[108:109], v[108:109], v[106:107]
	s_waitcnt lgkmcnt(2)
	v_pk_add_f32 v[118:119], v[92:93], v[94:95]
	v_xor_b32_e32 v101, 1, v181
	s_waitcnt lgkmcnt(0)
	v_pk_add_f32 v[92:93], v[96:97], v[98:99]
	ds_bpermute_b32 v95, v111, v93
	ds_bpermute_b32 v94, v111, v92
	v_cmp_lt_i32_e32 vcc, v101, v90
	v_mov_b32_e32 v105, v139
	v_mul_f32_e32 v102, v139, v139
	v_cndmask_b32_e32 v90, v181, v101, vcc
	v_lshlrev_b32_e32 v108, 2, v90
	v_mov_b32_e32 v101, v131
	v_mul_f32_e32 v90, v131, v131
	s_waitcnt lgkmcnt(0)
	v_pk_add_f32 v[92:93], v[92:93], v[94:95]
	v_pk_add_f32 v[94:95], v[104:105], v[102:103]
	v_pk_add_f32 v[90:91], v[100:101], v[90:91]
	v_cndmask_b32_e64 v95, 0, v95, s[38:39]
	v_cndmask_b32_e64 v94, 0, v94, s[38:39]
	v_cndmask_b32_e64 v91, 0, v91, s[38:39]
	v_cndmask_b32_e64 v90, 0, v90, s[38:39]
	ds_bpermute_b32 v97, v112, v95
	ds_bpermute_b32 v96, v112, v94
	ds_bpermute_b32 v99, v112, v91
	ds_bpermute_b32 v98, v112, v90
	ds_bpermute_b32 v101, v116, v93
	ds_bpermute_b32 v100, v116, v92
	s_waitcnt lgkmcnt(4)
	v_pk_add_f32 v[94:95], v[94:95], v[96:97]
	ds_bpermute_b32 v97, v113, v95
	s_waitcnt lgkmcnt(3)
	v_pk_add_f32 v[90:91], v[90:91], v[98:99]
	ds_bpermute_b32 v96, v113, v94
	ds_bpermute_b32 v99, v113, v91
	ds_bpermute_b32 v98, v113, v90
	s_waitcnt lgkmcnt(4)
	v_pk_add_f32 v[114:115], v[92:93], v[100:101]
	ds_bpermute_b32 v121, v108, v119
	s_waitcnt lgkmcnt(3)
	v_pk_add_f32 v[94:95], v[94:95], v[96:97]
	ds_bpermute_b32 v97, v110, v95
	s_waitcnt lgkmcnt(2)
	v_pk_add_f32 v[90:91], v[90:91], v[98:99]
	ds_bpermute_b32 v96, v110, v94
	ds_bpermute_b32 v99, v110, v91
	ds_bpermute_b32 v98, v110, v90
	ds_bpermute_b32 v120, v108, v118
	ds_bpermute_b32 v117, v108, v115
	s_waitcnt lgkmcnt(4)
	v_pk_add_f32 v[92:93], v[94:95], v[96:97]
	ds_bpermute_b32 v95, v111, v93
	s_waitcnt lgkmcnt(3)
	v_pk_add_f32 v[90:91], v[90:91], v[98:99]
	ds_bpermute_b32 v94, v111, v92
	ds_bpermute_b32 v97, v111, v91
	ds_bpermute_b32 v96, v111, v90
	v_lshl_or_b32 v148, v148, 11, v154
	v_add_u32_e32 v123, 0x1000, v148
	s_waitcnt lgkmcnt(2)
	v_pk_add_f32 v[92:93], v[92:93], v[94:95]
	ds_bpermute_b32 v95, v116, v93
	s_waitcnt lgkmcnt(1)
	v_pk_add_f32 v[90:91], v[90:91], v[96:97]
	ds_bpermute_b32 v94, v116, v92
	ds_bpermute_b32 v97, v116, v91
	ds_bpermute_b32 v96, v116, v90
	ds_bpermute_b32 v116, v108, v114
	s_waitcnt lgkmcnt(3)
	v_pk_add_f32 v[110:111], v[92:93], v[94:95]
	ds_bpermute_b32 v113, v108, v111
	s_waitcnt lgkmcnt(2)
	v_pk_add_f32 v[106:107], v[90:91], v[96:97]
	ds_bpermute_b32 v112, v108, v110
	ds_bpermute_b32 v109, v108, v107
	ds_bpermute_b32 v108, v108, v106
	s_and_saveexec_b64 s[12:13], s[38:39]
	s_cbranch_execz .LBB0_842
	v_mov_b64_e32 v[90:91], v[194:195]
	v_mov_b64_e32 v[92:93], v[196:197]
	v_mov_b64_e32 v[98:99], v[198:199]
	v_mov_b64_e32 v[100:101], v[200:201]
	v_mov_b64_e32 v[94:95], v[202:203]
	v_mov_b64_e32 v[96:97], v[204:205]
	v_mov_b64_e32 v[102:103], v[206:207]
	v_mov_b64_e32 v[104:105], v[208:209]
	v_pk_add_f32 v[118:119], v[118:119], v[120:121]
	s_mov_b32 s2, 0x3b2aaaab
	v_pk_mul_f32 v[118:119], v[118:119], s[2:3] op_sel_hi:[1,0]
	v_and_b32_e32 v150, 0xffff0000, v81
	v_fma_f32 v118, -v119, v119, v118
	v_max_f32_e32 v118, 0, v118
	v_add_f32_e32 v118, 0x358637bd, v118
	v_cmp_gt_f32_e32 vcc, s33, v118
	v_mul_f32_e32 v120, 0x4b800000, v118
	v_sub_f32_e32 v89, v89, v119
	v_cndmask_b32_e32 v118, v118, v120, vcc
	v_rsq_f32_e32 v118, v118
	v_sub_f32_e32 v88, v88, v119
	v_sub_f32_e32 v87, v87, v119
	v_sub_f32_e32 v86, v86, v119
	v_mul_f32_e32 v120, 0x45800000, v118
	v_cndmask_b32_e32 v118, v118, v120, vcc
	v_mul_f32_e32 v89, v89, v118
	v_mul_f32_e32 v88, v88, v118
	v_mul_f32_e32 v87, v87, v118
	v_lshlrev_b32_e32 v81, 16, v81
	v_mul_f32_e32 v86, v86, v118
	v_sub_f32_e32 v85, v85, v119
	v_mul_f32_e32 v85, v85, v118
	v_sub_f32_e32 v84, v84, v119
	v_mul_f32_e32 v84, v84, v118
	v_sub_f32_e32 v83, v83, v119
	v_mul_f32_e32 v83, v83, v118
	v_sub_f32_e32 v82, v82, v119
	v_mul_f32_e32 v82, v82, v118
	s_mov_b32 s10, s66
	s_mov_b32 s11, s67
	v_fma_f32 v85, v85, v97, v93
	v_fma_f32 v89, v89, v105, v101
	v_mul_f32_e32 v120, 0xbfb8aa3b, v89
	v_exp_f32_e32 v120, v120
	v_fma_f32 v88, v88, v104, v100
	v_fma_f32 v87, v87, v103, v99
	v_fma_f32 v86, v86, v102, v98
	v_add_f32_e32 v120, 1.0, v120
	v_rcp_f32_e32 v120, v120
	v_fma_f32 v84, v84, v96, v92
	v_fma_f32 v83, v83, v95, v91
	v_fma_f32 v82, v82, v94, v90
	v_mul_f32_e32 v89, v89, v120
	v_mul_f32_e32 v120, 0xbfb8aa3b, v88
	v_exp_f32_e32 v120, v120
	v_mul_f32_e32 v89, v89, v150
	v_add_f32_e32 v120, 1.0, v120
	v_rcp_f32_e32 v120, v120
	s_nop 0
	v_mul_f32_e32 v88, v88, v120
	v_mul_f32_e32 v120, 0xbfb8aa3b, v87
	v_exp_f32_e32 v120, v120
	v_mul_f32_e32 v81, v88, v81
	v_and_b32_e32 v88, 0xffff0000, v80
	v_lshlrev_b32_e32 v80, 16, v80
	v_add_f32_e32 v120, 1.0, v120
	v_rcp_f32_e32 v120, v120
	s_nop 0
	v_mul_f32_e32 v87, v87, v120
	v_mul_f32_e32 v87, v87, v88
	v_mul_f32_e32 v88, 0xbfb8aa3b, v86
	v_exp_f32_e32 v88, v88
	s_nop 0
	v_add_f32_e32 v88, 1.0, v88
	v_rcp_f32_e32 v88, v88
	s_nop 0
	v_mul_f32_e32 v86, v86, v88
	v_mul_f32_e32 v88, 0xbfb8aa3b, v85
	v_exp_f32_e32 v88, v88
	v_mul_f32_e32 v80, v86, v80
	v_and_b32_e32 v86, 0xffff0000, v79
	v_lshlrev_b32_e32 v79, 16, v79
	v_add_f32_e32 v88, 1.0, v88
	v_rcp_f32_e32 v88, v88
	s_nop 0
	v_mul_f32_e32 v85, v85, v88
	v_mul_f32_e32 v85, v85, v86
	v_mul_f32_e32 v86, 0xbfb8aa3b, v84
	v_exp_f32_e32 v86, v86
	s_nop 0
	v_add_f32_e32 v86, 1.0, v86
	v_rcp_f32_e32 v86, v86
	s_nop 0
	v_mul_f32_e32 v84, v84, v86
	v_mul_f32_e32 v86, 0xbfb8aa3b, v83
	v_exp_f32_e32 v86, v86
	v_mul_f32_e32 v79, v84, v79
	v_and_b32_e32 v84, 0xffff0000, v78
	v_lshlrev_b32_e32 v78, 16, v78
	v_add_f32_e32 v86, 1.0, v86
	v_rcp_f32_e32 v86, v86
	s_nop 0
	v_mul_f32_e32 v83, v83, v86
	v_mul_f32_e32 v83, v83, v84
	v_mul_f32_e32 v84, 0xbfb8aa3b, v82
	v_exp_f32_e32 v84, v84
	s_nop 0
	v_add_f32_e32 v84, 1.0, v84
	v_rcp_f32_e32 v84, v84
	s_nop 0
	v_mul_f32_e32 v82, v82, v84
	v_mul_f32_e32 v78, v82, v78
	v_cvt_pk_bf16_f32 v78, v78, v83
	v_cvt_pk_bf16_f32 v79, v79, v85
	v_cvt_pk_bf16_f32 v80, v80, v87
	v_cvt_pk_bf16_f32 v81, v81, v89
	buffer_store_dwordx4 v[78:81], v148, s[8:11], 0 offen sc1
	s_waitcnt lgkmcnt(4)
	s_nop 0
	v_pk_add_f32 v[78:79], v[114:115], v[116:117]
	v_and_b32_e32 v80, 0xffff0000, v77
	v_pk_mul_f32 v[78:79], v[78:79], s[2:3] op_sel_hi:[1,0]
	v_lshlrev_b32_e32 v77, 16, v77
	v_fma_f32 v78, -v79, v79, v78
	v_max_f32_e32 v78, 0, v78
	v_add_f32_e32 v78, 0x358637bd, v78
	v_cmp_gt_f32_e32 vcc, s33, v78
	v_mul_f32_e32 v81, 0x4b800000, v78
	s_nop 0
	v_cndmask_b32_e32 v78, v78, v81, vcc
	v_rsq_f32_e32 v78, v78
	s_nop 0
	v_mul_f32_e32 v81, 0x45800000, v78
	v_cndmask_b32_e32 v78, v78, v81, vcc
	v_sub_f32_e32 v81, v147, v79
	v_mul_f32_e32 v81, v81, v78
	v_fma_f32 v81, v81, v105, v101
	v_mul_f32_e32 v82, 0xbfb8aa3b, v81
	v_exp_f32_e32 v82, v82
	s_nop 0
	v_add_f32_e32 v82, 1.0, v82
	v_rcp_f32_e32 v82, v82
	s_nop 0
	v_mul_f32_e32 v81, v81, v82
	v_mul_f32_e32 v80, v81, v80
	v_sub_f32_e32 v81, v146, v79
	v_mul_f32_e32 v81, v81, v78
	v_fma_f32 v81, v81, v104, v100
	v_mul_f32_e32 v82, 0xbfb8aa3b, v81
	v_exp_f32_e32 v82, v82
	s_nop 0
	v_add_f32_e32 v82, 1.0, v82
	v_rcp_f32_e32 v82, v82
	s_nop 0
	v_mul_f32_e32 v81, v81, v82
	v_sub_f32_e32 v82, v145, v79
	v_mul_f32_e32 v82, v82, v78
	v_fma_f32 v82, v82, v103, v99
	v_mul_f32_e32 v83, 0xbfb8aa3b, v82
	v_exp_f32_e32 v83, v83
	v_mul_f32_e32 v77, v81, v77
	v_and_b32_e32 v81, 0xffff0000, v76
	v_lshlrev_b32_e32 v76, 16, v76
	v_add_f32_e32 v83, 1.0, v83
	v_rcp_f32_e32 v83, v83
	s_nop 0
	v_mul_f32_e32 v82, v82, v83
	v_mul_f32_e32 v81, v82, v81
	v_sub_f32_e32 v82, v144, v79
	v_mul_f32_e32 v82, v82, v78
	v_fma_f32 v82, v82, v102, v98
	v_mul_f32_e32 v83, 0xbfb8aa3b, v82
	v_exp_f32_e32 v83, v83
	s_nop 0
	v_add_f32_e32 v83, 1.0, v83
	v_rcp_f32_e32 v83, v83
	s_nop 0
	v_mul_f32_e32 v82, v82, v83
	v_sub_f32_e32 v83, v143, v79
	v_mul_f32_e32 v83, v83, v78
	v_fma_f32 v83, v83, v97, v93
	v_mul_f32_e32 v84, 0xbfb8aa3b, v83
	v_exp_f32_e32 v84, v84
	v_mul_f32_e32 v76, v82, v76
	v_and_b32_e32 v82, 0xffff0000, v75
	v_lshlrev_b32_e32 v75, 16, v75
	v_add_f32_e32 v84, 1.0, v84
	v_rcp_f32_e32 v84, v84
	s_nop 0
	v_mul_f32_e32 v83, v83, v84
	v_mul_f32_e32 v82, v83, v82
	v_sub_f32_e32 v83, v142, v79
	v_mul_f32_e32 v83, v83, v78
	v_fma_f32 v83, v83, v96, v92
	v_mul_f32_e32 v84, 0xbfb8aa3b, v83
	v_exp_f32_e32 v84, v84
	s_nop 0
	v_add_f32_e32 v84, 1.0, v84
	v_rcp_f32_e32 v84, v84
	s_nop 0
	v_mul_f32_e32 v83, v83, v84
	v_sub_f32_e32 v84, v141, v79
	v_sub_f32_e32 v79, v140, v79
	v_mul_f32_e32 v84, v84, v78
	v_mul_f32_e32 v78, v79, v78
	v_fma_f32 v78, v78, v94, v90
	v_fma_f32 v84, v84, v95, v91
	v_mul_f32_e32 v79, 0xbfb8aa3b, v78
	v_mul_f32_e32 v85, 0xbfb8aa3b, v84
	v_exp_f32_e32 v79, v79
	v_exp_f32_e32 v85, v85
	v_mul_f32_e32 v75, v83, v75
	v_and_b32_e32 v83, 0xffff0000, v74
	v_add_f32_e32 v79, 1.0, v79
	v_add_f32_e32 v85, 1.0, v85
	v_rcp_f32_e32 v79, v79
	v_rcp_f32_e32 v85, v85
	v_lshlrev_b32_e32 v74, 16, v74
	v_mul_f32_e32 v78, v78, v79
	v_mul_f32_e32 v84, v84, v85
	v_mul_f32_e32 v74, v78, v74
	v_mul_f32_e32 v83, v84, v83
	v_cvt_pk_bf16_f32 v74, v74, v83
	v_cvt_pk_bf16_f32 v75, v75, v82
	v_cvt_pk_bf16_f32 v76, v76, v81
	v_cvt_pk_bf16_f32 v77, v77, v80
	buffer_store_dwordx4 v[74:77], v148, s[8:11], 0 offen offset:2048 sc1
	s_waitcnt lgkmcnt(2)
	s_nop 0
	v_pk_add_f32 v[74:75], v[110:111], v[112:113]
	v_and_b32_e32 v76, 0xffff0000, v73
	v_pk_mul_f32 v[74:75], v[74:75], s[2:3] op_sel_hi:[1,0]
	v_lshlrev_b32_e32 v73, 16, v73
	v_fma_f32 v74, -v75, v75, v74
	v_max_f32_e32 v74, 0, v74
	v_add_f32_e32 v74, 0x358637bd, v74
	v_cmp_gt_f32_e32 vcc, s33, v74
	v_mul_f32_e32 v77, 0x4b800000, v74
	s_nop 0
	v_cndmask_b32_e32 v74, v74, v77, vcc
	v_rsq_f32_e32 v74, v74
	s_nop 0
	v_mul_f32_e32 v77, 0x45800000, v74
	v_cndmask_b32_e32 v74, v74, v77, vcc
	v_sub_f32_e32 v77, v139, v75
	v_mul_f32_e32 v77, v77, v74
	v_fma_f32 v77, v77, v105, v101
	v_mul_f32_e32 v78, 0xbfb8aa3b, v77
	v_exp_f32_e32 v78, v78
	s_nop 0
	v_add_f32_e32 v78, 1.0, v78
	v_rcp_f32_e32 v78, v78
	s_nop 0
	v_mul_f32_e32 v77, v77, v78
	v_mul_f32_e32 v76, v77, v76
	v_sub_f32_e32 v77, v138, v75
	v_mul_f32_e32 v77, v77, v74
	v_fma_f32 v77, v77, v104, v100
	v_mul_f32_e32 v78, 0xbfb8aa3b, v77
	v_exp_f32_e32 v78, v78
	s_nop 0
	v_add_f32_e32 v78, 1.0, v78
	v_rcp_f32_e32 v78, v78
	s_nop 0
	v_mul_f32_e32 v77, v77, v78
	v_sub_f32_e32 v78, v137, v75
	v_mul_f32_e32 v78, v78, v74
	v_fma_f32 v78, v78, v103, v99
	v_mul_f32_e32 v79, 0xbfb8aa3b, v78
	v_exp_f32_e32 v79, v79
	v_mul_f32_e32 v73, v77, v73
	v_and_b32_e32 v77, 0xffff0000, v72
	v_lshlrev_b32_e32 v72, 16, v72
	v_add_f32_e32 v79, 1.0, v79
	v_rcp_f32_e32 v79, v79
	s_nop 0
	v_mul_f32_e32 v78, v78, v79
	v_mul_f32_e32 v77, v78, v77
	v_sub_f32_e32 v78, v136, v75
	v_mul_f32_e32 v78, v78, v74
	v_fma_f32 v78, v78, v102, v98
	v_mul_f32_e32 v79, 0xbfb8aa3b, v78
	v_exp_f32_e32 v79, v79
	s_nop 0
	v_add_f32_e32 v79, 1.0, v79
	v_rcp_f32_e32 v79, v79
	s_nop 0
	v_mul_f32_e32 v78, v78, v79
	v_sub_f32_e32 v79, v135, v75
	v_mul_f32_e32 v79, v79, v74
	v_fma_f32 v79, v79, v97, v93
	v_mul_f32_e32 v80, 0xbfb8aa3b, v79
	v_exp_f32_e32 v80, v80
	v_mul_f32_e32 v72, v78, v72
	v_and_b32_e32 v78, 0xffff0000, v71
	v_lshlrev_b32_e32 v71, 16, v71
	v_add_f32_e32 v80, 1.0, v80
	v_rcp_f32_e32 v80, v80
	s_nop 0
	v_mul_f32_e32 v79, v79, v80
	v_mul_f32_e32 v78, v79, v78
	v_sub_f32_e32 v79, v134, v75
	v_mul_f32_e32 v79, v79, v74
	v_fma_f32 v79, v79, v96, v92
	v_mul_f32_e32 v80, 0xbfb8aa3b, v79
	v_exp_f32_e32 v80, v80
	s_nop 0
	v_add_f32_e32 v80, 1.0, v80
	v_rcp_f32_e32 v80, v80
	s_nop 0
	v_mul_f32_e32 v79, v79, v80
	v_sub_f32_e32 v80, v133, v75
	v_sub_f32_e32 v75, v132, v75
	v_mul_f32_e32 v80, v80, v74
	v_mul_f32_e32 v74, v75, v74
	v_fma_f32 v74, v74, v94, v90
	v_fma_f32 v80, v80, v95, v91
	v_mul_f32_e32 v75, 0xbfb8aa3b, v74
	v_mul_f32_e32 v81, 0xbfb8aa3b, v80
	v_exp_f32_e32 v75, v75
	v_exp_f32_e32 v81, v81
	v_mul_f32_e32 v71, v79, v71
	v_and_b32_e32 v79, 0xffff0000, v70
	v_add_f32_e32 v75, 1.0, v75
	v_add_f32_e32 v81, 1.0, v81
	v_rcp_f32_e32 v75, v75
	v_rcp_f32_e32 v81, v81
	v_lshlrev_b32_e32 v70, 16, v70
	v_mul_f32_e32 v74, v74, v75
	v_mul_f32_e32 v80, v80, v81
	v_mul_f32_e32 v70, v74, v70
	v_mul_f32_e32 v79, v80, v79
	v_cvt_pk_bf16_f32 v70, v70, v79
	v_cvt_pk_bf16_f32 v71, v71, v78
	v_cvt_pk_bf16_f32 v72, v72, v77
	v_cvt_pk_bf16_f32 v73, v73, v76
	buffer_store_dwordx4 v[70:73], v123, s[8:11], 0 offen sc1
	s_waitcnt lgkmcnt(0)
	s_nop 0
	v_pk_add_f32 v[70:71], v[106:107], v[108:109]
	v_and_b32_e32 v72, 0xffff0000, v61
	v_pk_mul_f32 v[70:71], v[70:71], s[2:3] op_sel_hi:[1,0]
	v_lshlrev_b32_e32 v61, 16, v61
	v_fma_f32 v70, -v71, v71, v70
	v_max_f32_e32 v70, 0, v70
	v_add_f32_e32 v70, 0x358637bd, v70
	v_cmp_gt_f32_e32 vcc, s33, v70
	v_mul_f32_e32 v73, 0x4b800000, v70
	s_nop 0
	v_cndmask_b32_e32 v70, v70, v73, vcc
	v_rsq_f32_e32 v70, v70
	s_nop 0
	v_mul_f32_e32 v73, 0x45800000, v70
	v_cndmask_b32_e32 v70, v70, v73, vcc
	v_sub_f32_e32 v73, v131, v71
	v_mul_f32_e32 v73, v73, v70
	v_fma_f32 v73, v73, v105, v101
	v_mul_f32_e32 v74, 0xbfb8aa3b, v73
	v_exp_f32_e32 v74, v74
	s_nop 0
	v_add_f32_e32 v74, 1.0, v74
	v_rcp_f32_e32 v74, v74
	s_nop 0
	v_mul_f32_e32 v73, v73, v74
	v_mul_f32_e32 v72, v73, v72
	v_sub_f32_e32 v73, v130, v71
	v_mul_f32_e32 v73, v73, v70
	v_fma_f32 v73, v73, v104, v100
	v_mul_f32_e32 v74, 0xbfb8aa3b, v73
	v_exp_f32_e32 v74, v74
	s_nop 0
	v_add_f32_e32 v74, 1.0, v74
	v_rcp_f32_e32 v74, v74
	s_nop 0
	v_mul_f32_e32 v73, v73, v74
	v_sub_f32_e32 v74, v129, v71
	v_mul_f32_e32 v74, v74, v70
	v_fma_f32 v74, v74, v103, v99
	v_mul_f32_e32 v75, 0xbfb8aa3b, v74
	v_exp_f32_e32 v75, v75
	v_mul_f32_e32 v61, v73, v61
	v_and_b32_e32 v73, 0xffff0000, v60
	v_lshlrev_b32_e32 v60, 16, v60
	v_add_f32_e32 v75, 1.0, v75
	v_rcp_f32_e32 v75, v75
	s_nop 0
	v_mul_f32_e32 v74, v74, v75
	v_mul_f32_e32 v73, v74, v73
	v_sub_f32_e32 v74, v128, v71
	v_mul_f32_e32 v74, v74, v70
	v_sub_f32_e32 v75, v127, v71
	v_fmac_f32_e32 v98, v74, v102
	v_mul_f32_e32 v75, v75, v70
	v_mul_f32_e32 v74, 0xbfb8aa3b, v98
	v_fma_f32 v75, v75, v97, v93
	v_exp_f32_e32 v74, v74
	v_mul_f32_e32 v76, 0xbfb8aa3b, v75
	v_exp_f32_e32 v76, v76
	v_add_f32_e32 v74, 1.0, v74
	v_rcp_f32_e32 v74, v74
	v_add_f32_e32 v76, 1.0, v76
	v_rcp_f32_e32 v76, v76
	v_mul_f32_e32 v74, v98, v74
	v_mul_f32_e32 v60, v74, v60
	v_and_b32_e32 v74, 0xffff0000, v59
	v_mul_f32_e32 v75, v75, v76
	v_mul_f32_e32 v74, v75, v74
	v_sub_f32_e32 v75, v126, v71
	v_mul_f32_e32 v75, v75, v70
	v_fma_f32 v75, v75, v96, v92
	v_mul_f32_e32 v76, 0xbfb8aa3b, v75
	v_exp_f32_e32 v76, v76
	v_lshlrev_b32_e32 v59, 16, v59
	v_add_f32_e32 v76, 1.0, v76
	v_rcp_f32_e32 v76, v76
	s_nop 0
	v_mul_f32_e32 v75, v75, v76
	v_sub_f32_e32 v76, v125, v71
	v_sub_f32_e32 v71, v124, v71
	v_mul_f32_e32 v76, v76, v70
	v_mul_f32_e32 v70, v71, v70
	v_fmac_f32_e32 v90, v70, v94
	v_fma_f32 v76, v76, v95, v91
	v_mul_f32_e32 v70, 0xbfb8aa3b, v90
	v_mul_f32_e32 v77, 0xbfb8aa3b, v76
	v_exp_f32_e32 v70, v70
	v_exp_f32_e32 v77, v77
	v_mul_f32_e32 v59, v75, v59
	v_and_b32_e32 v75, 0xffff0000, v58
	v_add_f32_e32 v70, 1.0, v70
	v_add_f32_e32 v77, 1.0, v77
	v_rcp_f32_e32 v70, v70
	v_rcp_f32_e32 v77, v77
	v_lshlrev_b32_e32 v58, 16, v58
	v_mul_f32_e32 v70, v90, v70
	v_mul_f32_e32 v76, v76, v77
	v_mul_f32_e32 v58, v70, v58
	v_mul_f32_e32 v75, v76, v75
	v_cvt_pk_bf16_f32 v58, v58, v75
	v_cvt_pk_bf16_f32 v59, v59, v74
	v_cvt_pk_bf16_f32 v60, v60, v73
	v_cvt_pk_bf16_f32 v61, v61, v72
	buffer_store_dwordx4 v[58:61], v123, s[8:11], 0 offen offset:2048 sc1
.LBB0_842:
	s_or_b64 exec, exec, s[12:13]
	v_lshlrev_b32_e32 v74, 16, v69
	v_lshlrev_b32_e32 v72, 16, v68
	v_lshlrev_b32_e32 v70, 16, v67
	v_lshlrev_b32_e32 v68, 16, v66
	v_and_b32_e32 v75, 0xffff0000, v165
	v_and_b32_e32 v73, 0xffff0000, v164
	v_and_b32_e32 v71, 0xffff0000, v153
	v_and_b32_e32 v69, 0xffff0000, v149
	v_lshlrev_b32_e32 v66, 16, v65
	v_lshlrev_b32_e32 v64, 16, v64
	v_lshlrev_b32_e32 v60, 16, v63
	v_lshlrev_b32_e32 v58, 16, v62
	v_and_b32_e32 v67, 0xffff0000, v169
	v_and_b32_e32 v65, 0xffff0000, v168
	v_and_b32_e32 v61, 0xffff0000, v167
	v_and_b32_e32 v59, 0xffff0000, v166
	s_and_saveexec_b64 s[12:13], s[38:39]
	s_cbranch_execz .LBB0_844
	v_and_b32_e32 v97, 0xffff0000, v57
	v_lshlrev_b32_e32 v95, 16, v57
	v_and_b32_e32 v93, 0xffff0000, v56
	v_lshlrev_b32_e32 v91, 16, v56
	v_and_b32_e32 v89, 0xffff0000, v55
	v_lshlrev_b32_e32 v87, 16, v55
	v_and_b32_e32 v85, 0xffff0000, v54
	v_lshlrev_b32_e32 v63, 16, v54
	s_waitcnt lgkmcnt(3)
	v_and_b32_e32 v113, 0xffff0000, v49
	s_waitcnt lgkmcnt(2)
	v_and_b32_e32 v112, 0xffff0000, v53
	v_lshlrev_b32_e32 v110, 16, v53
	v_lshlrev_b32_e32 v111, 16, v49
	s_waitcnt lgkmcnt(1)
	v_and_b32_e32 v109, 0xffff0000, v48
	s_waitcnt lgkmcnt(0)
	v_and_b32_e32 v108, 0xffff0000, v52
	v_lshlrev_b32_e32 v106, 16, v52
	v_lshlrev_b32_e32 v107, 16, v48
	v_and_b32_e32 v105, 0xffff0000, v47
	v_and_b32_e32 v104, 0xffff0000, v51
	v_lshlrev_b32_e32 v102, 16, v51
	v_lshlrev_b32_e32 v103, 16, v47
	v_and_b32_e32 v101, 0xffff0000, v46
	v_and_b32_e32 v100, 0xffff0000, v50
	v_lshlrev_b32_e32 v98, 16, v50
	v_lshlrev_b32_e32 v99, 16, v46
	v_mov_b64_e32 v[46:47], v[210:211]
	v_mov_b64_e32 v[48:49], v[212:213]
	v_mov_b64_e32 v[54:55], v[214:215]
	v_mov_b64_e32 v[56:57], v[216:217]
	v_mov_b64_e32 v[80:81], v[218:219]
	v_mov_b64_e32 v[82:83], v[220:221]
	v_mov_b64_e32 v[118:119], v[222:223]
	v_mov_b64_e32 v[120:121], v[224:225]
	v_mov_b64_e32 v[50:51], v[226:227]
	v_mov_b64_e32 v[52:53], v[228:229]
	v_mov_b64_e32 v[76:77], v[230:231]
	v_mov_b64_e32 v[78:79], v[232:233]
	v_and_b32_e32 v84, 0xffff0000, v45
	v_and_b32_e32 v62, 0xffff0000, v41
	v_lshlrev_b32_e32 v45, 16, v45
	v_lshlrev_b32_e32 v41, 16, v41
	v_and_b32_e32 v92, 0xffff0000, v43
	v_and_b32_e32 v90, 0xffff0000, v39
	v_lshlrev_b32_e32 v43, 16, v43
	v_lshlrev_b32_e32 v39, 16, v39
	s_mov_b32 s10, s66
	s_mov_b32 s11, s67
	v_mov_b32_e32 v96, v75
	v_mov_b32_e32 v94, v74
	v_mov_b32_e32 v114, v57
	v_mov_b32_e32 v115, v121
	v_pk_mul_f32 v[116:117], v[114:115], v[112:113]
	v_fma_f32 v57, v79, v84, v117
	v_add_f32_e32 v57, v116, v57
	v_mul_f32_e32 v62, v57, v62
	v_mov_b32_e32 v57, v120
	v_pk_mul_f32 v[116:117], v[56:57], v[110:111]
	s_nop 0
	v_fma_f32 v45, v78, v45, v117
	v_add_f32_e32 v45, v116, v45
	v_mov_b32_e32 v116, v55
	v_mov_b32_e32 v117, v119
	v_mul_f32_e32 v84, v45, v41
	v_and_b32_e32 v45, 0xffff0000, v44
	v_pk_mul_f32 v[120:121], v[116:117], v[108:109]
	v_and_b32_e32 v41, 0xffff0000, v40
	v_fma_f32 v45, v77, v45, v121
	v_add_f32_e32 v45, v120, v45
	v_mov_b32_e32 v55, v118
	v_mul_f32_e32 v86, v45, v41
	v_lshlrev_b32_e32 v45, 16, v40
	v_lshlrev_b32_e32 v44, 16, v44
	v_pk_mul_f32 v[40:41], v[54:55], v[106:107]
	s_nop 0
	v_fma_f32 v41, v76, v44, v41
	v_add_f32_e32 v40, v40, v41
	v_mul_f32_e32 v88, v40, v45
	v_mov_b32_e32 v40, v49
	v_mov_b32_e32 v41, v83
	v_pk_mul_f32 v[44:45], v[40:41], v[104:105]
	v_mov_b32_e32 v49, v82
	v_fma_f32 v45, v53, v92, v45
	v_add_f32_e32 v44, v44, v45
	v_mul_f32_e32 v90, v44, v90
	v_pk_mul_f32 v[44:45], v[48:49], v[102:103]
	v_and_b32_e32 v92, 0xffff0000, v42
	v_fma_f32 v43, v52, v43, v45
	v_add_f32_e32 v43, v44, v43
	v_mov_b32_e32 v44, v47
	v_mov_b32_e32 v45, v81
	v_pk_mul_f32 v[82:83], v[44:45], v[100:101]
	v_mul_f32_e32 v43, v43, v39
	v_fma_f32 v47, v51, v92, v83
	v_and_b32_e32 v39, 0xffff0000, v38
	v_add_f32_e32 v47, v82, v47
	v_mul_f32_e32 v81, v47, v39
	v_mov_b32_e32 v47, v80
	v_lshlrev_b32_e32 v82, 16, v38
	v_lshlrev_b32_e32 v42, 16, v42
	v_pk_mul_f32 v[38:39], v[46:47], v[98:99]
	v_mov_b32_e32 v92, v73
	v_fma_f32 v39, v50, v42, v39
	v_add_f32_e32 v38, v38, v39
	v_mul_f32_e32 v38, v38, v82
	v_cvt_pk_bf16_f32 v80, v38, v81
	v_cvt_pk_bf16_f32 v81, v43, v90
	v_cvt_pk_bf16_f32 v82, v88, v86
	v_cvt_pk_bf16_f32 v83, v84, v62
	buffer_store_dwordx4 v[80:83], v148, s[8:11], 0 offen offset:768 sc1
	v_and_b32_e32 v42, 0xffff0000, v35
	v_lshlrev_b32_e32 v43, 16, v35
	v_and_b32_e32 v62, 0xffff0000, v34
	v_lshlrev_b32_e32 v80, 16, v34
	v_pk_mov_b32 v[34:35], v[96:97], v[112:113] op_sel:[1,0]
	v_and_b32_e32 v38, 0xffff0000, v37
	v_pk_mul_f32 v[34:35], v[114:115], v[34:35]
	v_and_b32_e32 v81, 0xffff0000, v33
	v_fma_f32 v35, v79, v113, v35
	v_add_f32_e32 v34, v34, v35
	v_mul_f32_e32 v38, v34, v38
	v_pk_mul_f32 v[34:35], v[114:115], v[96:97]
	v_lshlrev_b32_e32 v37, 16, v37
	v_fma_f32 v35, v79, v112, v35
	v_add_f32_e32 v34, v34, v35
	v_mul_f32_e32 v81, v34, v81
	v_pk_mov_b32 v[34:35], v[94:95], v[110:111] op_sel:[1,0]
	v_lshlrev_b32_e32 v33, 16, v33
	v_pk_mul_f32 v[34:35], v[56:57], v[34:35]
	v_and_b32_e32 v39, 0xffff0000, v36
	v_fma_f32 v35, v78, v111, v35
	v_add_f32_e32 v34, v34, v35
	v_mul_f32_e32 v37, v34, v37
	v_pk_mul_f32 v[34:35], v[56:57], v[94:95]
	v_mov_b32_e32 v90, v72
	v_fma_f32 v35, v78, v110, v35
	v_add_f32_e32 v34, v34, v35
	v_mul_f32_e32 v82, v34, v33
	v_pk_mov_b32 v[34:35], v[92:93], v[108:109] op_sel:[1,0]
	v_and_b32_e32 v33, 0xffff0000, v32
	v_pk_mul_f32 v[34:35], v[116:117], v[34:35]
	v_lshlrev_b32_e32 v36, 16, v36
	v_fma_f32 v35, v77, v109, v35
	v_add_f32_e32 v34, v34, v35
	v_mul_f32_e32 v39, v34, v39
	v_pk_mul_f32 v[34:35], v[116:117], v[92:93]
	v_mov_b32_e32 v88, v71
	v_fma_f32 v35, v77, v108, v35
	v_add_f32_e32 v34, v34, v35
	v_mul_f32_e32 v34, v34, v33
	v_lshlrev_b32_e32 v35, 16, v32
	v_pk_mov_b32 v[32:33], v[90:91], v[106:107] op_sel:[1,0]
	v_and_b32_e32 v83, 0xffff0000, v31
	v_pk_mul_f32 v[32:33], v[54:55], v[32:33]
	v_mov_b32_e32 v86, v70
	v_fma_f32 v33, v76, v107, v33
	v_add_f32_e32 v32, v32, v33
	v_mul_f32_e32 v36, v32, v36
	v_pk_mul_f32 v[32:33], v[54:55], v[90:91]
	v_lshlrev_b32_e32 v31, 16, v31
	v_fma_f32 v33, v76, v106, v33
	v_add_f32_e32 v32, v32, v33
	v_mul_f32_e32 v35, v32, v35
	v_pk_mov_b32 v[32:33], v[88:89], v[104:105] op_sel:[1,0]
	v_mov_b32_e32 v84, v69
	v_pk_mul_f32 v[32:33], v[40:41], v[32:33]
	v_lshlrev_b32_e32 v90, 16, v30
	v_fma_f32 v33, v53, v105, v33
	v_add_f32_e32 v32, v32, v33
	v_mul_f32_e32 v42, v32, v42
	v_pk_mul_f32 v[32:33], v[40:41], v[88:89]
	s_nop 0
	v_fma_f32 v33, v53, v104, v33
	v_add_f32_e32 v32, v32, v33
	v_mul_f32_e32 v83, v32, v83
	v_pk_mov_b32 v[32:33], v[86:87], v[102:103] op_sel:[1,0]
	s_nop 0
	v_pk_mul_f32 v[32:33], v[48:49], v[32:33]
	s_nop 0
	v_fma_f32 v33, v52, v103, v33
	v_add_f32_e32 v32, v32, v33
	v_mul_f32_e32 v43, v32, v43
	v_pk_mul_f32 v[32:33], v[48:49], v[86:87]
	s_nop 0
	v_fma_f32 v33, v52, v102, v33
	v_add_f32_e32 v32, v32, v33
	v_mul_f32_e32 v86, v32, v31
	v_pk_mov_b32 v[32:33], v[84:85], v[100:101] op_sel:[1,0]
	v_and_b32_e32 v31, 0xffff0000, v30
	v_pk_mul_f32 v[32:33], v[44:45], v[32:33]
	s_nop 0
	v_fma_f32 v33, v51, v101, v33
	v_add_f32_e32 v32, v32, v33
	v_mul_f32_e32 v88, v32, v62
	v_pk_mul_f32 v[32:33], v[44:45], v[84:85]
	v_mov_b32_e32 v62, v68
	v_fma_f32 v33, v51, v100, v33
	v_add_f32_e32 v32, v32, v33
	v_mul_f32_e32 v84, v32, v31
	v_pk_mov_b32 v[30:31], v[62:63], v[98:99] op_sel:[1,0]
	s_nop 0
	v_pk_mul_f32 v[30:31], v[46:47], v[30:31]
	s_nop 0
	v_fma_f32 v31, v50, v99, v31
	v_add_f32_e32 v30, v30, v31
	v_mul_f32_e32 v30, v30, v80
	v_cvt_pk_bf16_f32 v30, v30, v88
	v_cvt_pk_bf16_f32 v31, v43, v42
	v_cvt_pk_bf16_f32 v32, v36, v39
	v_cvt_pk_bf16_f32 v33, v37, v38
	buffer_store_dwordx4 v[30:33], v148, s[8:11], 0 offen offset:2816 sc1
	s_nop 1
	v_pk_mul_f32 v[30:31], v[46:47], v[62:63]
	s_nop 0
	v_fma_f32 v31, v50, v98, v31
	v_add_f32_e32 v30, v30, v31
	v_mul_f32_e32 v30, v30, v90
	v_cvt_pk_bf16_f32 v30, v30, v84
	v_cvt_pk_bf16_f32 v31, v86, v83
	v_cvt_pk_bf16_f32 v32, v35, v34
	v_cvt_pk_bf16_f32 v33, v82, v81
	buffer_store_dwordx4 v[30:33], v123, s[8:11], 0 offen offset:768 sc1
	v_and_b32_e32 v34, 0xffff0000, v27
	v_lshlrev_b32_e32 v27, 16, v27
	v_mov_b32_e32 v30, v67
	v_mov_b32_e32 v31, v75
	v_pk_mul_f32 v[30:31], v[114:115], v[30:31]
	v_and_b32_e32 v32, 0xffff0000, v29
	v_fma_f32 v31, v79, v97, v31
	v_add_f32_e32 v30, v30, v31
	v_mul_f32_e32 v32, v30, v32
	v_mov_b32_e32 v30, v66
	v_mov_b32_e32 v31, v74
	v_pk_mul_f32 v[30:31], v[56:57], v[30:31]
	v_lshlrev_b32_e32 v29, 16, v29
	v_fma_f32 v31, v78, v95, v31
	v_add_f32_e32 v30, v30, v31
	v_mul_f32_e32 v33, v30, v29
	v_mov_b32_e32 v30, v65
	v_mov_b32_e32 v31, v73
	v_pk_mul_f32 v[30:31], v[116:117], v[30:31]
	v_and_b32_e32 v29, 0xffff0000, v28
	v_fma_f32 v31, v77, v93, v31
	v_add_f32_e32 v30, v30, v31
	v_mul_f32_e32 v30, v30, v29
	v_lshlrev_b32_e32 v31, 16, v28
	v_mov_b32_e32 v28, v64
	v_mov_b32_e32 v29, v72
	v_pk_mul_f32 v[28:29], v[54:55], v[28:29]
	s_nop 0
	v_fma_f32 v29, v76, v91, v29
	v_add_f32_e32 v28, v28, v29
	v_mul_f32_e32 v31, v28, v31
	v_mov_b32_e32 v28, v61
	v_mov_b32_e32 v29, v71
	v_pk_mul_f32 v[28:29], v[40:41], v[28:29]
	s_nop 0
	v_fma_f32 v29, v53, v89, v29
	v_add_f32_e32 v28, v28, v29
	v_mul_f32_e32 v34, v28, v34
	v_mov_b32_e32 v28, v60
	v_mov_b32_e32 v29, v70
	v_pk_mul_f32 v[28:29], v[48:49], v[28:29]
	s_nop 0
	v_fma_f32 v29, v52, v87, v29
	v_add_f32_e32 v28, v28, v29
	v_mul_f32_e32 v35, v28, v27
	v_mov_b32_e32 v28, v59
	v_mov_b32_e32 v29, v69
	v_pk_mul_f32 v[28:29], v[44:45], v[28:29]
	v_and_b32_e32 v27, 0xffff0000, v26
	v_fma_f32 v29, v51, v85, v29
	v_add_f32_e32 v28, v28, v29
	v_mul_f32_e32 v28, v28, v27
	v_lshlrev_b32_e32 v29, 16, v26
	v_mov_b32_e32 v26, v58
	v_mov_b32_e32 v27, v68
	v_pk_mul_f32 v[26:27], v[46:47], v[26:27]
	s_nop 0
	v_fma_f32 v27, v50, v63, v27
	v_add_f32_e32 v26, v26, v27
	v_mul_f32_e32 v26, v26, v29
	v_cvt_pk_bf16_f32 v26, v26, v28
	v_cvt_pk_bf16_f32 v27, v35, v34
	v_cvt_pk_bf16_f32 v28, v31, v30
	v_cvt_pk_bf16_f32 v29, v33, v32
	buffer_store_dwordx4 v[26:29], v123, s[8:11], 0 offen offset:2816 sc1

.LBB0_849:
	v_mov_b32_e32 v43, v0
	s_ashr_i32 s5, s3, 31
	v_ashrrev_i32_e32 v44, 7, v43
	s_waitcnt vmcnt(7)
	v_add_u32_e32 v130, s2, v44
	v_ashrrev_i32_e32 v131, 31, v130
	v_and_b32_e32 v134, 31, v43
	s_waitcnt vmcnt(0)
	v_lshlrev_b64 v[2:3], 15, v[130:131]
	v_bfe_u32 v135, v43, 5, 1
	v_lshl_add_u64 v[2:3], s[56:57], 0, v[2:3]
	v_lshlrev_b32_e32 v154, 8, v134
	v_lshl_add_u64 v[2:3], v[2:3], 0, v[154:155]
	v_lshlrev_b32_e32 v154, 4, v135
	v_lshl_add_u64 v[18:19], v[2:3], 0, v[154:155]
	v_add_co_u32_e32 v20, vcc, s14, v18
	v_ashrrev_i32_e32 v45, 2, v43
	s_nop 0
	v_addc_co_u32_e32 v21, vcc, 0, v19, vcc
	v_add_co_u32_e32 v22, vcc, s17, v18
	global_load_dwordx4 v[2:5], v[18:19], off
	global_load_dwordx4 v[6:9], v[20:21], off
	v_addc_co_u32_e32 v23, vcc, 0, v19, vcc
	v_add_co_u32_e32 v24, vcc, s30, v18
	global_load_dwordx4 v[10:13], v[22:23], off
	s_nop 0
	v_addc_co_u32_e32 v25, vcc, 0, v19, vcc
	global_load_dwordx4 v[14:17], v[24:25], off
	global_load_dwordx4 v[114:117], v[18:19], off offset:32
	global_load_dwordx4 v[118:121], v[20:21], off offset:32
	global_load_dwordx4 v[122:125], v[22:23], off offset:32
	global_load_dwordx4 v[126:129], v[24:25], off offset:32
	global_load_dwordx4 v[102:105], v[20:21], off offset:64
	global_load_dwordx4 v[106:109], v[22:23], off offset:64
	global_load_dwordx4 v[110:113], v[24:25], off offset:64
	global_load_dwordx4 v[90:93], v[20:21], off offset:96
	global_load_dwordx4 v[94:97], v[22:23], off offset:96
	global_load_dwordx4 v[98:101], v[24:25], off offset:96
	global_load_dwordx4 v[82:85], v[22:23], off offset:128
	global_load_dwordx4 v[86:89], v[24:25], off offset:128
	global_load_dwordx4 v[74:77], v[22:23], off offset:160
	global_load_dwordx4 v[78:81], v[24:25], off offset:160
	global_load_dwordx4 v[70:73], v[24:25], off offset:192
	global_load_dwordx4 v[66:69], v[24:25], off offset:224
	v_add_u32_e32 v18, s3, v45
	v_ashrrev_i32_e32 v19, 31, v18
	v_lshlrev_b32_e32 v20, 6, v43
	v_lshlrev_b64 v[18:19], 12, v[18:19]
	v_and_b32_e32 v46, 0xc0, v20
	v_lshl_add_u64 v[18:19], s[60:61], 0, v[18:19]
	v_lshlrev_b32_e32 v20, 1, v46
	v_mov_b32_e32 v21, v155
	v_lshl_add_u64 v[34:35], v[18:19], 0, v[20:21]
	global_load_dwordx4 v[18:21], v[34:35], off offset:3632
	global_load_dwordx4 v[22:25], v[34:35], off offset:3616
	global_load_dwordx4 v[26:29], v[34:35], off offset:3600
	global_load_dwordx4 v[30:33], v[34:35], off offset:3584
	global_load_dwordx4 v[36:39], v[34:35], off offset:3680
	global_load_dwordx4 v[176:179], v[34:35], off offset:3664
	global_load_dwordx4 v[48:51], v[34:35], off offset:3648
	global_load_dwordx4 v[182:185], v[34:35], off offset:3696
	v_lshrrev_b32_e32 v42, 5, v43
	s_add_i32 s4, s4, s46
	s_waitcnt vmcnt(7)
	v_lshlrev_b32_e32 v144, 16, v18
	s_waitcnt vmcnt(6)
	v_lshlrev_b32_e32 v150, 16, v22
	s_waitcnt vmcnt(5)
	v_lshlrev_b32_e32 v168, 16, v26
	s_waitcnt vmcnt(4)
	v_lshlrev_b32_e32 v174, 16, v30
	v_and_b32_e32 v173, 0xffff0000, v30
	v_add_f32_e32 v30, 0, v174
	v_lshlrev_b32_e32 v172, 16, v31
	v_add_f32_e32 v30, v30, v173
	v_and_b32_e32 v171, 0xffff0000, v31
	v_mul_f32_e32 v31, v173, v173
	v_add_f32_e32 v30, v30, v172
	v_lshlrev_b32_e32 v170, 16, v32
	v_fmac_f32_e32 v31, v174, v174
	v_add_f32_e32 v30, v30, v171
	v_and_b32_e32 v169, 0xffff0000, v32
	v_fmac_f32_e32 v31, v172, v172
	v_add_f32_e32 v30, v30, v170
	v_lshlrev_b32_e32 v167, 16, v33
	v_fmac_f32_e32 v31, v171, v171
	v_add_f32_e32 v30, v30, v169
	v_and_b32_e32 v165, 0xffff0000, v33
	v_fmac_f32_e32 v31, v170, v170
	v_add_f32_e32 v30, v30, v167
	v_fmac_f32_e32 v31, v169, v169
	v_add_f32_e32 v30, v30, v165
	v_fmac_f32_e32 v31, v167, v167
	v_and_b32_e32 v166, 0xffff0000, v26
	v_add_f32_e32 v26, v30, v168
	v_fmac_f32_e32 v31, v165, v165
	v_lshlrev_b32_e32 v164, 16, v27
	v_add_f32_e32 v26, v26, v166
	v_and_b32_e32 v153, 0xffff0000, v27
	v_fmac_f32_e32 v31, v168, v168
	v_add_f32_e32 v26, v26, v164
	v_lshlrev_b32_e32 v152, 16, v28
	v_fmac_f32_e32 v31, v166, v166
	v_add_f32_e32 v26, v26, v153
	v_and_b32_e32 v151, 0xffff0000, v28
	v_fmac_f32_e32 v31, v164, v164
	v_add_f32_e32 v26, v26, v152
	v_lshlrev_b32_e32 v148, 16, v29
	v_fmac_f32_e32 v31, v153, v153
	v_add_f32_e32 v26, v26, v151
	v_and_b32_e32 v146, 0xffff0000, v29
	v_fmac_f32_e32 v31, v152, v152
	v_add_f32_e32 v26, v26, v148
	v_fmac_f32_e32 v31, v151, v151
	v_add_f32_e32 v26, v26, v146
	v_fmac_f32_e32 v31, v148, v148
	v_and_b32_e32 v149, 0xffff0000, v22
	v_add_f32_e32 v22, v26, v150
	v_fmac_f32_e32 v31, v146, v146
	v_lshlrev_b32_e32 v147, 16, v23
	v_add_f32_e32 v22, v22, v149
	v_and_b32_e32 v145, 0xffff0000, v23
	v_fmac_f32_e32 v31, v150, v150
	v_add_f32_e32 v22, v22, v147
	v_lshlrev_b32_e32 v143, 16, v24
	v_fmac_f32_e32 v31, v149, v149
	v_add_f32_e32 v22, v22, v145
	v_and_b32_e32 v141, 0xffff0000, v24
	v_fmac_f32_e32 v31, v147, v147
	v_add_f32_e32 v22, v22, v143
	v_lshlrev_b32_e32 v139, 16, v25
	v_fmac_f32_e32 v31, v145, v145
	v_add_f32_e32 v22, v22, v141
	v_and_b32_e32 v137, 0xffff0000, v25
	v_fmac_f32_e32 v31, v143, v143
	v_add_f32_e32 v22, v22, v139
	v_fmac_f32_e32 v31, v141, v141
	v_add_f32_e32 v22, v22, v137
	v_fmac_f32_e32 v31, v139, v139
	v_and_b32_e32 v142, 0xffff0000, v18
	v_add_f32_e32 v18, v22, v144
	v_fmac_f32_e32 v31, v137, v137
	v_lshlrev_b32_e32 v140, 16, v19
	v_add_f32_e32 v18, v18, v142
	v_and_b32_e32 v138, 0xffff0000, v19
	v_fmac_f32_e32 v31, v144, v144
	v_add_f32_e32 v18, v18, v140
	v_lshlrev_b32_e32 v133, 16, v20
	v_fmac_f32_e32 v31, v142, v142
	v_add_f32_e32 v18, v18, v138
	v_and_b32_e32 v131, 0xffff0000, v20
	v_fmac_f32_e32 v31, v140, v140
	v_add_f32_e32 v18, v18, v133
	v_lshlrev_b32_e32 v64, 16, v21
	v_fmac_f32_e32 v31, v138, v138
	v_add_f32_e32 v18, v18, v131
	v_and_b32_e32 v62, 0xffff0000, v21
	v_fmac_f32_e32 v31, v133, v133
	v_add_f32_e32 v18, v18, v64
	v_fmac_f32_e32 v31, v131, v131
	v_add_f32_e32 v18, v18, v62
	s_waitcnt vmcnt(1)
	v_lshlrev_b32_e32 v136, 16, v48
	v_fmac_f32_e32 v31, v64, v64
	v_and_b32_e32 v132, 0xffff0000, v48
	v_add_f32_e32 v18, v18, v136
	v_fmac_f32_e32 v31, v62, v62
	v_lshlrev_b32_e32 v65, 16, v49
	v_add_f32_e32 v18, v18, v132
	v_and_b32_e32 v63, 0xffff0000, v49
	v_fmac_f32_e32 v31, v136, v136
	v_add_f32_e32 v18, v18, v65
	v_lshlrev_b32_e32 v60, 16, v50
	v_fmac_f32_e32 v31, v132, v132
	v_add_f32_e32 v18, v18, v63
	v_and_b32_e32 v59, 0xffff0000, v50
	v_fmac_f32_e32 v31, v65, v65
	v_add_f32_e32 v18, v18, v60
	v_lshlrev_b32_e32 v57, 16, v51
	v_fmac_f32_e32 v31, v63, v63
	v_add_f32_e32 v18, v18, v59
	v_and_b32_e32 v55, 0xffff0000, v51
	v_fmac_f32_e32 v31, v60, v60
	v_add_f32_e32 v18, v18, v57
	v_fmac_f32_e32 v31, v59, v59
	v_add_f32_e32 v18, v18, v55
	v_lshlrev_b32_e32 v61, 16, v176
	v_fmac_f32_e32 v31, v57, v57
	v_and_b32_e32 v58, 0xffff0000, v176
	v_add_f32_e32 v18, v18, v61
	v_fmac_f32_e32 v31, v55, v55
	v_lshlrev_b32_e32 v56, 16, v177
	v_add_f32_e32 v18, v18, v58
	v_and_b32_e32 v54, 0xffff0000, v177
	v_fmac_f32_e32 v31, v61, v61
	v_add_f32_e32 v18, v18, v56
	v_lshlrev_b32_e32 v53, 16, v178
	v_fmac_f32_e32 v31, v58, v58
	v_add_f32_e32 v18, v18, v54
	v_and_b32_e32 v51, 0xffff0000, v178
	v_fmac_f32_e32 v31, v56, v56
	v_add_f32_e32 v18, v18, v53
	v_lshlrev_b32_e32 v49, 16, v179
	v_fmac_f32_e32 v31, v54, v54
	v_add_f32_e32 v18, v18, v51
	v_and_b32_e32 v47, 0xffff0000, v179
	v_fmac_f32_e32 v31, v53, v53
	v_add_f32_e32 v18, v18, v49
	v_fmac_f32_e32 v31, v51, v51
	v_add_f32_e32 v18, v18, v47
	v_lshlrev_b32_e32 v52, 16, v36
	v_fmac_f32_e32 v31, v49, v49
	v_and_b32_e32 v50, 0xffff0000, v36
	v_add_f32_e32 v18, v18, v52
	v_fmac_f32_e32 v31, v47, v47
	v_lshlrev_b32_e32 v48, 16, v37
	v_add_f32_e32 v18, v18, v50
	v_fmac_f32_e32 v31, v52, v52
	v_add_f32_e32 v18, v18, v48
	v_and_b32_e32 v37, 0xffff0000, v37
	v_fmac_f32_e32 v31, v50, v50
	v_lshlrev_b32_e32 v34, 16, v38
	v_mov_b32_e32 v35, v37
	v_add_f32_e32 v20, v18, v37
	v_fmac_f32_e32 v31, v48, v48
	v_and_b32_e32 v24, 0xffff0000, v38
	v_pk_mul_f32 v[18:19], v[34:35], v[34:35]
	v_add_f32_e32 v20, v20, v34
	v_lshlrev_b32_e32 v25, 16, v39
	v_add_f32_e32 v19, v19, v31
	v_add_f32_e32 v20, v20, v24
	v_add_f32_e32 v21, v18, v19
	v_pk_mul_f32 v[18:19], v[24:25], v[24:25]
	v_add_f32_e32 v20, v20, v25
	v_and_b32_e32 v33, 0xffff0000, v39
	v_add_f32_e32 v18, v18, v21
	s_waitcnt vmcnt(0)
	v_lshlrev_b32_e32 v28, 16, v182
	v_mov_b32_e32 v29, v33
	v_add_f32_e32 v20, v20, v33
	v_add_f32_e32 v21, v19, v18
	v_and_b32_e32 v22, 0xffff0000, v182
	v_pk_mul_f32 v[18:19], v[28:29], v[28:29]
	v_add_f32_e32 v20, v20, v28
	v_lshlrev_b32_e32 v23, 16, v183
	v_add_f32_e32 v19, v19, v21
	v_add_f32_e32 v20, v20, v22
	v_add_f32_e32 v21, v18, v19
	v_pk_mul_f32 v[18:19], v[22:23], v[22:23]
	v_add_f32_e32 v29, v20, v23
	v_and_b32_e32 v31, 0xffff0000, v183
	v_add_f32_e32 v18, v18, v21
	v_lshlrev_b32_e32 v26, 16, v184
	v_mov_b32_e32 v27, v31
	v_add_f32_e32 v29, v29, v31
	v_and_b32_e32 v36, s0, v38
	v_add_f32_e32 v18, v19, v18
	v_and_b32_e32 v20, 0xffff0000, v184
	v_pk_mul_f32 v[38:39], v[26:27], v[26:27]
	v_add_f32_e32 v27, v29, v26
	v_lshlrev_b32_e32 v21, 16, v185
	v_add_f32_e32 v18, v39, v18
	v_add_f32_e32 v27, v27, v20
	v_and_b32_e32 v29, 64, v181
	v_add_f32_e32 v18, v38, v18
	v_pk_mul_f32 v[40:41], v[20:21], v[20:21]
	v_add_f32_e32 v39, v27, v21
	v_xor_b32_e32 v27, 1, v181
	v_add_u32_e32 v29, 64, v29
	v_and_b32_e32 v19, 0xffff0000, v185
	v_add_f32_e32 v18, v40, v18
	v_cmp_lt_i32_e32 vcc, v27, v29
	v_add_f32_e32 v18, v41, v18
	v_mul_f32_e32 v38, v19, v19
	v_cndmask_b32_e32 v27, v181, v27, vcc
	v_lshlrev_b32_e32 v27, 2, v27
	v_pk_add_f32 v[38:39], v[38:39], v[18:19]
	ds_bpermute_b32 v41, v27, v39
	ds_bpermute_b32 v40, v27, v38
	v_xor_b32_e32 v35, 2, v181
	v_cmp_lt_i32_e32 vcc, v35, v29
	v_and_b32_e32 v30, s0, v182
	v_mov_b32_e32 v32, v36
	v_cndmask_b32_e32 v29, v181, v35, vcc
	v_lshlrev_b32_e32 v29, 2, v29
	s_waitcnt lgkmcnt(0)
	v_pk_add_f32 v[38:39], v[38:39], v[40:41]
	ds_bpermute_b32 v41, v29, v39
	ds_bpermute_b32 v40, v29, v38
	s_waitcnt lgkmcnt(0)
	v_pk_add_f32 v[40:41], v[38:39], v[40:41]
	s_nop 0
	v_pk_mul_f32 v[38:39], v[40:41], s[22:23] op_sel_hi:[1,0]
	v_pk_fma_f32 v[36:37], v[40:41], s[22:23], v[36:37] op_sel_hi:[1,0,1] neg_lo:[1,0,0] neg_hi:[1,0,0]
	v_fma_f32 v18, -v39, v39, v38
	v_max_f32_e32 v18, 0, v18
	v_add_f32_e32 v18, 0x358637bd, v18
	v_cmp_gt_f32_e32 vcc, s33, v18
	v_mul_f32_e32 v27, 0x4b800000, v18
	v_sub_f32_e32 v29, v174, v39
	v_cndmask_b32_e32 v18, v18, v27, vcc
	v_rsq_f32_e32 v18, v18
	v_sub_f32_e32 v19, v19, v39
	v_mul_f32_e32 v27, 0x45800000, v18
	v_cndmask_b32_e32 v18, v18, v27, vcc
	v_mul_f32_e32 v29, v29, v18
	v_lshlrev_b32_e32 v27, 1, v45
	v_bfe_u32 v35, v29, 16, 1
	v_ashrrev_i32_e32 v45, 1, v43
	v_and_b32_e32 v27, 14, v27
	v_add3_u32 v29, v29, v35, s15
	v_lshl_add_u32 v35, v46, 8, 32
	v_and_b32_e32 v46, -16, v45
	v_add3_u32 v174, v35, v46, v27
	ds_write_b16_d16_hi v174, v29 offset:55296
	v_sub_f32_e32 v29, v173, v39
	v_mul_f32_e32 v29, v29, v18
	v_bfe_u32 v173, v29, 16, 1
	v_add3_u32 v29, v29, v173, s15
	v_bitop3_b32 v173, v45, 16, -16 bitop3:0x6c
	v_add3_u32 v175, v35, v173, v27
	ds_write_b16_d16_hi v175, v29 offset:55552
	v_sub_f32_e32 v29, v172, v39
	v_mul_f32_e32 v29, v29, v18
	v_bfe_u32 v172, v29, 16, 1
	v_add3_u32 v29, v29, v172, s15
	v_bitop3_b32 v172, v45, 32, -16 bitop3:0x6c
	v_add3_u32 v176, v35, v172, v27
	ds_write_b16_d16_hi v176, v29 offset:55808
	v_sub_f32_e32 v29, v171, v39
	v_mul_f32_e32 v29, v29, v18
	v_bfe_u32 v171, v29, 16, 1
	v_add3_u32 v29, v29, v171, s15
	v_bitop3_b32 v171, v45, 48, -16 bitop3:0x6c
	v_add3_u32 v177, v35, v171, v27
	ds_write_b16_d16_hi v177, v29 offset:56064
	v_sub_f32_e32 v29, v170, v39
	v_mul_f32_e32 v29, v29, v18
	v_bfe_u32 v170, v29, 16, 1
	v_add3_u32 v29, v29, v170, s15
	v_bitop3_b32 v170, v45, 64, -16 bitop3:0x6c
	v_add3_u32 v178, v35, v170, v27
	ds_write_b16_d16_hi v178, v29 offset:56320
	v_sub_f32_e32 v29, v169, v39
	v_mul_f32_e32 v29, v29, v18
	v_bfe_u32 v169, v29, 16, 1
	v_add3_u32 v29, v29, v169, s15
	v_bitop3_b32 v169, v45, s34, -16 bitop3:0x6c
	v_add3_u32 v179, v35, v169, v27
	ds_write_b16_d16_hi v179, v29 offset:56576
	v_sub_f32_e32 v29, v167, v39
	v_mul_f32_e32 v29, v29, v18
	v_bfe_u32 v167, v29, 16, 1
	v_add3_u32 v29, v29, v167, s15
	v_bitop3_b32 v167, v45, s31, -16 bitop3:0x6c
	v_add3_u32 v182, v35, v167, v27
	ds_write_b16_d16_hi v182, v29 offset:56832
	v_sub_f32_e32 v29, v165, v39
	v_mul_f32_e32 v29, v29, v18
	v_bfe_u32 v165, v29, 16, 1
	v_add3_u32 v29, v29, v165, s15
	v_bitop3_b32 v165, v45, s13, -16 bitop3:0x6c
	v_add3_u32 v183, v35, v165, v27
	ds_write_b16_d16_hi v183, v29 offset:57088
	v_sub_f32_e32 v29, v168, v39
	v_mul_f32_e32 v29, v29, v18
	v_bfe_u32 v168, v29, 16, 1
	v_add3_u32 v29, v29, v168, s15
	v_bitop3_b32 v168, v45, s12, -16 bitop3:0x6c
	v_add3_u32 v184, v35, v168, v27
	ds_write_b16_d16_hi v184, v29 offset:57344
	v_sub_f32_e32 v29, v166, v39
	v_mul_f32_e32 v29, v29, v18
	v_bfe_u32 v166, v29, 16, 1
	v_add3_u32 v29, v29, v166, s15
	v_bitop3_b32 v166, v45, s35, -16 bitop3:0x6c
	v_add3_u32 v185, v35, v166, v27
	ds_write_b16_d16_hi v185, v29 offset:57600
	v_sub_f32_e32 v29, v164, v39
	v_mul_f32_e32 v29, v29, v18
	v_bfe_u32 v164, v29, 16, 1
	v_add3_u32 v29, v29, v164, s15
	v_bitop3_b32 v164, v45, s38, -16 bitop3:0x6c
	v_add3_u32 v186, v35, v164, v27
	ds_write_b16_d16_hi v186, v29 offset:57856
	v_sub_f32_e32 v29, v153, v39
	v_mul_f32_e32 v29, v29, v18
	v_bfe_u32 v153, v29, 16, 1
	v_add3_u32 v29, v29, v153, s15
	v_bitop3_b32 v153, v45, s39, -16 bitop3:0x6c
	v_add3_u32 v187, v35, v153, v27
	ds_write_b16_d16_hi v187, v29 offset:58112
	v_sub_f32_e32 v29, v152, v39
	v_mul_f32_e32 v29, v29, v18
	v_bfe_u32 v152, v29, 16, 1
	v_add3_u32 v29, v29, v152, s15
	v_bitop3_b32 v152, v45, s16, -16 bitop3:0x6c
	v_add3_u32 v188, v35, v152, v27
	ds_write_b16_d16_hi v188, v29 offset:58368
	v_sub_f32_e32 v29, v151, v39
	v_mul_f32_e32 v29, v29, v18
	v_bfe_u32 v151, v29, 16, 1
	v_add3_u32 v29, v29, v151, s15
	v_bitop3_b32 v151, v45, s40, -16 bitop3:0x6c
	v_add3_u32 v189, v35, v151, v27
	ds_write_b16_d16_hi v189, v29 offset:58624
	v_sub_f32_e32 v29, v148, v39
	v_mul_f32_e32 v29, v29, v18
	v_bfe_u32 v148, v29, 16, 1
	v_add3_u32 v29, v29, v148, s15
	v_bitop3_b32 v148, v45, s41, -16 bitop3:0x6c
	v_add3_u32 v190, v35, v148, v27
	ds_write_b16_d16_hi v190, v29 offset:58880
	v_sub_f32_e32 v29, v146, v39
	v_mul_f32_e32 v29, v29, v18
	v_bfe_u32 v146, v29, 16, 1
	v_bitop3_b32 v45, v45, s42, -16 bitop3:0x6c
	v_add_u32_e32 v38, 0xd800, v35
	v_add3_u32 v29, v29, v146, s15
	v_add3_u32 v35, v35, v45, v27
	ds_write_b16_d16_hi v35, v29 offset:59136
	v_sub_f32_e32 v29, v150, v39
	v_mul_f32_e32 v29, v29, v18
	v_bfe_u32 v146, v29, 16, 1
	v_add3_u32 v29, v29, v146, s15
	ds_write_b16_d16_hi v174, v29 offset:59392
	v_sub_f32_e32 v29, v149, v39
	v_mul_f32_e32 v29, v29, v18
	v_bfe_u32 v146, v29, 16, 1
	v_add3_u32 v29, v29, v146, s15
	ds_write_b16_d16_hi v175, v29 offset:59648
	v_sub_f32_e32 v29, v147, v39
	v_mul_f32_e32 v29, v29, v18
	v_bfe_u32 v146, v29, 16, 1
	v_add3_u32 v29, v29, v146, s15
	ds_write_b16_d16_hi v176, v29 offset:59904
	v_sub_f32_e32 v29, v145, v39
	v_mul_f32_e32 v29, v29, v18
	v_bfe_u32 v145, v29, 16, 1
	v_add3_u32 v29, v29, v145, s15
	ds_write_b16_d16_hi v177, v29 offset:60160
	v_sub_f32_e32 v29, v143, v39
	v_mul_f32_e32 v29, v29, v18
	v_bfe_u32 v143, v29, 16, 1
	v_add3_u32 v29, v29, v143, s15
	ds_write_b16_d16_hi v178, v29 offset:60416
	v_sub_f32_e32 v29, v141, v39
	v_mul_f32_e32 v29, v29, v18
	v_bfe_u32 v141, v29, 16, 1
	v_add3_u32 v29, v29, v141, s15
	ds_write_b16_d16_hi v179, v29 offset:60672
	v_sub_f32_e32 v29, v139, v39
	v_mul_f32_e32 v29, v29, v18
	v_bfe_u32 v139, v29, 16, 1
	v_add3_u32 v29, v29, v139, s15
	ds_write_b16_d16_hi v182, v29 offset:60928
	v_sub_f32_e32 v29, v137, v39
	v_mul_f32_e32 v29, v29, v18
	v_bfe_u32 v137, v29, 16, 1
	v_add3_u32 v29, v29, v137, s15
	ds_write_b16_d16_hi v183, v29 offset:61184
	v_sub_f32_e32 v29, v144, v39
	v_mul_f32_e32 v29, v29, v18
	v_bfe_u32 v137, v29, 16, 1
	v_add3_u32 v29, v29, v137, s15
	ds_write_b16_d16_hi v184, v29 offset:61440
	v_sub_f32_e32 v29, v142, v39
	v_mul_f32_e32 v29, v29, v18
	v_bfe_u32 v137, v29, 16, 1
	v_add3_u32 v29, v29, v137, s15
	ds_write_b16_d16_hi v185, v29 offset:61696
	v_sub_f32_e32 v29, v140, v39
	v_mul_f32_e32 v29, v29, v18
	v_bfe_u32 v137, v29, 16, 1
	v_add3_u32 v29, v29, v137, s15
	ds_write_b16_d16_hi v186, v29 offset:61952
	v_sub_f32_e32 v29, v138, v39
	v_mul_f32_e32 v29, v29, v18
	v_bfe_u32 v137, v29, 16, 1
	v_add3_u32 v29, v29, v137, s15
	ds_write_b16_d16_hi v187, v29 offset:62208
	v_sub_f32_e32 v29, v133, v39
	v_mul_f32_e32 v29, v29, v18
	v_bfe_u32 v133, v29, 16, 1
	v_add3_u32 v29, v29, v133, s15
	ds_write_b16_d16_hi v188, v29 offset:62464
	v_sub_f32_e32 v29, v131, v39
	v_mul_f32_e32 v29, v29, v18
	v_bfe_u32 v131, v29, 16, 1
	v_add3_u32 v29, v29, v131, s15
	ds_write_b16_d16_hi v189, v29 offset:62720
	v_sub_f32_e32 v29, v64, v39
	v_mul_f32_e32 v29, v29, v18
	v_bfe_u32 v64, v29, 16, 1
	v_add3_u32 v29, v29, v64, s15
	ds_write_b16_d16_hi v190, v29 offset:62976
	v_sub_f32_e32 v29, v62, v39
	v_mul_f32_e32 v29, v29, v18
	v_bfe_u32 v62, v29, 16, 1
	v_add3_u32 v29, v29, v62, s15
	ds_write_b16_d16_hi v35, v29 offset:63232
	v_sub_f32_e32 v29, v136, v39
	v_mul_f32_e32 v29, v29, v18
	v_bfe_u32 v35, v29, 16, 1
	v_add3_u32 v29, v29, v35, s15
	ds_write_b16_d16_hi v174, v29 offset:63488
	v_sub_f32_e32 v29, v132, v39
	v_mul_f32_e32 v29, v29, v18
	v_bfe_u32 v35, v29, 16, 1
	v_add3_u32 v29, v29, v35, s15
	ds_write_b16_d16_hi v175, v29 offset:63744
	v_sub_f32_e32 v29, v65, v39
	v_mul_f32_e32 v29, v29, v18
	v_bfe_u32 v35, v29, 16, 1
	v_add3_u32 v29, v29, v35, s15
	ds_write_b16_d16_hi v176, v29 offset:64000
	v_sub_f32_e32 v29, v63, v39
	v_mul_f32_e32 v29, v29, v18
	v_bfe_u32 v35, v29, 16, 1
	v_add3_u32 v29, v29, v35, s15
	ds_write_b16_d16_hi v177, v29 offset:64256
	v_sub_f32_e32 v29, v60, v39
	v_mul_f32_e32 v29, v29, v18
	v_bfe_u32 v35, v29, 16, 1
	v_add3_u32 v29, v29, v35, s15
	ds_write_b16_d16_hi v178, v29 offset:64512
	v_sub_f32_e32 v29, v59, v39
	v_mul_f32_e32 v29, v29, v18
	v_bfe_u32 v35, v29, 16, 1
	v_add3_u32 v29, v29, v35, s15
	ds_write_b16_d16_hi v179, v29 offset:64768
	v_sub_f32_e32 v29, v57, v39
	v_mul_f32_e32 v29, v29, v18
	v_bfe_u32 v35, v29, 16, 1
	v_add3_u32 v29, v29, v35, s15
	ds_write_b16_d16_hi v182, v29 offset:65024
	v_sub_f32_e32 v29, v55, v39
	v_mul_f32_e32 v29, v29, v18
	v_bfe_u32 v35, v29, 16, 1
	v_add3_u32 v29, v29, v35, s15
	ds_write_b16_d16_hi v183, v29 offset:65280
	v_sub_f32_e32 v29, v61, v39
	v_mul_f32_e32 v29, v29, v18
	v_bfe_u32 v35, v29, 16, 1
	v_add3_u32 v29, v29, v35, s15
	v_add3_u32 v35, v38, v168, v27
	ds_write_b16_d16_hi v35, v29 offset:10240
	v_sub_f32_e32 v29, v58, v39
	v_mul_f32_e32 v29, v29, v18
	v_bfe_u32 v55, v29, 16, 1
	v_add3_u32 v29, v29, v55, s15
	v_add3_u32 v55, v38, v166, v27
	ds_write_b16_d16_hi v55, v29 offset:10496
	v_sub_f32_e32 v29, v56, v39
	v_mul_f32_e32 v29, v29, v18
	v_bfe_u32 v56, v29, 16, 1
	v_add3_u32 v29, v29, v56, s15
	v_add3_u32 v56, v38, v164, v27
	ds_write_b16_d16_hi v56, v29 offset:10752
	v_sub_f32_e32 v29, v54, v39
	v_mul_f32_e32 v29, v29, v18
	v_bfe_u32 v54, v29, 16, 1
	v_add3_u32 v29, v29, v54, s15
	v_add3_u32 v54, v38, v153, v27
	ds_write_b16_d16_hi v54, v29 offset:11008
	v_sub_f32_e32 v29, v53, v39
	v_mul_f32_e32 v29, v29, v18
	v_bfe_u32 v53, v29, 16, 1
	v_add3_u32 v29, v29, v53, s15
	v_add3_u32 v53, v38, v152, v27
	ds_write_b16_d16_hi v53, v29 offset:11264
	v_sub_f32_e32 v29, v51, v39
	v_mul_f32_e32 v29, v29, v18
	v_bfe_u32 v51, v29, 16, 1
	v_add3_u32 v29, v29, v51, s15
	v_add3_u32 v51, v38, v151, v27
	ds_write_b16_d16_hi v51, v29 offset:11520
	v_sub_f32_e32 v29, v49, v39
	v_mul_f32_e32 v29, v29, v18
	v_bfe_u32 v49, v29, 16, 1
	v_add3_u32 v29, v29, v49, s15
	v_add3_u32 v49, v38, v148, v27
	ds_write_b16_d16_hi v49, v29 offset:11776
	v_sub_f32_e32 v29, v47, v39
	v_mul_f32_e32 v29, v29, v18
	v_bfe_u32 v47, v29, 16, 1
	v_add3_u32 v29, v29, v47, s15
	v_add3_u32 v45, v38, v45, v27
	ds_write_b16_d16_hi v45, v29 offset:12032
	v_sub_f32_e32 v29, v52, v39
	v_mul_f32_e32 v29, v29, v18
	v_bfe_u32 v47, v29, 16, 1
	v_add3_u32 v29, v29, v47, s15
	v_add3_u32 v46, v38, v46, v27
	ds_write_b16_d16_hi v46, v29 offset:12288
	v_sub_f32_e32 v29, v50, v39
	v_mul_f32_e32 v29, v29, v18
	v_bfe_u32 v46, v29, 16, 1
	v_add3_u32 v29, v29, v46, s15
	v_add3_u32 v46, v38, v173, v27
	ds_write_b16_d16_hi v46, v29 offset:12544
	v_sub_f32_e32 v29, v48, v39
	v_mul_f32_e32 v29, v29, v18
	v_bfe_u32 v46, v29, 16, 1
	v_add3_u32 v29, v29, v46, s15
	v_add3_u32 v46, v38, v172, v27
	ds_write_b16_d16_hi v46, v29 offset:12800
	v_mul_f32_e32 v29, v37, v18
	v_bfe_u32 v36, v29, 16, 1
	v_add3_u32 v29, v29, v36, s15
	v_add3_u32 v36, v38, v171, v27
	ds_write_b16_d16_hi v36, v29 offset:13056
	v_sub_f32_e32 v29, v34, v39
	v_mul_f32_e32 v29, v29, v18
	v_bfe_u32 v34, v29, 16, 1
	v_add3_u32 v29, v29, v34, s15
	v_add3_u32 v34, v38, v170, v27
	ds_write_b16_d16_hi v34, v29 offset:13312
	v_sub_f32_e32 v29, v24, v39
	v_pk_fma_f32 v[24:25], v[40:41], s[22:23], v[24:25] op_sel_hi:[1,0,1] neg_lo:[1,0,0] neg_hi:[1,0,0]
	v_mul_f32_e32 v29, v29, v18
	v_mul_f32_e32 v24, v25, v18
	v_bfe_u32 v34, v29, 16, 1
	v_bfe_u32 v25, v24, 16, 1
	v_add3_u32 v29, v29, v34, s15
	v_add3_u32 v34, v38, v169, v27
	v_add3_u32 v24, v24, v25, s15
	v_add3_u32 v25, v38, v167, v27
	ds_write_b16_d16_hi v34, v29 offset:13568
	ds_write_b16_d16_hi v25, v24 offset:13824
	v_pk_fma_f32 v[24:25], v[40:41], s[22:23], v[32:33] op_sel_hi:[1,0,1] neg_lo:[1,0,0] neg_hi:[1,0,0]
	v_and_b32_e32 v133, 15, v43
	v_mul_f32_e32 v24, v25, v18
	v_bfe_u32 v25, v24, 16, 1
	v_add3_u32 v24, v24, v25, s15
	v_add3_u32 v25, v38, v165, v27
	ds_write_b16_d16_hi v25, v24 offset:14080
	v_sub_f32_e32 v24, v28, v39
	v_mul_f32_e32 v24, v24, v18
	v_bfe_u32 v25, v24, 16, 1
	v_add3_u32 v24, v24, v25, s15
	ds_write_b16_d16_hi v35, v24 offset:14336
	v_sub_f32_e32 v24, v22, v39
	v_pk_fma_f32 v[22:23], v[40:41], s[22:23], v[22:23] op_sel_hi:[1,0,1] neg_lo:[1,0,0] neg_hi:[1,0,0]
	v_mul_f32_e32 v24, v24, v18
	v_mul_f32_e32 v22, v23, v18
	v_bfe_u32 v25, v24, 16, 1
	v_bfe_u32 v23, v22, 16, 1
	v_add3_u32 v24, v24, v25, s15
	v_add3_u32 v22, v22, v23, s15
	ds_write_b16_d16_hi v55, v24 offset:14592
	ds_write_b16_d16_hi v56, v22 offset:14848
	v_pk_fma_f32 v[22:23], v[40:41], s[22:23], v[30:31] op_sel_hi:[1,0,1] neg_lo:[1,0,0] neg_hi:[1,0,0]
	s_nop 0
	v_mul_f32_e32 v22, v23, v18
	v_bfe_u32 v23, v22, 16, 1
	v_add3_u32 v22, v22, v23, s15
	ds_write_b16_d16_hi v54, v22 offset:15104
	v_sub_f32_e32 v22, v26, v39
	v_mul_f32_e32 v22, v22, v18
	v_bfe_u32 v23, v22, 16, 1
	v_add3_u32 v22, v22, v23, s15
	ds_write_b16_d16_hi v53, v22 offset:15360
	v_sub_f32_e32 v22, v20, v39
	v_pk_fma_f32 v[20:21], v[40:41], s[22:23], v[20:21] op_sel_hi:[1,0,1] neg_lo:[1,0,0] neg_hi:[1,0,0]
	v_mul_f32_e32 v22, v22, v18
	v_mul_f32_e32 v20, v21, v18
	v_mul_f32_e32 v18, v19, v18
	v_bfe_u32 v23, v22, 16, 1
	v_bfe_u32 v21, v20, 16, 1
	v_bfe_u32 v19, v18, 16, 1
	v_add3_u32 v22, v22, v23, s15
	v_add3_u32 v20, v20, v21, s15
	v_add3_u32 v18, v18, v19, s15
	ds_write_b16_d16_hi v51, v22 offset:15616
	ds_write_b16_d16_hi v49, v20 offset:15872
	ds_write_b16_d16_hi v45, v18 offset:16128
	v_lshrrev_b32_e32 v18, 1, v43
	v_and_b32_e32 v18, 32, v18
	v_lshl_or_b32 v132, v44, 6, v18
	v_or_b32_e32 v18, v132, v134
	v_lshl_add_u32 v131, v18, 8, 32
	v_bitop3_b32 v18, v42, v133, 1 bitop3:0x6c
	v_lshl_add_u32 v18, v18, 4, v131
	s_waitcnt lgkmcnt(0)
	s_barrier
	ds_read_b128 v[136:139], v18 offset:55296
	s_waitcnt lgkmcnt(0)
	v_mfma_f32_32x32x16_bf16 v[50:65], v[136:139], v[2:5], 0
	v_mfma_f32_32x32x16_bf16 v[34:49], v[136:139], v[6:9], 0
	v_mfma_f32_32x32x16_bf16 v[18:33], v[136:139], v[10:13], 0
	v_mfma_f32_32x32x16_bf16 v[2:17], v[136:139], v[14:17], 0
	v_bitop3_b32 v136, v135, v133, 2 bitop3:0x36
	v_lshl_add_u32 v136, v136, 4, v131
	ds_read_b128 v[136:139], v136 offset:55296
	s_waitcnt lgkmcnt(0)
	v_mfma_f32_32x32x16_bf16 v[50:65], v[136:139], v[114:117], v[50:65]
	v_bitop3_b32 v114, v135, v133, 4 bitop3:0x36
	v_lshl_add_u32 v114, v114, 4, v131
	ds_read_b128 v[114:117], v114 offset:55296
	v_mfma_f32_32x32x16_bf16 v[34:49], v[136:139], v[118:121], v[34:49]
	v_mfma_f32_32x32x16_bf16 v[18:33], v[136:139], v[122:125], v[18:33]
	s_waitcnt lgkmcnt(0)
	v_mfma_f32_32x32x16_bf16 v[34:49], v[114:117], v[102:105], v[34:49]
	v_bitop3_b32 v102, v135, v133, 6 bitop3:0x36
	v_lshl_add_u32 v102, v102, 4, v131
	ds_read_b128 v[102:105], v102 offset:55296
	v_mfma_f32_32x32x16_bf16 v[2:17], v[136:139], v[126:129], v[2:17]
	v_mfma_f32_32x32x16_bf16 v[18:33], v[114:117], v[106:109], v[18:33]
	s_waitcnt lgkmcnt(0)
	v_mfma_f32_32x32x16_bf16 v[34:49], v[102:105], v[90:93], v[34:49]
	v_bitop3_b32 v90, v135, v133, 8 bitop3:0x36
	v_lshl_add_u32 v90, v90, 4, v131
	ds_read_b128 v[90:93], v90 offset:55296
	v_mfma_f32_32x32x16_bf16 v[2:17], v[114:117], v[110:113], v[2:17]
	v_mfma_f32_32x32x16_bf16 v[18:33], v[102:105], v[94:97], v[18:33]
	v_mfma_f32_32x32x16_bf16 v[2:17], v[102:105], v[98:101], v[2:17]
	v_lshlrev_b32_e32 v104, 7, v130
	v_or_b32_e32 v102, v104, v134
	v_ashrrev_i32_e32 v103, 31, v102
	v_lshlrev_b64 v[106:107], 2, v[102:103]
	v_lshl_or_b32 v98, v135, 2, v132
	v_or_b32_e32 v100, s3, v134
	v_mov_b32_e32 v101, s5
	s_waitcnt lgkmcnt(0)
	v_mfma_f32_32x32x16_bf16 v[18:33], v[90:93], v[82:85], v[18:33]
	v_bitop3_b32 v82, v135, v133, 10 bitop3:0x36
	v_lshl_add_u32 v82, v82, 4, v131
	ds_read_b128 v[82:85], v82 offset:55296
	v_lshl_add_u64 v[108:109], s[6:7], 0, v[106:107]
	v_lshl_add_u64 v[106:107], s[92:93], 0, v[106:107]
	v_ashrrev_i32_e32 v99, 31, v98
	v_lshlrev_b64 v[98:99], 1, v[98:99]
	v_mfma_f32_32x32x16_bf16 v[2:17], v[90:93], v[86:89], v[2:17]
	s_add_i32 s3, s3, s18
	s_cmpk_gt_i32 s4, 0x7f
	s_waitcnt lgkmcnt(0)
	v_mfma_f32_32x32x16_bf16 v[18:33], v[82:85], v[74:77], v[18:33]
	v_bitop3_b32 v74, v135, v133, 12 bitop3:0x36
	v_lshl_add_u32 v74, v74, 4, v131
	ds_read_b128 v[74:77], v74 offset:55296
	v_mfma_f32_32x32x16_bf16 v[2:17], v[82:85], v[78:81], v[2:17]
	s_waitcnt lgkmcnt(0)
	v_mfma_f32_32x32x16_bf16 v[2:17], v[74:77], v[70:73], v[2:17]
	v_bitop3_b32 v70, v135, v133, 14 bitop3:0x36
	v_lshl_add_u32 v70, v70, 4, v131
	ds_read_b128 v[70:73], v70 offset:55296
	v_ashrrev_i32_e32 v133, 31, v132
	s_waitcnt lgkmcnt(0)
	v_mfma_f32_32x32x16_bf16 v[2:17], v[70:73], v[66:69], v[2:17]
	v_lshlrev_b64 v[66:67], 2, v[132:133]
	v_lshl_add_u64 v[68:69], s[10:11], 0, v[66:67]
	v_lshl_add_u64 v[66:67], s[36:37], 0, v[66:67]
	v_lshl_add_u64 v[68:69], v[68:69], 0, v[154:155]
	v_lshl_add_u64 v[70:71], v[66:67], 0, v[154:155]
	global_load_dwordx4 v[90:93], v[68:69], off
	global_load_dwordx4 v[94:97], v[70:71], off
	global_load_dwordx4 v[82:85], v[68:69], off offset:32
	global_load_dwordx4 v[86:89], v[70:71], off offset:32
	global_load_dwordx4 v[74:77], v[68:69], off offset:64
	global_load_dwordx4 v[78:81], v[70:71], off offset:64
	s_nop 0
	global_load_dwordx4 v[66:69], v[68:69], off offset:96
	s_nop 0
	global_load_dwordx4 v[70:73], v[70:71], off offset:96
	s_nop 0
	global_load_dword v150, v[108:109], off
	global_load_dword v151, v[108:109], off offset:128
	global_load_dword v152, v[108:109], off offset:256
	global_load_dword v153, v[108:109], off offset:384
	global_load_dword v164, v[106:107], off
	global_load_dword v165, v[106:107], off offset:128
	global_load_dword v166, v[106:107], off offset:256
	global_load_dword v167, v[106:107], off offset:384
	v_lshlrev_b64 v[142:143], 12, v[100:101]
	v_lshl_add_u64 v[142:143], s[60:61], 0, v[142:143]
	v_lshl_add_u64 v[142:143], v[142:143], 0, v[98:99]
	v_add_co_u32_e32 v144, vcc, 0x20000, v142
	s_nop 1
	v_addc_co_u32_e32 v145, vcc, 0, v143, vcc
	v_add_co_u32_e32 v146, vcc, 0x40000, v142
	s_nop 1
	v_addc_co_u32_e32 v147, vcc, 0, v143, vcc
	v_add_co_u32_e32 v148, vcc, 0x60000, v142
	s_nop 1
	v_addc_co_u32_e32 v149, vcc, 0, v143, vcc
	global_load_dwordx2 v[110:111], v[142:143], off offset:3072
	global_load_dwordx2 v[112:113], v[142:143], off offset:3088
	global_load_dwordx2 v[114:115], v[142:143], off offset:3104
	global_load_dwordx2 v[116:117], v[142:143], off offset:3120
	global_load_dwordx2 v[118:119], v[144:145], off offset:3072
	global_load_dwordx2 v[120:121], v[144:145], off offset:3088
	global_load_dwordx2 v[122:123], v[144:145], off offset:3104
	global_load_dwordx2 v[124:125], v[144:145], off offset:3120
	global_load_dwordx2 v[126:127], v[146:147], off offset:3072
	global_load_dwordx2 v[128:129], v[146:147], off offset:3088
	global_load_dwordx2 v[130:131], v[146:147], off offset:3104
	global_load_dwordx2 v[132:133], v[146:147], off offset:3120
	global_load_dwordx2 v[134:135], v[148:149], off offset:3072
	global_load_dwordx2 v[136:137], v[148:149], off offset:3088
	global_load_dwordx2 v[138:139], v[148:149], off offset:3104
	global_load_dwordx2 v[140:141], v[148:149], off offset:3120
	v_lshlrev_b64 v[142:143], 11, v[100:101]
	v_lshl_add_u64 v[142:143], s[62:63], 0, v[142:143]
	v_lshl_add_u64 v[142:143], v[142:143], 0, v[98:99]
	v_add_co_u32_e32 v144, vcc, 0x10000, v142
	s_nop 1
	v_addc_co_u32_e32 v145, vcc, 0, v143, vcc
	v_add_co_u32_e32 v146, vcc, 0x20000, v142
	s_nop 1
	v_addc_co_u32_e32 v147, vcc, 0, v143, vcc
	v_add_co_u32_e32 v148, vcc, 0x30000, v142
	s_nop 1
	v_addc_co_u32_e32 v149, vcc, 0, v143, vcc
	s_waitcnt vmcnt(0)
	v_mul_f32_e32 v168, v94, v150
	v_fmac_f32_e32 v168, v50, v90
	v_add_f32_e32 v50, v164, v168
	v_lshlrev_b32_e32 v169, 16, v110
	v_mul_f32_e32 v50, v50, v169
	v_mul_f32_e32 v168, v95, v150
	v_fmac_f32_e32 v168, v51, v91
	v_add_f32_e32 v51, v164, v168
	v_and_b32_e32 v169, 0xffff0000, v110
	v_mul_f32_e32 v51, v51, v169
	v_mul_f32_e32 v168, v96, v150
	v_fmac_f32_e32 v168, v52, v92
	v_add_f32_e32 v52, v164, v168
	v_lshlrev_b32_e32 v169, 16, v111
	v_mul_f32_e32 v52, v52, v169
	v_mul_f32_e32 v168, v97, v150
	v_fmac_f32_e32 v168, v53, v93
	v_add_f32_e32 v53, v164, v168
	v_and_b32_e32 v169, 0xffff0000, v111
	v_mul_f32_e32 v53, v53, v169
	v_cvt_pk_bf16_f32 v50, v50, v51
	v_cvt_pk_bf16_f32 v51, v52, v53
	global_store_dwordx2 v[142:143], v[50:51], off offset:1536
	v_mul_f32_e32 v168, v86, v150
	v_fmac_f32_e32 v168, v54, v82
	v_add_f32_e32 v54, v164, v168
	v_lshlrev_b32_e32 v169, 16, v112
	v_mul_f32_e32 v54, v54, v169
	v_mul_f32_e32 v168, v87, v150
	v_fmac_f32_e32 v168, v55, v83
	v_add_f32_e32 v55, v164, v168
	v_and_b32_e32 v169, 0xffff0000, v112
	v_mul_f32_e32 v55, v55, v169
	v_mul_f32_e32 v168, v88, v150
	v_fmac_f32_e32 v168, v56, v84
	v_add_f32_e32 v56, v164, v168
	v_lshlrev_b32_e32 v169, 16, v113
	v_mul_f32_e32 v56, v56, v169
	v_mul_f32_e32 v168, v89, v150
	v_fmac_f32_e32 v168, v57, v85
	v_add_f32_e32 v57, v164, v168
	v_and_b32_e32 v169, 0xffff0000, v113
	v_mul_f32_e32 v57, v57, v169
	v_cvt_pk_bf16_f32 v54, v54, v55
	v_cvt_pk_bf16_f32 v55, v56, v57
	global_store_dwordx2 v[142:143], v[54:55], off offset:1552
	v_mul_f32_e32 v168, v78, v150
	v_fmac_f32_e32 v168, v58, v74
	v_add_f32_e32 v58, v164, v168
	v_lshlrev_b32_e32 v169, 16, v114
	v_mul_f32_e32 v58, v58, v169
	v_mul_f32_e32 v168, v79, v150
	v_fmac_f32_e32 v168, v59, v75
	v_add_f32_e32 v59, v164, v168
	v_and_b32_e32 v169, 0xffff0000, v114
	v_mul_f32_e32 v59, v59, v169
	v_mul_f32_e32 v168, v80, v150
	v_fmac_f32_e32 v168, v60, v76
	v_add_f32_e32 v60, v164, v168
	v_lshlrev_b32_e32 v169, 16, v115
	v_mul_f32_e32 v60, v60, v169
	v_mul_f32_e32 v168, v81, v150
	v_fmac_f32_e32 v168, v61, v77
	v_add_f32_e32 v61, v164, v168
	v_and_b32_e32 v169, 0xffff0000, v115
	v_mul_f32_e32 v61, v61, v169
	v_cvt_pk_bf16_f32 v58, v58, v59
	v_cvt_pk_bf16_f32 v59, v60, v61
	global_store_dwordx2 v[142:143], v[58:59], off offset:1568
	v_mul_f32_e32 v168, v70, v150
	v_fmac_f32_e32 v168, v62, v66
	v_add_f32_e32 v62, v164, v168
	v_lshlrev_b32_e32 v169, 16, v116
	v_mul_f32_e32 v62, v62, v169
	v_mul_f32_e32 v168, v71, v150
	v_fmac_f32_e32 v168, v63, v67
	v_add_f32_e32 v63, v164, v168
	v_and_b32_e32 v169, 0xffff0000, v116
	v_mul_f32_e32 v63, v63, v169
	v_mul_f32_e32 v168, v72, v150
	v_fmac_f32_e32 v168, v64, v68
	v_add_f32_e32 v64, v164, v168
	v_lshlrev_b32_e32 v169, 16, v117
	v_mul_f32_e32 v64, v64, v169
	v_mul_f32_e32 v168, v73, v150
	v_fmac_f32_e32 v168, v65, v69
	v_add_f32_e32 v65, v164, v168
	v_and_b32_e32 v169, 0xffff0000, v117
	v_mul_f32_e32 v65, v65, v169
	v_cvt_pk_bf16_f32 v62, v62, v63
	v_cvt_pk_bf16_f32 v63, v64, v65
	global_store_dwordx2 v[142:143], v[62:63], off offset:1584
	v_mul_f32_e32 v168, v94, v151
	v_fmac_f32_e32 v168, v34, v90
	v_add_f32_e32 v34, v165, v168
	v_lshlrev_b32_e32 v169, 16, v118
	v_mul_f32_e32 v34, v34, v169
	v_mul_f32_e32 v168, v95, v151
	v_fmac_f32_e32 v168, v35, v91
	v_add_f32_e32 v35, v165, v168
	v_and_b32_e32 v169, 0xffff0000, v118
	v_mul_f32_e32 v35, v35, v169
	v_mul_f32_e32 v168, v96, v151
	v_fmac_f32_e32 v168, v36, v92
	v_add_f32_e32 v36, v165, v168
	v_lshlrev_b32_e32 v169, 16, v119
	v_mul_f32_e32 v36, v36, v169
	v_mul_f32_e32 v168, v97, v151
	v_fmac_f32_e32 v168, v37, v93
	v_add_f32_e32 v37, v165, v168
	v_and_b32_e32 v169, 0xffff0000, v119
	v_mul_f32_e32 v37, v37, v169
	v_cvt_pk_bf16_f32 v34, v34, v35
	v_cvt_pk_bf16_f32 v35, v36, v37
	global_store_dwordx2 v[144:145], v[34:35], off offset:1536
	v_mul_f32_e32 v168, v86, v151
	v_fmac_f32_e32 v168, v38, v82
	v_add_f32_e32 v38, v165, v168
	v_lshlrev_b32_e32 v169, 16, v120
	v_mul_f32_e32 v38, v38, v169
	v_mul_f32_e32 v168, v87, v151
	v_fmac_f32_e32 v168, v39, v83
	v_add_f32_e32 v39, v165, v168
	v_and_b32_e32 v169, 0xffff0000, v120
	v_mul_f32_e32 v39, v39, v169
	v_mul_f32_e32 v168, v88, v151
	v_fmac_f32_e32 v168, v40, v84
	v_add_f32_e32 v40, v165, v168
	v_lshlrev_b32_e32 v169, 16, v121
	v_mul_f32_e32 v40, v40, v169
	v_mul_f32_e32 v168, v89, v151
	v_fmac_f32_e32 v168, v41, v85
	v_add_f32_e32 v41, v165, v168
	v_and_b32_e32 v169, 0xffff0000, v121
	v_mul_f32_e32 v41, v41, v169
	v_cvt_pk_bf16_f32 v38, v38, v39
	v_cvt_pk_bf16_f32 v39, v40, v41
	global_store_dwordx2 v[144:145], v[38:39], off offset:1552
	v_mul_f32_e32 v168, v78, v151
	v_fmac_f32_e32 v168, v42, v74
	v_add_f32_e32 v42, v165, v168
	v_lshlrev_b32_e32 v169, 16, v122
	v_mul_f32_e32 v42, v42, v169
	v_mul_f32_e32 v168, v79, v151
	v_fmac_f32_e32 v168, v43, v75
	v_add_f32_e32 v43, v165, v168
	v_and_b32_e32 v169, 0xffff0000, v122
	v_mul_f32_e32 v43, v43, v169
	v_mul_f32_e32 v168, v80, v151
	v_fmac_f32_e32 v168, v44, v76
	v_add_f32_e32 v44, v165, v168
	v_lshlrev_b32_e32 v169, 16, v123
	v_mul_f32_e32 v44, v44, v169
	v_mul_f32_e32 v168, v81, v151
	v_fmac_f32_e32 v168, v45, v77
	v_add_f32_e32 v45, v165, v168
	v_and_b32_e32 v169, 0xffff0000, v123
	v_mul_f32_e32 v45, v45, v169
	v_cvt_pk_bf16_f32 v42, v42, v43
	v_cvt_pk_bf16_f32 v43, v44, v45
	global_store_dwordx2 v[144:145], v[42:43], off offset:1568
	v_mul_f32_e32 v168, v70, v151
	v_fmac_f32_e32 v168, v46, v66
	v_add_f32_e32 v46, v165, v168
	v_lshlrev_b32_e32 v169, 16, v124
	v_mul_f32_e32 v46, v46, v169
	v_mul_f32_e32 v168, v71, v151
	v_fmac_f32_e32 v168, v47, v67
	v_add_f32_e32 v47, v165, v168
	v_and_b32_e32 v169, 0xffff0000, v124
	v_mul_f32_e32 v47, v47, v169
	v_mul_f32_e32 v168, v72, v151
	v_fmac_f32_e32 v168, v48, v68
	v_add_f32_e32 v48, v165, v168
	v_lshlrev_b32_e32 v169, 16, v125
	v_mul_f32_e32 v48, v48, v169
	v_mul_f32_e32 v168, v73, v151
	v_fmac_f32_e32 v168, v49, v69
	v_add_f32_e32 v49, v165, v168
	v_and_b32_e32 v169, 0xffff0000, v125
	v_mul_f32_e32 v49, v49, v169
	v_cvt_pk_bf16_f32 v46, v46, v47
	v_cvt_pk_bf16_f32 v47, v48, v49
	global_store_dwordx2 v[144:145], v[46:47], off offset:1584
	v_mul_f32_e32 v168, v94, v152
	v_fmac_f32_e32 v168, v18, v90
	v_add_f32_e32 v18, v166, v168
	v_lshlrev_b32_e32 v169, 16, v126
	v_mul_f32_e32 v18, v18, v169
	v_mul_f32_e32 v168, v95, v152
	v_fmac_f32_e32 v168, v19, v91
	v_add_f32_e32 v19, v166, v168
	v_and_b32_e32 v169, 0xffff0000, v126
	v_mul_f32_e32 v19, v19, v169
	v_mul_f32_e32 v168, v96, v152
	v_fmac_f32_e32 v168, v20, v92
	v_add_f32_e32 v20, v166, v168
	v_lshlrev_b32_e32 v169, 16, v127
	v_mul_f32_e32 v20, v20, v169
	v_mul_f32_e32 v168, v97, v152
	v_fmac_f32_e32 v168, v21, v93
	v_add_f32_e32 v21, v166, v168
	v_and_b32_e32 v169, 0xffff0000, v127
	v_mul_f32_e32 v21, v21, v169
	v_cvt_pk_bf16_f32 v18, v18, v19
	v_cvt_pk_bf16_f32 v19, v20, v21
	global_store_dwordx2 v[146:147], v[18:19], off offset:1536
	v_mul_f32_e32 v168, v86, v152
	v_fmac_f32_e32 v168, v22, v82
	v_add_f32_e32 v22, v166, v168
	v_lshlrev_b32_e32 v169, 16, v128
	v_mul_f32_e32 v22, v22, v169
	v_mul_f32_e32 v168, v87, v152
	v_fmac_f32_e32 v168, v23, v83
	v_add_f32_e32 v23, v166, v168
	v_and_b32_e32 v169, 0xffff0000, v128
	v_mul_f32_e32 v23, v23, v169
	v_mul_f32_e32 v168, v88, v152
	v_fmac_f32_e32 v168, v24, v84
	v_add_f32_e32 v24, v166, v168
	v_lshlrev_b32_e32 v169, 16, v129
	v_mul_f32_e32 v24, v24, v169
	v_mul_f32_e32 v168, v89, v152
	v_fmac_f32_e32 v168, v25, v85
	v_add_f32_e32 v25, v166, v168
	v_and_b32_e32 v169, 0xffff0000, v129
	v_mul_f32_e32 v25, v25, v169
	v_cvt_pk_bf16_f32 v22, v22, v23
	v_cvt_pk_bf16_f32 v23, v24, v25
	global_store_dwordx2 v[146:147], v[22:23], off offset:1552
	v_mul_f32_e32 v168, v78, v152
	v_fmac_f32_e32 v168, v26, v74
	v_add_f32_e32 v26, v166, v168
	v_lshlrev_b32_e32 v169, 16, v130
	v_mul_f32_e32 v26, v26, v169
	v_mul_f32_e32 v168, v79, v152
	v_fmac_f32_e32 v168, v27, v75
	v_add_f32_e32 v27, v166, v168
	v_and_b32_e32 v169, 0xffff0000, v130
	v_mul_f32_e32 v27, v27, v169
	v_mul_f32_e32 v168, v80, v152
	v_fmac_f32_e32 v168, v28, v76
	v_add_f32_e32 v28, v166, v168
	v_lshlrev_b32_e32 v169, 16, v131
	v_mul_f32_e32 v28, v28, v169
	v_mul_f32_e32 v168, v81, v152
	v_fmac_f32_e32 v168, v29, v77
	v_add_f32_e32 v29, v166, v168
	v_and_b32_e32 v169, 0xffff0000, v131
	v_mul_f32_e32 v29, v29, v169
	v_cvt_pk_bf16_f32 v26, v26, v27
	v_cvt_pk_bf16_f32 v27, v28, v29
	global_store_dwordx2 v[146:147], v[26:27], off offset:1568
	v_mul_f32_e32 v168, v70, v152
	v_fmac_f32_e32 v168, v30, v66
	v_add_f32_e32 v30, v166, v168
	v_lshlrev_b32_e32 v169, 16, v132
	v_mul_f32_e32 v30, v30, v169
	v_mul_f32_e32 v168, v71, v152
	v_fmac_f32_e32 v168, v31, v67
	v_add_f32_e32 v31, v166, v168
	v_and_b32_e32 v169, 0xffff0000, v132
	v_mul_f32_e32 v31, v31, v169
	v_mul_f32_e32 v168, v72, v152
	v_fmac_f32_e32 v168, v32, v68
	v_add_f32_e32 v32, v166, v168
	v_lshlrev_b32_e32 v169, 16, v133
	v_mul_f32_e32 v32, v32, v169
	v_mul_f32_e32 v168, v73, v152
	v_fmac_f32_e32 v168, v33, v69
	v_add_f32_e32 v33, v166, v168
	v_and_b32_e32 v169, 0xffff0000, v133
	v_mul_f32_e32 v33, v33, v169
	v_cvt_pk_bf16_f32 v30, v30, v31
	v_cvt_pk_bf16_f32 v31, v32, v33
	global_store_dwordx2 v[146:147], v[30:31], off offset:1584
	v_mul_f32_e32 v168, v94, v153
	v_fmac_f32_e32 v168, v2, v90
	v_add_f32_e32 v2, v167, v168
	v_lshlrev_b32_e32 v169, 16, v134
	v_mul_f32_e32 v2, v2, v169
	v_mul_f32_e32 v168, v95, v153
	v_fmac_f32_e32 v168, v3, v91
	v_add_f32_e32 v3, v167, v168
	v_and_b32_e32 v169, 0xffff0000, v134
	v_mul_f32_e32 v3, v3, v169
	v_mul_f32_e32 v168, v96, v153
	v_fmac_f32_e32 v168, v4, v92
	v_add_f32_e32 v4, v167, v168
	v_lshlrev_b32_e32 v169, 16, v135
	v_mul_f32_e32 v4, v4, v169
	v_mul_f32_e32 v168, v97, v153
	v_fmac_f32_e32 v168, v5, v93
	v_add_f32_e32 v5, v167, v168
	v_and_b32_e32 v169, 0xffff0000, v135
	v_mul_f32_e32 v5, v5, v169
	v_cvt_pk_bf16_f32 v2, v2, v3
	v_cvt_pk_bf16_f32 v3, v4, v5
	global_store_dwordx2 v[148:149], v[2:3], off offset:1536
	v_mul_f32_e32 v168, v86, v153
	v_fmac_f32_e32 v168, v6, v82
	v_add_f32_e32 v6, v167, v168
	v_lshlrev_b32_e32 v169, 16, v136
	v_mul_f32_e32 v6, v6, v169
	v_mul_f32_e32 v168, v87, v153
	v_fmac_f32_e32 v168, v7, v83
	v_add_f32_e32 v7, v167, v168
	v_and_b32_e32 v169, 0xffff0000, v136
	v_mul_f32_e32 v7, v7, v169
	v_mul_f32_e32 v168, v88, v153
	v_fmac_f32_e32 v168, v8, v84
	v_add_f32_e32 v8, v167, v168
	v_lshlrev_b32_e32 v169, 16, v137
	v_mul_f32_e32 v8, v8, v169
	v_mul_f32_e32 v168, v89, v153
	v_fmac_f32_e32 v168, v9, v85
	v_add_f32_e32 v9, v167, v168
	v_and_b32_e32 v169, 0xffff0000, v137
	v_mul_f32_e32 v9, v9, v169
	v_cvt_pk_bf16_f32 v6, v6, v7
	v_cvt_pk_bf16_f32 v7, v8, v9
	global_store_dwordx2 v[148:149], v[6:7], off offset:1552
	v_mul_f32_e32 v168, v78, v153
	v_fmac_f32_e32 v168, v10, v74
	v_add_f32_e32 v10, v167, v168
	v_lshlrev_b32_e32 v169, 16, v138
	v_mul_f32_e32 v10, v10, v169
	v_mul_f32_e32 v168, v79, v153
	v_fmac_f32_e32 v168, v11, v75
	v_add_f32_e32 v11, v167, v168
	v_and_b32_e32 v169, 0xffff0000, v138
	v_mul_f32_e32 v11, v11, v169
	v_mul_f32_e32 v168, v80, v153
	v_fmac_f32_e32 v168, v12, v76
	v_add_f32_e32 v12, v167, v168
	v_lshlrev_b32_e32 v169, 16, v139
	v_mul_f32_e32 v12, v12, v169
	v_mul_f32_e32 v168, v81, v153
	v_fmac_f32_e32 v168, v13, v77
	v_add_f32_e32 v13, v167, v168
	v_and_b32_e32 v169, 0xffff0000, v139
	v_mul_f32_e32 v13, v13, v169
	v_cvt_pk_bf16_f32 v10, v10, v11
	v_cvt_pk_bf16_f32 v11, v12, v13
	global_store_dwordx2 v[148:149], v[10:11], off offset:1568
	v_mul_f32_e32 v168, v70, v153
	v_fmac_f32_e32 v168, v14, v66
	v_add_f32_e32 v14, v167, v168
	v_lshlrev_b32_e32 v169, 16, v140
	v_mul_f32_e32 v14, v14, v169
	v_mul_f32_e32 v168, v71, v153
	v_fmac_f32_e32 v168, v15, v67
	v_add_f32_e32 v15, v167, v168
	v_and_b32_e32 v169, 0xffff0000, v140
	v_mul_f32_e32 v15, v15, v169
	v_mul_f32_e32 v168, v72, v153
	v_fmac_f32_e32 v168, v16, v68
	v_add_f32_e32 v16, v167, v168
	v_lshlrev_b32_e32 v169, 16, v141
	v_mul_f32_e32 v16, v16, v169
	v_mul_f32_e32 v168, v73, v153
	v_fmac_f32_e32 v168, v17, v69
	v_add_f32_e32 v17, v167, v168
	v_and_b32_e32 v169, 0xffff0000, v141
	v_mul_f32_e32 v17, v17, v169
	v_cvt_pk_bf16_f32 v14, v14, v15
	v_cvt_pk_bf16_f32 v15, v16, v17
	global_store_dwordx2 v[148:149], v[14:15], off offset:1584
	s_barrier
	s_cbranch_scc0 .LBB0_849

.LBB0_857:
	s_or_b64 exec, exec, s[2:3]
	s_mov_b32 s98, 0xffffd000
	s_mov_b32 s99, -1
	v_lshl_add_u64 v[200:201], v[130:131], 1, s[30:31]
	v_lshl_add_u64 v[202:203], v[200:201], 0, s[98:99]
	s_mov_b32 s98, 0xfffff000
	v_lshl_add_u64 v[200:201], v[200:201], 0, s[98:99]
	global_load_ushort v192, v[202:203], off offset:-2816
	global_load_ushort v193, v[202:203], off offset:-1280
	global_load_ushort v194, v[202:203], off offset:1280
	global_load_ushort v195, v[202:203], off offset:2816
	global_load_ushort v196, v[200:201], off offset:-2816
	global_load_ushort v197, v[200:201], off offset:-1280
	global_load_ushort v198, v[200:201], off offset:1280
	global_load_ushort v199, v[200:201], off offset:2816
	s_mov_b64 s[100:101], exec
	s_mov_b64 exec, s[36:37]
	s_cbranch_execz .Ls_hoist_skip_c2
	global_load_ushort v220, v[202:203], off offset:-512
	global_load_ushort v221, v[202:203], off offset:3584
	global_load_ushort v222, v[200:201], off offset:-512
	global_load_ushort v223, v[200:201], off offset:3584
	v_add_u32_e32 v232, s5, v130
	v_ashrrev_i32_e32 v233, 31, v232
	v_lshlrev_b64 v[232:233], 2, v[232:233]
	v_lshl_add_u64 v[234:235], s[86:87], 0, v[232:233]
	v_lshl_add_u64 v[232:233], s[88:89], 0, v[232:233]
	global_load_dword v204, v[234:235], off
	global_load_dword v205, v[232:233], off
	v_ashrrev_i32_e32 v232, 6, v130
	v_add_u32_e32 v232, s6, v232
	v_lshlrev_b32_e32 v234, 7, v232
	v_ashrrev_i32_e32 v233, 31, v232
	v_ashrrev_i32_e32 v235, 31, v234
	v_lshlrev_b64 v[232:233], 16, v[232:233]
	v_lshl_add_u64 v[234:235], v[234:235], 2, s[92:93]
	v_lshl_add_u64 v[232:233], s[90:91], 0, v[232:233]
	global_load_dwordx4 v[206:209], v[234:235], off
	global_load_dword v210, v[232:233], off
	global_load_dwordx2 v[212:213], v[232:233], off offset:512
	global_load_dwordx3 v[224:226], v[232:233], off offset:1024
	global_load_dwordx4 v[228:231], v[232:233], off offset:1536
.Ls_hoist_skip_c2:
	s_mov_b64 exec, s[100:101]
	v_and_b32_e32 v10, 64, v181
	v_add_u32_e32 v16, 64, v10
	v_xor_b32_e32 v10, 32, v181
	v_cmp_lt_i32_e32 vcc, v10, v16
	v_xor_b32_e32 v11, 16, v181
	v_xor_b32_e32 v12, 8, v181
	v_cndmask_b32_e32 v10, v181, v10, vcc
	v_cmp_lt_i32_e32 vcc, v11, v16
	v_lshlrev_b32_e32 v34, 2, v10
	ds_bpermute_b32 v10, v34, v140
	v_cndmask_b32_e32 v11, v181, v11, vcc
	v_lshlrev_b32_e32 v35, 2, v11
	ds_bpermute_b32 v11, v34, v141
	v_cmp_lt_i32_e32 vcc, v12, v16
	v_xor_b32_e32 v14, 4, v181
	v_xor_b32_e32 v17, 1, v181
	v_cndmask_b32_e32 v12, v181, v12, vcc
	s_waitcnt lgkmcnt(0)
	v_pk_add_f32 v[10:11], v[140:141], v[10:11]
	v_lshlrev_b32_e32 v36, 2, v12
	ds_bpermute_b32 v12, v35, v10
	ds_bpermute_b32 v13, v35, v11
	v_cmp_lt_i32_e32 vcc, v14, v16
	ds_bpermute_b32 v18, v34, v8
	ds_bpermute_b32 v19, v34, v9
	v_cndmask_b32_e32 v14, v181, v14, vcc
	s_waitcnt lgkmcnt(2)
	v_pk_add_f32 v[10:11], v[10:11], v[12:13]
	ds_bpermute_b32 v12, v36, v10
	ds_bpermute_b32 v13, v36, v11
	v_lshlrev_b32_e32 v37, 2, v14
	v_xor_b32_e32 v14, 2, v181
	v_cmp_lt_i32_e32 vcc, v14, v16
	ds_bpermute_b32 v20, v34, v6
	s_waitcnt lgkmcnt(1)
	v_pk_add_f32 v[10:11], v[10:11], v[12:13]
	ds_bpermute_b32 v12, v37, v10
	ds_bpermute_b32 v13, v37, v11
	v_cndmask_b32_e32 v14, v181, v14, vcc
	v_cmp_lt_i32_e32 vcc, v17, v16
	v_lshlrev_b32_e32 v38, 2, v14
	ds_bpermute_b32 v21, v34, v7
	v_cndmask_b32_e32 v16, v181, v17, vcc
	s_waitcnt lgkmcnt(1)
	v_pk_add_f32 v[10:11], v[10:11], v[12:13]
	v_lshlrev_b32_e32 v39, 2, v16
	ds_bpermute_b32 v16, v38, v10
	ds_bpermute_b32 v17, v38, v11
	s_waitcnt lgkmcnt(2)
	v_pk_add_f32 v[20:21], v[6:7], v[20:21]
	ds_bpermute_b32 v22, v35, v20
	ds_bpermute_b32 v23, v35, v21
	ds_bpermute_b32 v14, v34, v136
	s_waitcnt lgkmcnt(3)
	v_pk_add_f32 v[10:11], v[10:11], v[16:17]
	v_pk_add_f32 v[16:17], v[8:9], v[18:19]
	ds_bpermute_b32 v18, v35, v16
	ds_bpermute_b32 v19, v35, v17
	s_waitcnt lgkmcnt(3)
	v_pk_add_f32 v[20:21], v[20:21], v[22:23]
	ds_bpermute_b32 v22, v36, v20
	ds_bpermute_b32 v23, v36, v21
	ds_bpermute_b32 v15, v34, v137
	s_waitcnt lgkmcnt(3)
	v_pk_add_f32 v[16:17], v[16:17], v[18:19]
	ds_bpermute_b32 v18, v36, v16
	ds_bpermute_b32 v19, v36, v17
	s_waitcnt lgkmcnt(3)
	v_pk_add_f32 v[20:21], v[20:21], v[22:23]
	ds_bpermute_b32 v22, v37, v20
	ds_bpermute_b32 v23, v37, v21
	s_waitcnt lgkmcnt(4)
	v_pk_add_f32 v[12:13], v[136:137], v[14:15]
	s_waitcnt lgkmcnt(2)
	v_pk_add_f32 v[16:17], v[16:17], v[18:19]
	ds_bpermute_b32 v18, v37, v16
	ds_bpermute_b32 v19, v37, v17
	s_waitcnt lgkmcnt(2)
	v_pk_add_f32 v[20:21], v[20:21], v[22:23]
	ds_bpermute_b32 v22, v34, v134
	ds_bpermute_b32 v23, v34, v135
	ds_bpermute_b32 v26, v38, v20
	s_waitcnt lgkmcnt(3)
	v_pk_add_f32 v[16:17], v[16:17], v[18:19]
	ds_bpermute_b32 v18, v38, v16
	ds_bpermute_b32 v19, v38, v17
	s_waitcnt lgkmcnt(3)
	v_pk_add_f32 v[22:23], v[134:135], v[22:23]
	ds_bpermute_b32 v28, v35, v22
	ds_bpermute_b32 v29, v35, v23
	ds_bpermute_b32 v27, v38, v21
	s_waitcnt lgkmcnt(3)
	v_pk_add_f32 v[6:7], v[16:17], v[18:19]
	ds_bpermute_b32 v18, v34, v132
	ds_bpermute_b32 v19, v34, v133
	s_waitcnt lgkmcnt(3)
	v_pk_add_f32 v[28:29], v[22:23], v[28:29]
	ds_bpermute_b32 v32, v36, v28
	ds_bpermute_b32 v33, v36, v29
	ds_bpermute_b32 v14, v35, v12
	s_waitcnt lgkmcnt(3)
	v_pk_add_f32 v[18:19], v[132:133], v[18:19]
	ds_bpermute_b32 v24, v35, v18
	ds_bpermute_b32 v25, v35, v19
	ds_bpermute_b32 v15, v35, v13
	ds_bpermute_b32 v8, v39, v10
	ds_bpermute_b32 v9, v39, v11
	ds_bpermute_b32 v16, v39, v6
	s_waitcnt lgkmcnt(4)
	v_pk_add_f32 v[18:19], v[18:19], v[24:25]
	ds_bpermute_b32 v24, v36, v18
	ds_bpermute_b32 v25, v36, v19
	s_waitcnt lgkmcnt(5)
	v_pk_add_f32 v[12:13], v[12:13], v[14:15]
	ds_bpermute_b32 v14, v36, v12
	ds_bpermute_b32 v15, v36, v13
	ds_bpermute_b32 v17, v39, v7
	s_waitcnt lgkmcnt(3)
	v_pk_add_f32 v[18:19], v[18:19], v[24:25]
	ds_bpermute_b32 v24, v37, v18
	ds_bpermute_b32 v25, v37, v19
	s_waitcnt lgkmcnt(3)
	v_pk_add_f32 v[12:13], v[12:13], v[14:15]
	ds_bpermute_b32 v14, v37, v12
	ds_bpermute_b32 v15, v37, v13
	s_waitcnt lgkmcnt(2)
	v_pk_add_f32 v[24:25], v[18:19], v[24:25]
	v_pk_add_f32 v[18:19], v[20:21], v[26:27]
	v_pk_add_f32 v[26:27], v[28:29], v[32:33]
	ds_bpermute_b32 v30, v38, v24
	ds_bpermute_b32 v31, v38, v25
	ds_bpermute_b32 v28, v37, v26
	ds_bpermute_b32 v29, v37, v27
	s_waitcnt lgkmcnt(4)
	v_pk_add_f32 v[12:13], v[12:13], v[14:15]
	ds_bpermute_b32 v14, v38, v12
	s_waitcnt lgkmcnt(3)
	v_pk_add_f32 v[20:21], v[24:25], v[30:31]
	ds_bpermute_b32 v30, v34, v2
	ds_bpermute_b32 v31, v34, v3
	s_waitcnt lgkmcnt(3)
	v_pk_add_f32 v[26:27], v[26:27], v[28:29]
	ds_bpermute_b32 v28, v34, v4
	ds_bpermute_b32 v29, v34, v5
	ds_bpermute_b32 v32, v38, v26
	s_waitcnt lgkmcnt(3)
	v_pk_add_f32 v[2:3], v[2:3], v[30:31]
	ds_bpermute_b32 v30, v35, v2
	ds_bpermute_b32 v31, v35, v3
	s_waitcnt lgkmcnt(3)
	v_pk_add_f32 v[4:5], v[4:5], v[28:29]
	ds_bpermute_b32 v28, v35, v4
	ds_bpermute_b32 v29, v35, v5
	ds_bpermute_b32 v33, v38, v27
	s_waitcnt lgkmcnt(3)
	v_pk_add_f32 v[30:31], v[2:3], v[30:31]
	ds_bpermute_b32 v34, v36, v30
	ds_bpermute_b32 v35, v36, v31
	s_waitcnt lgkmcnt(3)
	v_pk_add_f32 v[4:5], v[4:5], v[28:29]
	ds_bpermute_b32 v28, v36, v4
	ds_bpermute_b32 v29, v36, v5
	s_waitcnt lgkmcnt(4)
	v_pk_add_f32 v[2:3], v[26:27], v[32:33]
	s_waitcnt lgkmcnt(2)
	v_pk_add_f32 v[26:27], v[30:31], v[34:35]
	ds_bpermute_b32 v30, v37, v26
	ds_bpermute_b32 v31, v37, v27
	s_waitcnt lgkmcnt(2)
	v_pk_add_f32 v[28:29], v[4:5], v[28:29]
	ds_bpermute_b32 v32, v37, v28
	ds_bpermute_b32 v33, v37, v29
	ds_bpermute_b32 v15, v38, v13
	s_waitcnt lgkmcnt(3)
	v_pk_add_f32 v[26:27], v[26:27], v[30:31]
	ds_bpermute_b32 v30, v38, v26
	ds_bpermute_b32 v31, v38, v27
	s_waitcnt lgkmcnt(3)
	v_pk_add_f32 v[32:33], v[28:29], v[32:33]
	ds_bpermute_b32 v34, v38, v32
	ds_bpermute_b32 v35, v38, v33
	s_waitcnt lgkmcnt(4)
	v_pk_add_f32 v[12:13], v[12:13], v[14:15]
	s_waitcnt lgkmcnt(2)
	v_pk_add_f32 v[26:27], v[26:27], v[30:31]
	ds_bpermute_b32 v14, v39, v12
	ds_bpermute_b32 v15, v39, v13
	s_waitcnt lgkmcnt(2)
	v_pk_add_f32 v[30:31], v[32:33], v[34:35]
	ds_bpermute_b32 v22, v39, v18
	ds_bpermute_b32 v23, v39, v19
	ds_bpermute_b32 v24, v39, v20
	ds_bpermute_b32 v25, v39, v21
	ds_bpermute_b32 v4, v39, v2
	ds_bpermute_b32 v5, v39, v3
	ds_bpermute_b32 v28, v39, v26
	ds_bpermute_b32 v29, v39, v27
	ds_bpermute_b32 v32, v39, v30
	ds_bpermute_b32 v33, v39, v31
	v_and_b32_e32 v34, 63, v130
	v_cmp_eq_u32_e32 vcc, 0, v34
	s_and_saveexec_b64 s[2:3], vcc
	s_cbranch_execz .LBB0_859
	v_add_u32_e32 v34, 32, v130
	v_add_u32_e32 v34, 0x16000, v34
	v_pk_add_f32 v[6:7], v[6:7], v[16:17]
	s_waitcnt lgkmcnt(4)
	v_pk_add_f32 v[2:3], v[2:3], v[4:5]
	v_pk_add_f32 v[8:9], v[10:11], v[8:9]
	ds_write2_b32 v34, v6, v7 offset0:4 offset1:5
	v_pk_add_f32 v[6:7], v[18:19], v[22:23]
	ds_write2_b32 v34, v2, v3 offset0:10 offset1:11
	s_waitcnt lgkmcnt(4)
	v_pk_add_f32 v[2:3], v[26:27], v[28:29]
	ds_write2_b32 v34, v8, v9 offset1:1
	v_pk_add_f32 v[8:9], v[12:13], v[14:15]
	ds_write2_b32 v34, v6, v7 offset0:6 offset1:7
	v_pk_add_f32 v[6:7], v[20:21], v[24:25]
	ds_write2_b32 v34, v2, v3 offset0:12 offset1:13
	s_waitcnt lgkmcnt(5)
	v_pk_add_f32 v[2:3], v[30:31], v[32:33]
	ds_write2_b32 v34, v8, v9 offset0:2 offset1:3
	ds_write2_b32 v34, v6, v7 offset0:8 offset1:9
	ds_write2_b32 v34, v2, v3 offset0:14 offset1:15
.LBB0_859:
	s_or_b64 exec, exec, s[2:3]
	v_readlane_b32 s2, v242, 9
	s_waitcnt lgkmcnt(0)
	s_barrier
	v_mov_b32_e32 v2, s2
	v_readlane_b32 s2, v242, 10
	s_nop 1
	v_mov_b32_e32 v3, s2
	v_readlane_b32 s2, v242, 11
	ds_read_b128 v[6:9], v2
	ds_read_b128 v[2:5], v3
	v_mov_b32_e32 v10, s2
	v_readlane_b32 s2, v242, 12
	s_nop 1
	v_mov_b32_e32 v11, s2
	v_readlane_b32 s2, v242, 13
	ds_read_b128 v[14:17], v10
	ds_read_b128 v[10:13], v11
	v_mov_b32_e32 v18, s2
	v_readlane_b32 s2, v242, 14
	s_nop 1
	v_mov_b32_e32 v19, s2
	v_readlane_b32 s2, v242, 15
	ds_read_b128 v[22:25], v18
	ds_read_b128 v[18:21], v19
	v_mov_b32_e32 v26, s2
	v_readlane_b32 s2, v242, 16
	s_nop 1
	v_mov_b32_e32 v27, s2
	v_readlane_b32 s2, v242, 17
	ds_read_b128 v[30:33], v26
	ds_read_b128 v[26:29], v27
	v_mov_b32_e32 v34, s2
	v_readlane_b32 s2, v242, 18
	s_nop 1
	v_mov_b32_e32 v35, s2
	v_readlane_b32 s2, v242, 19
	ds_read_b128 v[38:41], v34
	ds_read_b128 v[34:37], v35
	v_mov_b32_e32 v42, s2
	v_readlane_b32 s2, v242, 20
	s_nop 1
	v_mov_b32_e32 v43, s2
	v_readlane_b32 s2, v242, 21
	ds_read_b128 v[46:49], v42
	ds_read_b128 v[42:45], v43
	v_mov_b32_e32 v50, s2
	v_readlane_b32 s2, v242, 22
	s_nop 1
	v_mov_b32_e32 v51, s2
	v_readlane_b32 s2, v242, 23
	ds_read_b128 v[54:57], v50
	ds_read_b128 v[50:53], v51
	v_mov_b32_e32 v58, s2
	v_readlane_b32 s2, v242, 24
	s_nop 1
	v_mov_b32_e32 v59, s2
	ds_read_b128 v[62:65], v58
	ds_read_b128 v[58:61], v59
	s_and_saveexec_b64 s[34:35], s[38:39]
	s_cbranch_execz .LBB0_861
	v_lshlrev_b64 v[142:143], 2, v[138:139]
	v_lshl_add_u64 v[144:145], s[80:81], 0, v[142:143]
	v_lshl_add_u64 v[142:143], s[82:83], 0, v[142:143]
	global_load_dword v164, v[144:145], off
	global_load_dword v154, v[142:143], off
	v_readlane_b32 s2, v242, 25
	s_mov_b32 s12, 0x3b2aaaab
	s_nop 0
	v_mov_b32_e32 v66, s2
	v_readlane_b32 s2, v242, 26
	ds_read_b128 v[66:69], v66
	s_nop 0
	v_mov_b32_e32 v70, s2
	v_readlane_b32 s2, v242, 27
	ds_read_b128 v[70:73], v70
	s_waitcnt lgkmcnt(0)
	v_mov_b32_e32 v142, v70
	v_mov_b32_e32 v74, s2
	v_readlane_b32 s2, v242, 28
	ds_read_b128 v[74:77], v74
	s_nop 0
	v_mov_b32_e32 v78, s2
	v_readlane_b32 s2, v242, 29
	ds_read_b128 v[78:81], v78
	s_nop 0
	v_mov_b32_e32 v82, s2
	v_readlane_b32 s2, v242, 30
	ds_read_b128 v[82:85], v82
	s_nop 0
	v_mov_b32_e32 v86, s2
	v_readlane_b32 s2, v242, 31
	ds_read_b128 v[86:89], v86
	s_nop 0
	v_mov_b32_e32 v90, s2
	v_readlane_b32 s2, v242, 32
	ds_read_b128 v[90:93], v90
	s_nop 0
	v_mov_b32_e32 v94, s2
	s_add_i32 s2, 32, 0x16000
	v_mov_b32_e32 v98, s2
	v_readlane_b32 s2, v242, 33
	ds_read_b128 v[98:101], v98
	ds_read_b128 v[94:97], v94
	v_mov_b32_e32 v102, s2
	v_readlane_b32 s2, v242, 34
	ds_read_b128 v[102:105], v102
	s_waitcnt lgkmcnt(0)
	v_mov_b32_e32 v143, v102
	v_mov_b32_e32 v106, s2
	v_readlane_b32 s2, v242, 35
	ds_read_b128 v[106:109], v106
	v_mov_b32_e32 v102, v71
	v_mov_b32_e32 v110, s2
	v_readlane_b32 s2, v242, 36
	ds_read_b128 v[110:113], v110
	s_nop 0
	v_mov_b32_e32 v114, s2
	v_readlane_b32 s2, v242, 37
	ds_read_b128 v[114:117], v114
	s_nop 0
	v_mov_b32_e32 v118, s2
	v_readlane_b32 s2, v242, 38
	ds_read_b128 v[118:121], v118
	s_nop 0
	v_mov_b32_e32 v122, s2
	v_readlane_b32 s2, v242, 39
	ds_read_b128 v[122:125], v122
	s_nop 0
	v_mov_b32_e32 v126, s2
	v_readlane_b32 s2, v242, 40
	s_mulk_i32 s2, 0x300
	ds_read_b128 v[126:129], v126
	v_add_u32_e32 v138, s2, v138
	v_ashrrev_i32_e32 v139, 31, v138
	v_lshl_add_u64 v[138:139], v[138:139], 2, s[84:85]
	global_load_dword v151, v[138:139], off
	global_load_dword v153, v[138:139], off offset:1536
	global_load_dword v152, v[138:139], off offset:3072
	v_mov_b32_e32 v138, v66
	v_mov_b32_e32 v139, v98
	v_pk_add_f32 v[138:139], v[138:139], 0 op_sel_hi:[1,0]
	s_movk_i32 s2, 0xd000
	v_pk_add_f32 v[138:139], v[138:139], v[142:143]
	v_mov_b32_e32 v142, v74
	s_waitcnt lgkmcnt(5)
	v_mov_b32_e32 v143, v106
	v_pk_add_f32 v[138:139], v[138:139], v[142:143]
	v_mov_b32_e32 v142, v78
	s_waitcnt lgkmcnt(4)
	v_mov_b32_e32 v143, v110
	v_pk_add_f32 v[138:139], v[138:139], v[142:143]
	v_mov_b32_e32 v142, v82
	s_waitcnt lgkmcnt(3)
	v_mov_b32_e32 v143, v114
	v_pk_add_f32 v[138:139], v[138:139], v[142:143]
	v_mov_b32_e32 v142, v86
	s_waitcnt lgkmcnt(2)
	v_mov_b32_e32 v143, v118
	v_pk_add_f32 v[138:139], v[138:139], v[142:143]
	v_mov_b32_e32 v142, v90
	s_waitcnt lgkmcnt(1)
	v_mov_b32_e32 v143, v122
	v_pk_add_f32 v[138:139], v[138:139], v[142:143]
	v_mov_b32_e32 v142, v94
	s_waitcnt lgkmcnt(0)
	v_mov_b32_e32 v143, v126
	v_pk_add_f32 v[138:139], v[138:139], v[142:143]
	v_lshlrev_b64 v[142:143], 1, v[130:131]
	v_pk_mul_f32 v[138:139], v[138:139], s[12:13] op_sel_hi:[1,0]
	v_mov_b32_e32 v98, v67
	v_fma_f32 v66, -v139, v139, v138
	v_max_f32_e32 v66, 0, v66
	v_add_f32_e32 v66, 0x358637bd, v66
	v_cmp_gt_f32_e32 vcc, s33, v66
	v_mul_f32_e32 v70, 0x4b800000, v66
	v_mov_b32_e32 v106, v75
	v_cndmask_b32_e32 v66, v66, v70, vcc
	v_rsq_f32_e32 v66, v66
	v_mov_b32_e32 v110, v79
	v_mov_b32_e32 v114, v83
	v_mov_b32_e32 v118, v87
	v_mul_f32_e32 v70, 0x45800000, v66
	v_cndmask_b32_e32 v66, v66, v70, vcc
	v_sub_f32_e32 v70, v140, v139
	v_mul_f32_e32 v66, v70, v66
	s_waitcnt vmcnt(3)
	v_fma_f32 v66, v164, v66, v154
	v_mul_f32_e32 v70, 0xbfb8aa3b, v66
	v_exp_f32_e32 v70, v70
	v_lshl_add_u64 v[138:139], s[30:31], 0, v[142:143]
	v_add_co_u32_e32 v144, vcc, s2, v138
	v_add_f32_e32 v70, 1.0, v70
	v_rcp_f32_e32 v70, v70
	v_addc_co_u32_e32 v145, vcc, -1, v139, vcc
	v_lshl_add_u64 v[142:143], s[10:11], 0, v[142:143]
	v_mul_f32_e32 v66, v66, v70
	v_mov_b32_e32 v122, v91
	v_mov_b32_e32 v126, v95
	s_movk_i32 s2, 0xe000
	s_waitcnt vmcnt(0)
	v_lshlrev_b32_e32 v70, 16, v192
	v_mul_f32_e32 v66, v66, v70
	v_bfe_u32 v70, v66, 16, 1
	v_add3_u32 v66, v66, v70, s15
	global_store_short_d16_hi v[142:143], v66, off
	v_mul_f32_e32 v66, v150, v153
	v_fmac_f32_e32 v66, v165, v151
	v_fmac_f32_e32 v66, v149, v152
	v_lshlrev_b32_e32 v70, 16, v193
	v_mul_f32_e32 v66, v66, v70
	v_bfe_u32 v70, v66, 16, 1
	v_add3_u32 v66, v66, v70, s15
	global_store_short_d16_hi v[142:143], v66, off offset:768
	v_pk_add_f32 v[66:67], v[98:99], 0 op_sel_hi:[1,0]
	s_nop 0
	v_pk_add_f32 v[66:67], v[66:67], v[102:103]
	s_nop 0
	v_pk_add_f32 v[66:67], v[66:67], v[106:107]
	s_nop 0
	v_pk_add_f32 v[66:67], v[66:67], v[110:111]
	s_nop 0
	v_pk_add_f32 v[66:67], v[66:67], v[114:115]
	s_nop 0
	v_pk_add_f32 v[66:67], v[66:67], v[118:119]
	s_nop 0
	v_pk_add_f32 v[66:67], v[66:67], v[122:123]
	s_nop 0
	v_pk_add_f32 v[66:67], v[66:67], v[126:127]
	s_nop 0
	v_pk_mul_f32 v[66:67], v[66:67], s[12:13] op_sel_hi:[1,0]
	s_nop 0
	v_fma_f32 v66, -v67, v67, v66
	v_max_f32_e32 v66, 0, v66
	v_add_f32_e32 v66, 0x358637bd, v66
	v_cmp_gt_f32_e32 vcc, s33, v66
	v_mul_f32_e32 v70, 0x4b800000, v66
	v_sub_f32_e32 v67, v141, v67
	v_cndmask_b32_e32 v66, v66, v70, vcc
	v_rsq_f32_e32 v66, v66
	s_nop 0
	v_mul_f32_e32 v70, 0x45800000, v66
	v_cndmask_b32_e32 v66, v66, v70, vcc
	v_mul_f32_e32 v66, v67, v66
	v_fma_f32 v66, v164, v66, v154
	v_mul_f32_e32 v67, 0xbfb8aa3b, v66
	v_exp_f32_e32 v67, v67
	s_nop 0
	v_add_f32_e32 v67, 1.0, v67
	v_rcp_f32_e32 v67, v67
	s_nop 0
	v_mul_f32_e32 v70, v66, v67
	v_add_co_u32_e32 v66, vcc, s2, v138
	s_movk_i32 s2, 0xf000
	s_nop 0
	v_addc_co_u32_e32 v67, vcc, -1, v139, vcc
	v_lshlrev_b32_e32 v71, 16, v194
	v_mul_f32_e32 v70, v70, v71
	v_bfe_u32 v71, v70, 16, 1
	v_add3_u32 v70, v70, v71, s15
	global_store_short_d16_hi v[142:143], v70, off offset:2048
	v_mul_f32_e32 v70, v149, v153
	v_fmac_f32_e32 v70, v150, v151
	v_fmac_f32_e32 v70, v148, v152
	v_mov_b32_e32 v71, v104
	v_mov_b32_e32 v104, v73
	v_lshlrev_b32_e32 v66, 16, v195
	v_mul_f32_e32 v66, v70, v66
	v_bfe_u32 v67, v66, 16, 1
	v_add3_u32 v66, v66, v67, s15
	global_store_short_d16_hi v[142:143], v66, off offset:2816
	v_mov_b32_e32 v66, v68
	v_mov_b32_e32 v67, v100
	v_pk_add_f32 v[66:67], v[66:67], 0 op_sel_hi:[1,0]
	v_mov_b32_e32 v70, v72
	v_pk_add_f32 v[66:67], v[66:67], v[70:71]
	v_mov_b32_e32 v70, v76
	v_mov_b32_e32 v71, v108
	v_pk_add_f32 v[66:67], v[66:67], v[70:71]
	v_mov_b32_e32 v70, v80
	v_mov_b32_e32 v71, v112
	v_pk_add_f32 v[66:67], v[66:67], v[70:71]
	v_mov_b32_e32 v70, v84
	v_mov_b32_e32 v71, v116
	v_pk_add_f32 v[66:67], v[66:67], v[70:71]
	v_mov_b32_e32 v70, v88
	v_mov_b32_e32 v71, v120
	v_pk_add_f32 v[66:67], v[66:67], v[70:71]
	v_mov_b32_e32 v70, v92
	v_mov_b32_e32 v71, v124
	v_pk_add_f32 v[66:67], v[66:67], v[70:71]
	v_mov_b32_e32 v70, v96
	v_mov_b32_e32 v71, v128
	v_pk_add_f32 v[66:67], v[66:67], v[70:71]
	v_mov_b32_e32 v100, v69
	v_pk_mul_f32 v[66:67], v[66:67], s[12:13] op_sel_hi:[1,0]
	v_mov_b32_e32 v108, v77
	v_fma_f32 v66, -v67, v67, v66
	v_max_f32_e32 v66, 0, v66
	v_add_f32_e32 v66, 0x358637bd, v66
	v_cmp_gt_f32_e32 vcc, s33, v66
	v_mul_f32_e32 v68, 0x4b800000, v66
	v_sub_f32_e32 v67, v136, v67
	v_cndmask_b32_e32 v66, v66, v68, vcc
	v_rsq_f32_e32 v66, v66
	v_mov_b32_e32 v112, v81
	v_mov_b32_e32 v116, v85
	v_mov_b32_e32 v120, v89
	v_mul_f32_e32 v68, 0x45800000, v66
	v_cndmask_b32_e32 v66, v66, v68, vcc
	v_mul_f32_e32 v66, v67, v66
	v_fma_f32 v66, v66, v164, v154
	v_mul_f32_e32 v67, 0xbfb8aa3b, v66
	v_exp_f32_e32 v67, v67
	v_add_co_u32_e32 v70, vcc, s2, v138
	s_movk_i32 s2, 0x1000
	v_add_f32_e32 v67, 1.0, v67
	v_rcp_f32_e32 v67, v67
	v_addc_co_u32_e32 v71, vcc, -1, v139, vcc
	v_mov_b32_e32 v124, v93
	v_mul_f32_e32 v66, v66, v67
	v_mov_b32_e32 v128, v97
	v_lshlrev_b32_e32 v67, 16, v196
	v_mul_f32_e32 v66, v66, v67
	v_bfe_u32 v67, v66, 16, 1
	v_add3_u32 v68, v66, v67, s15
	v_add_co_u32_e32 v66, vcc, s2, v142
	s_add_i32 s2, s4, s7
	s_nop 0
	v_addc_co_u32_e32 v67, vcc, 0, v143, vcc
	global_store_short_d16_hi v[66:67], v68, off
	v_mul_f32_e32 v68, v148, v153
	v_fmac_f32_e32 v68, v149, v151
	v_fmac_f32_e32 v68, v147, v152
	s_mul_hi_i32 s3, s2, 0xc00
	s_mulk_i32 s2, 0xc00
	s_add_u32 s2, s50, s2
	s_addc_u32 s3, s51, s3
	v_lshlrev_b32_e32 v70, 16, v197
	v_mul_f32_e32 v68, v68, v70
	v_bfe_u32 v70, v68, 16, 1
	v_add3_u32 v68, v68, v70, s15
	global_store_short_d16_hi v[66:67], v68, off offset:768
	v_pk_add_f32 v[68:69], v[100:101], 0 op_sel_hi:[1,0]
	s_nop 0
	v_pk_add_f32 v[68:69], v[68:69], v[104:105]
	s_nop 0
	v_pk_add_f32 v[68:69], v[68:69], v[108:109]
	s_nop 0
	v_pk_add_f32 v[68:69], v[68:69], v[112:113]
	s_nop 0
	v_pk_add_f32 v[68:69], v[68:69], v[116:117]
	s_nop 0
	v_pk_add_f32 v[68:69], v[68:69], v[120:121]
	s_nop 0
	v_pk_add_f32 v[68:69], v[68:69], v[124:125]
	s_nop 0
	v_pk_add_f32 v[68:69], v[68:69], v[128:129]
	s_nop 0
	v_pk_mul_f32 v[68:69], v[68:69], s[12:13] op_sel_hi:[1,0]
	s_nop 0
	v_fma_f32 v68, -v69, v69, v68
	v_max_f32_e32 v68, 0, v68
	v_add_f32_e32 v68, 0x358637bd, v68
	v_cmp_gt_f32_e32 vcc, s33, v68
	v_mul_f32_e32 v70, 0x4b800000, v68
	v_sub_f32_e32 v69, v137, v69
	v_cndmask_b32_e32 v68, v68, v70, vcc
	v_rsq_f32_e32 v68, v68
	s_nop 0
	v_mul_f32_e32 v70, 0x45800000, v68
	v_cndmask_b32_e32 v68, v68, v70, vcc
	v_mul_f32_e32 v68, v69, v68
	v_fmac_f32_e32 v154, v68, v164
	v_mul_f32_e32 v68, 0xbfb8aa3b, v154
	v_exp_f32_e32 v68, v68
	v_lshlrev_b32_e32 v69, 16, v198
	v_add_f32_e32 v68, 1.0, v68
	v_rcp_f32_e32 v68, v68
	s_nop 0
	v_mul_f32_e32 v68, v154, v68
	v_mul_f32_e32 v68, v68, v69
	v_bfe_u32 v69, v68, 16, 1
	v_add3_u32 v68, v68, v69, s15
	global_store_short_d16_hi v[66:67], v68, off offset:2048
	v_mul_f32_e32 v68, v147, v153
	v_fmac_f32_e32 v68, v148, v151
	v_fmac_f32_e32 v68, v146, v152
	v_lshlrev_b32_e32 v69, 16, v199
	v_mul_f32_e32 v68, v68, v69
	v_bfe_u32 v69, v68, 16, 1
	v_add3_u32 v68, v68, v69, s15
	global_store_short_d16_hi v[66:67], v68, off offset:2816
	v_lshl_add_u64 v[66:67], v[130:131], 2, s[2:3]
	v_add_co_u32_e32 v66, vcc, 0x4e00000, v66
	s_nop 1
	v_addc_co_u32_e32 v67, vcc, 0, v67, vcc
	global_store_dword v[66:67], v147, off
	global_store_dword v[66:67], v146, off offset:1536
.LBB0_861:
	s_or_b64 exec, exec, s[34:35]
	s_and_saveexec_b64 s[12:13], s[36:37]
	s_cbranch_execz .LBB0_852
	s_waitcnt lgkmcnt(7)
	v_mov_b32_e32 v66, v38
	v_mov_b32_e32 v67, v6
	v_mov_b32_e32 v6, v39
	v_pk_add_f32 v[66:67], v[66:67], 0 op_sel_hi:[1,0]
	s_waitcnt lgkmcnt(6)
	v_mov_b32_e32 v68, v34
	v_mov_b32_e32 v69, v2
	v_pk_add_f32 v[6:7], v[6:7], 0 op_sel_hi:[1,0]
	v_mov_b32_e32 v2, v35
	v_pk_add_f32 v[66:67], v[66:67], v[68:69]
	s_waitcnt lgkmcnt(5)
	v_mov_b32_e32 v68, v46
	v_mov_b32_e32 v69, v14
	v_pk_add_f32 v[2:3], v[6:7], v[2:3]
	v_mov_b32_e32 v14, v47
	v_pk_add_f32 v[66:67], v[66:67], v[68:69]
	s_waitcnt lgkmcnt(4)
	v_mov_b32_e32 v68, v42
	v_mov_b32_e32 v69, v10
	v_pk_add_f32 v[2:3], v[2:3], v[14:15]
	v_mov_b32_e32 v10, v43
	v_pk_add_f32 v[66:67], v[66:67], v[68:69]
	s_waitcnt lgkmcnt(3)
	v_mov_b32_e32 v68, v54
	v_mov_b32_e32 v69, v22
	v_pk_add_f32 v[2:3], v[2:3], v[10:11]
	v_mov_b32_e32 v22, v55
	v_pk_add_f32 v[66:67], v[66:67], v[68:69]
	s_waitcnt lgkmcnt(2)
	v_mov_b32_e32 v68, v50
	v_mov_b32_e32 v69, v18
	v_pk_add_f32 v[2:3], v[2:3], v[22:23]
	v_mov_b32_e32 v18, v51
	v_pk_add_f32 v[66:67], v[66:67], v[68:69]
	s_waitcnt lgkmcnt(1)
	v_mov_b32_e32 v68, v62
	v_mov_b32_e32 v69, v30
	v_pk_add_f32 v[2:3], v[2:3], v[18:19]
	v_mov_b32_e32 v30, v63
	v_pk_add_f32 v[66:67], v[66:67], v[68:69]
	v_mov_b32_e32 v69, v26
	v_pk_add_f32 v[2:3], v[2:3], v[30:31]
	s_waitcnt lgkmcnt(0)
	v_mov_b32_e32 v26, v59
	v_pk_add_f32 v[10:11], v[2:3], v[26:27]
	v_mov_b32_e32 v2, v40
	v_mov_b32_e32 v3, v8
	v_pk_add_f32 v[2:3], v[2:3], 0 op_sel_hi:[1,0]
	v_mov_b32_e32 v6, v36
	v_mov_b32_e32 v7, v4
	v_pk_add_f32 v[2:3], v[2:3], v[6:7]
	v_mov_b32_e32 v6, v48
	v_mov_b32_e32 v7, v16
	v_pk_add_f32 v[2:3], v[2:3], v[6:7]
	v_mov_b32_e32 v6, v44
	v_mov_b32_e32 v7, v12
	v_pk_add_f32 v[2:3], v[2:3], v[6:7]
	v_mov_b32_e32 v6, v56
	v_mov_b32_e32 v7, v24
	v_pk_add_f32 v[2:3], v[2:3], v[6:7]
	v_mov_b32_e32 v6, v52
	v_mov_b32_e32 v7, v20
	v_pk_add_f32 v[2:3], v[2:3], v[6:7]
	v_mov_b32_e32 v6, v64
	v_mov_b32_e32 v7, v32
	v_pk_add_f32 v[2:3], v[2:3], v[6:7]
	v_mov_b32_e32 v6, v60
	v_mov_b32_e32 v7, v28
	v_mov_b32_e32 v8, v41
	v_pk_add_f32 v[6:7], v[2:3], v[6:7]
	v_pk_add_f32 v[2:3], v[8:9], 0 op_sel_hi:[1,0]
	v_mov_b32_e32 v4, v37
	v_add_u32_e32 v8, s5, v130
	v_pk_add_f32 v[2:3], v[2:3], v[4:5]
	v_mov_b32_e32 v16, v49
	v_ashrrev_i32_e32 v9, 31, v8
	v_pk_add_f32 v[2:3], v[2:3], v[16:17]
	v_mov_b32_e32 v12, v45
	v_lshlrev_b64 v[8:9], 2, v[8:9]
	v_pk_add_f32 v[2:3], v[2:3], v[12:13]
	v_lshl_add_u64 v[12:13], s[86:87], 0, v[8:9]
	v_lshl_add_u64 v[8:9], s[88:89], 0, v[8:9]
	s_waitcnt vmcnt(10)
	v_mov_b32_e32 v5, v204
	v_mov_b32_e32 v68, v58
	v_mov_b32_e32 v8, v205
	v_pk_add_f32 v[66:67], v[66:67], v[68:69]
	s_mov_b32 s14, 0x3b800000
	v_pk_mul_f32 v[12:13], v[66:67], s[14:15] op_sel_hi:[1,0]
	s_add_i32 s2, s4, s7
	v_fma_f32 v9, -v13, v13, v12
	v_max_f32_e32 v9, 0, v9
	v_add_f32_e32 v9, 0x358637bd, v9
	v_cmp_gt_f32_e32 vcc, s33, v9
	v_mul_f32_e32 v12, 0x4b800000, v9
	s_ashr_i32 s3, s2, 31
	v_cndmask_b32_e32 v9, v9, v12, vcc
	v_rsq_f32_e32 v9, v9
	s_lshl_b64 s[2:3], s[2:3], 12
	s_add_u32 s2, s50, s2
	s_addc_u32 s3, s51, s3
	v_mul_f32_e32 v12, 0x45800000, v9
	v_cndmask_b32_e32 v9, v9, v12, vcc
	v_sub_f32_e32 v12, v132, v13
	v_pk_mul_f32 v[10:11], v[10:11], s[14:15] op_sel_hi:[1,0]
	v_mul_f32_e32 v9, v12, v9
	v_lshl_add_u64 v[12:13], v[130:131], 2, s[2:3]
	s_mov_b32 s2, 0x4ec0000
	v_fma_f32 v10, -v11, v11, v10
	v_add_co_u32_e32 v12, vcc, s2, v12
	v_max_f32_e32 v10, 0, v10
	s_nop 0
	v_addc_co_u32_e32 v13, vcc, 0, v13, vcc
	v_add_f32_e32 v10, 0x358637bd, v10
	v_cmp_gt_f32_e32 vcc, s33, v10
	v_mul_f32_e32 v14, 0x4b800000, v10
	v_pk_mul_f32 v[6:7], v[6:7], s[14:15] op_sel_hi:[1,0]
	v_cndmask_b32_e32 v10, v10, v14, vcc
	v_rsq_f32_e32 v10, v10
	v_fma_f32 v6, -v7, v7, v6
	v_sub_f32_e32 v11, v133, v11
	v_max_f32_e32 v6, 0, v6
	v_mul_f32_e32 v14, 0x45800000, v10
	v_cndmask_b32_e32 v10, v10, v14, vcc
	v_mul_f32_e32 v10, v11, v10
	v_add_f32_e32 v6, 0x358637bd, v6
	v_mov_b32_e32 v24, v57
	v_cmp_gt_f32_e32 vcc, s33, v6
	v_pk_add_f32 v[2:3], v[2:3], v[24:25]
	v_mov_b32_e32 v20, v53
	v_pk_add_f32 v[2:3], v[2:3], v[20:21]
	v_mov_b32_e32 v32, v65
	v_pk_add_f32 v[2:3], v[2:3], v[32:33]
	v_mov_b32_e32 v28, v61
	v_pk_add_f32 v[2:3], v[2:3], v[28:29]
	v_sub_f32_e32 v7, v134, v7
	v_pk_mul_f32 v[2:3], v[2:3], s[14:15] op_sel_hi:[1,0]
	v_ashrrev_i32_e32 v4, 6, v130
	v_fma_f32 v2, -v3, v3, v2
	v_max_f32_e32 v2, 0, v2
	v_add_f32_e32 v2, 0x358637bd, v2
	v_sub_f32_e32 v3, v135, v3
	s_movk_i32 s2, 0xd000
	v_fma_f32 v18, v10, v5, v8
	v_mul_f32_e32 v10, 0x4b800000, v6
	v_cndmask_b32_e32 v6, v6, v10, vcc
	v_rsq_f32_e32 v6, v6
	v_fma_f32 v9, v9, v5, v8
	global_store_dword v[12:13], v9, off
	global_store_dword v[12:13], v18, off offset:1024
	v_mul_f32_e32 v10, 0x45800000, v6
	v_cndmask_b32_e32 v6, v6, v10, vcc
	v_mul_f32_e32 v6, v7, v6
	v_fma_f32 v19, v6, v5, v8
	v_cmp_gt_f32_e32 vcc, s33, v2
	v_mul_f32_e32 v6, 0x4b800000, v2
	global_store_dword v[12:13], v19, off offset:2048
	v_cndmask_b32_e32 v2, v2, v6, vcc
	v_rsq_f32_e32 v2, v2
	v_lshlrev_b64 v[10:11], 1, v[130:131]
	v_lshl_add_u64 v[16:17], s[10:11], 0, v[10:11]
	v_mul_f32_e32 v6, 0x45800000, v2
	v_cndmask_b32_e32 v2, v2, v6, vcc
	v_mul_f32_e32 v2, v3, v2
	v_fmac_f32_e32 v8, v2, v5
	v_add_u32_e32 v2, s6, v4
	v_lshlrev_b32_e32 v4, 7, v2
	v_ashrrev_i32_e32 v3, 31, v2
	v_lshlrev_b64 v[2:3], 16, v[2:3]
	v_ashrrev_i32_e32 v5, 31, v4
	global_store_dword v[12:13], v8, off offset:3072
	v_lshl_add_u64 v[14:15], s[90:91], 0, v[2:3]
	v_lshl_add_u64 v[2:3], v[4:5], 2, s[92:93]
	v_mov_b32_e32 v2, v206
	v_mov_b32_e32 v3, v207
	v_mov_b32_e32 v4, v208
	v_mov_b32_e32 v5, v209
	s_nop 0
	v_mov_b32_e32 v6, v210
	v_fma_f32 v2, v9, v6, v2
	v_lshl_add_u64 v[6:7], s[30:31], 0, v[10:11]
	v_add_co_u32_e32 v12, vcc, s2, v6
	v_mov_b32_e32 v10, v212
	v_mov_b32_e32 v11, v213
	s_nop 0
	v_addc_co_u32_e32 v13, vcc, -1, v7, vcc
	v_mov_b32_e32 v12, v220
	s_movk_i32 s2, 0xe000
	v_fma_f32 v10, v9, v10, v3
	v_fmac_f32_e32 v10, v18, v11
	v_lshlrev_b32_e32 v12, 16, v12
	v_mul_f32_e32 v2, v2, v12
	v_bfe_u32 v12, v2, 16, 1
	v_add3_u32 v2, v2, v12, s15
	global_store_short_d16_hi v[16:17], v2, off offset:1536
	v_add_co_u32_e32 v2, vcc, s2, v6
	s_movk_i32 s2, 0xf000
	s_nop 0
	v_addc_co_u32_e32 v3, vcc, -1, v7, vcc
	v_mov_b32_e32 v2, v221
	v_lshlrev_b32_e32 v2, 16, v2
	v_mul_f32_e32 v2, v10, v2
	v_bfe_u32 v3, v2, 16, 1
	v_add3_u32 v2, v2, v3, s15
	global_store_short_d16_hi v[16:17], v2, off offset:3584
	v_mov_b32_e32 v10, v224
	v_mov_b32_e32 v11, v225
	v_mov_b32_e32 v12, v226
	v_add_co_u32_e32 v2, vcc, s2, v6
	s_movk_i32 s2, 0x1000
	s_nop 0
	v_addc_co_u32_e32 v3, vcc, -1, v7, vcc
	v_mov_b32_e32 v2, v222
	v_fma_f32 v4, v9, v10, v4
	v_fmac_f32_e32 v4, v18, v11
	v_fmac_f32_e32 v4, v19, v12
	v_mov_b32_e32 v10, v228
	v_mov_b32_e32 v11, v229
	v_mov_b32_e32 v12, v230
	v_mov_b32_e32 v13, v231
	v_lshlrev_b32_e32 v2, 16, v2
	v_mul_f32_e32 v2, v4, v2
	v_bfe_u32 v3, v2, 16, 1
	v_add3_u32 v4, v2, v3, s15
	v_add_co_u32_e32 v2, vcc, s2, v16
	v_fmac_f32_e32 v5, v9, v10
	v_addc_co_u32_e32 v3, vcc, 0, v17, vcc
	global_store_short_d16_hi v[2:3], v4, off offset:1536
	v_mov_b32_e32 v4, v223
	v_fmac_f32_e32 v5, v18, v11
	v_fmac_f32_e32 v5, v19, v12
	v_fmac_f32_e32 v5, v8, v13
	v_lshlrev_b32_e32 v4, 16, v4
	v_mul_f32_e32 v4, v5, v4
	v_bfe_u32 v5, v4, 16, 1
	v_add3_u32 v4, v4, v5, s15
	global_store_short_d16_hi v[2:3], v4, off offset:3584
	s_branch .LBB0_852

.LBB0_935:
	s_add_u32 s2, s12, 0xfffc0080
	s_addc_u32 s3, s13, -1
	s_add_i32 s38, 32, 0x10000
	v_add_u32_e32 v152, s38, v145
	ds_read_b128 v[140:143], v152
	ds_read_b128 v[148:151], v152 offset:1024
	ds_read_b128 v[164:167], v152 offset:2048
	ds_read_b128 v[168:171], v152 offset:3072
	s_cmp_eq_u32 vcc_hi, 12
	s_cselect_b32 s3, s31, s3
	s_cselect_b32 s2, s4, s2
	s_cselect_b32 s19, s11, s35
	s_cselect_b32 s18, vcc_lo, s34
	v_lshl_add_u64 v[152:153], s[12:13], 0, v[136:137]
	s_add_i32 m0, s14, 0xc000
	ds_read_b128 v[172:175], v147
	ds_read_b128 v[176:179], v147 offset:1024
	ds_read_b128 v[182:185], v147 offset:2048
	ds_read_b128 v[186:189], v147 offset:3072
	ds_read_b128 v[190:193], v147 offset:4096
	ds_read_b128 v[194:197], v147 offset:5120
	ds_read_b128 v[198:201], v147 offset:6144
	ds_read_b128 v[202:205], v147 offset:7168
	global_load_lds_dwordx4 v[152:153], off
	v_lshl_add_u64 v[152:153], s[12:13], 0, v[138:139]
	s_add_i32 m0, s14, 0xe000
	s_nop 0
	global_load_lds_dwordx4 v[152:153], off
	s_waitcnt lgkmcnt(8)
	s_barrier
	s_waitcnt lgkmcnt(0)
	s_setprio 1
	s_waitcnt lgkmcnt(0)
	v_mfma_f32_16x16x32_bf16 v[126:129], v[140:143], v[172:175], v[126:129]
	v_mfma_f32_16x16x32_bf16 v[122:125], v[164:167], v[172:175], v[122:125]
	v_mfma_f32_16x16x32_bf16 v[110:113], v[140:143], v[182:185], v[110:113]
	v_mfma_f32_16x16x32_bf16 v[106:109], v[164:167], v[182:185], v[106:109]
	v_mfma_f32_16x16x32_bf16 v[94:97], v[140:143], v[190:193], v[94:97]
	v_mfma_f32_16x16x32_bf16 v[90:93], v[164:167], v[190:193], v[90:93]
	v_mfma_f32_16x16x32_bf16 v[78:81], v[140:143], v[198:201], v[78:81]
	v_mfma_f32_16x16x32_bf16 v[74:77], v[164:167], v[198:201], v[74:77]
	v_mfma_f32_16x16x32_bf16 v[126:129], v[148:151], v[176:179], v[126:129]
	v_mfma_f32_16x16x32_bf16 v[122:125], v[168:171], v[176:179], v[122:125]
	v_mfma_f32_16x16x32_bf16 v[110:113], v[148:151], v[186:189], v[110:113]
	v_mfma_f32_16x16x32_bf16 v[106:109], v[168:171], v[186:189], v[106:109]
	v_mfma_f32_16x16x32_bf16 v[94:97], v[148:151], v[194:197], v[94:97]
	v_mfma_f32_16x16x32_bf16 v[90:93], v[168:171], v[194:197], v[90:93]
	v_mfma_f32_16x16x32_bf16 v[78:81], v[148:151], v[202:205], v[78:81]
	v_mfma_f32_16x16x32_bf16 v[74:77], v[168:171], v[202:205], v[74:77]
	s_setprio 0
	s_barrier
	s_add_i32 s24, 32, 0x14000
	v_add_u32_e32 v152, s24, v145
	s_add_i32 s38, s38, s7
	ds_read_b128 v[206:209], v152
	ds_read_b128 v[210:213], v152 offset:1024
	ds_read_b128 v[214:217], v152 offset:2048
	ds_read_b128 v[218:221], v152 offset:3072
	v_lshl_add_u64 v[152:153], s[18:19], 0, v[154:155]
	s_mov_b32 m0, s38
	v_lshl_add_u64 v[222:223], s[18:19], 0, v[130:131]
	global_load_lds_dwordx4 v[152:153], off
	s_add_i32 m0, s38, 0x2000
	s_nop 0
	global_load_lds_dwordx4 v[222:223], off
	s_barrier
	s_waitcnt lgkmcnt(0)
	s_setprio 1
	s_waitcnt lgkmcnt(0)
	v_mfma_f32_16x16x32_bf16 v[118:121], v[206:209], v[172:175], v[118:121]
	v_mfma_f32_16x16x32_bf16 v[114:117], v[214:217], v[172:175], v[114:117]
	v_mfma_f32_16x16x32_bf16 v[102:105], v[206:209], v[182:185], v[102:105]
	v_mfma_f32_16x16x32_bf16 v[98:101], v[214:217], v[182:185], v[98:101]
	v_mfma_f32_16x16x32_bf16 v[86:89], v[206:209], v[190:193], v[86:89]
	v_mfma_f32_16x16x32_bf16 v[82:85], v[214:217], v[190:193], v[82:85]
	v_mfma_f32_16x16x32_bf16 v[70:73], v[206:209], v[198:201], v[70:73]
	v_mfma_f32_16x16x32_bf16 v[66:69], v[214:217], v[198:201], v[66:69]
	v_mfma_f32_16x16x32_bf16 v[118:121], v[210:213], v[176:179], v[118:121]
	v_mfma_f32_16x16x32_bf16 v[114:117], v[218:221], v[176:179], v[114:117]
	v_mfma_f32_16x16x32_bf16 v[102:105], v[210:213], v[186:189], v[102:105]
	v_mfma_f32_16x16x32_bf16 v[98:101], v[218:221], v[186:189], v[98:101]
	v_mfma_f32_16x16x32_bf16 v[86:89], v[210:213], v[194:197], v[86:89]
	v_mfma_f32_16x16x32_bf16 v[82:85], v[218:221], v[194:197], v[82:85]
	v_mfma_f32_16x16x32_bf16 v[70:73], v[210:213], v[202:205], v[70:73]
	v_mfma_f32_16x16x32_bf16 v[66:69], v[218:221], v[202:205], v[66:69]
	s_setprio 0
	s_mov_b32 m0, s14
	v_lshl_add_u64 v[224:225], s[2:3], 0, v[134:135]
	s_barrier
	ds_read_b128 v[172:175], v147 offset:16384
	ds_read_b128 v[176:179], v147 offset:17408
	ds_read_b128 v[182:185], v147 offset:18432
	ds_read_b128 v[186:189], v147 offset:19456
	ds_read_b128 v[190:193], v147 offset:20480
	ds_read_b128 v[194:197], v147 offset:21504
	ds_read_b128 v[198:201], v147 offset:22528
	ds_read_b128 v[202:205], v147 offset:23552
	global_load_lds_dwordx4 v[224:225], off
	v_lshl_add_u64 v[226:227], s[2:3], 0, v[132:133]
	s_mov_b32 m0, s20
	s_nop 0
	global_load_lds_dwordx4 v[226:227], off
	s_barrier
	s_waitcnt lgkmcnt(0)
	s_setprio 1
	s_waitcnt lgkmcnt(0)
	v_mfma_f32_16x16x32_bf16 v[62:65], v[140:143], v[172:175], v[62:65]
	v_mfma_f32_16x16x32_bf16 v[58:61], v[164:167], v[172:175], v[58:61]
	v_mfma_f32_16x16x32_bf16 v[46:49], v[140:143], v[182:185], v[46:49]
	v_mfma_f32_16x16x32_bf16 v[42:45], v[164:167], v[182:185], v[42:45]
	v_mfma_f32_16x16x32_bf16 v[30:33], v[140:143], v[190:193], v[30:33]
	v_mfma_f32_16x16x32_bf16 v[26:29], v[164:167], v[190:193], v[26:29]
	v_mfma_f32_16x16x32_bf16 v[14:17], v[140:143], v[198:201], v[14:17]
	v_mfma_f32_16x16x32_bf16 v[10:13], v[164:167], v[198:201], v[10:13]
	v_mfma_f32_16x16x32_bf16 v[62:65], v[148:151], v[176:179], v[62:65]
	v_mfma_f32_16x16x32_bf16 v[58:61], v[168:171], v[176:179], v[58:61]
	v_mfma_f32_16x16x32_bf16 v[46:49], v[148:151], v[186:189], v[46:49]
	v_mfma_f32_16x16x32_bf16 v[42:45], v[168:171], v[186:189], v[42:45]
	v_mfma_f32_16x16x32_bf16 v[30:33], v[148:151], v[194:197], v[30:33]
	v_mfma_f32_16x16x32_bf16 v[26:29], v[168:171], v[194:197], v[26:29]
	v_mfma_f32_16x16x32_bf16 v[14:17], v[148:151], v[202:205], v[14:17]
	v_mfma_f32_16x16x32_bf16 v[10:13], v[168:171], v[202:205], v[10:13]
	s_setprio 0
	s_barrier
	s_add_u32 s38, s18, 0x40000
	s_addc_u32 s39, s19, 0
	s_add_i32 s24, s24, s7
	v_lshl_add_u64 v[140:141], s[38:39], 0, v[154:155]
	s_mov_b32 m0, s24
	s_nop 0
	global_load_lds_dwordx4 v[140:141], off
	v_lshl_add_u64 v[140:141], s[38:39], 0, v[130:131]
	s_add_i32 m0, s24, 0x2000
	s_nop 0
	global_load_lds_dwordx4 v[140:141], off
	s_waitcnt vmcnt(6)
	s_barrier
	s_setprio 1
	v_mfma_f32_16x16x32_bf16 v[54:57], v[206:209], v[172:175], v[54:57]
	v_mfma_f32_16x16x32_bf16 v[50:53], v[214:217], v[172:175], v[50:53]
	v_mfma_f32_16x16x32_bf16 v[38:41], v[206:209], v[182:185], v[38:41]
	v_mfma_f32_16x16x32_bf16 v[34:37], v[214:217], v[182:185], v[34:37]
	v_mfma_f32_16x16x32_bf16 v[22:25], v[206:209], v[190:193], v[22:25]
	v_mfma_f32_16x16x32_bf16 v[18:21], v[214:217], v[190:193], v[18:21]
	v_mfma_f32_16x16x32_bf16 v[6:9], v[206:209], v[198:201], v[6:9]
	v_mfma_f32_16x16x32_bf16 v[2:5], v[214:217], v[198:201], v[2:5]
	v_mfma_f32_16x16x32_bf16 v[54:57], v[210:213], v[176:179], v[54:57]
	v_mfma_f32_16x16x32_bf16 v[50:53], v[218:221], v[176:179], v[50:53]
	v_mfma_f32_16x16x32_bf16 v[38:41], v[210:213], v[186:189], v[38:41]
	v_mfma_f32_16x16x32_bf16 v[34:37], v[218:221], v[186:189], v[34:37]
	v_mfma_f32_16x16x32_bf16 v[22:25], v[210:213], v[194:197], v[22:25]
	v_mfma_f32_16x16x32_bf16 v[18:21], v[218:221], v[194:197], v[18:21]
	v_mfma_f32_16x16x32_bf16 v[6:9], v[210:213], v[202:205], v[6:9]
	v_mfma_f32_16x16x32_bf16 v[2:5], v[218:221], v[202:205], v[2:5]
	s_setprio 0
	s_add_i32 s24, 32, 0x18000
	v_add_u32_e32 v168, s24, v145
	s_barrier
	ds_read_b128 v[140:143], v168
	ds_read_b128 v[148:151], v168 offset:1024
	ds_read_b128 v[164:167], v168 offset:2048
	ds_read_b128 v[168:171], v168 offset:3072
	s_add_u32 s2, s2, 0x40000
	s_addc_u32 s3, s3, 0
	s_mov_b32 m0, s21
	v_lshl_add_u64 v[206:207], s[2:3], 0, v[134:135]
	ds_read_b128 v[172:175], v147 offset:32768
	ds_read_b128 v[176:179], v147 offset:33792
	ds_read_b128 v[182:185], v147 offset:34816
	ds_read_b128 v[186:189], v147 offset:35840
	ds_read_b128 v[190:193], v147 offset:36864
	ds_read_b128 v[194:197], v147 offset:37888
	ds_read_b128 v[198:201], v147 offset:38912
	ds_read_b128 v[202:205], v147 offset:39936
	global_load_lds_dwordx4 v[206:207], off
	v_lshl_add_u64 v[206:207], s[2:3], 0, v[132:133]
	s_mov_b32 m0, s22
	s_nop 0
	global_load_lds_dwordx4 v[206:207], off
	s_waitcnt lgkmcnt(8)
	s_barrier
	s_waitcnt lgkmcnt(0)
	s_setprio 1
	s_waitcnt lgkmcnt(0)
	v_mfma_f32_16x16x32_bf16 v[126:129], v[140:143], v[172:175], v[126:129]
	v_mfma_f32_16x16x32_bf16 v[122:125], v[164:167], v[172:175], v[122:125]
	v_mfma_f32_16x16x32_bf16 v[110:113], v[140:143], v[182:185], v[110:113]
	v_mfma_f32_16x16x32_bf16 v[106:109], v[164:167], v[182:185], v[106:109]
	v_mfma_f32_16x16x32_bf16 v[94:97], v[140:143], v[190:193], v[94:97]
	v_mfma_f32_16x16x32_bf16 v[90:93], v[164:167], v[190:193], v[90:93]
	v_mfma_f32_16x16x32_bf16 v[78:81], v[140:143], v[198:201], v[78:81]
	v_mfma_f32_16x16x32_bf16 v[74:77], v[164:167], v[198:201], v[74:77]
	v_mfma_f32_16x16x32_bf16 v[126:129], v[148:151], v[176:179], v[126:129]
	v_mfma_f32_16x16x32_bf16 v[122:125], v[168:171], v[176:179], v[122:125]
	v_mfma_f32_16x16x32_bf16 v[110:113], v[148:151], v[186:189], v[110:113]
	v_mfma_f32_16x16x32_bf16 v[106:109], v[168:171], v[186:189], v[106:109]
	v_mfma_f32_16x16x32_bf16 v[94:97], v[148:151], v[194:197], v[94:97]
	v_mfma_f32_16x16x32_bf16 v[90:93], v[168:171], v[194:197], v[90:93]
	v_mfma_f32_16x16x32_bf16 v[78:81], v[148:151], v[202:205], v[78:81]
	v_mfma_f32_16x16x32_bf16 v[74:77], v[168:171], v[202:205], v[74:77]
	s_setprio 0
	s_barrier
	s_add_i32 s38, 32, 0x1c000
	s_add_i32 s2, s24, s7
	v_add_u32_e32 v218, s38, v145
	v_lshl_add_u64 v[152:153], v[152:153], 0, s[44:45]
	s_mov_b32 m0, s2
	ds_read_b128 v[206:209], v218
	ds_read_b128 v[210:213], v218 offset:1024
	ds_read_b128 v[214:217], v218 offset:2048
	ds_read_b128 v[218:221], v218 offset:3072
	global_load_lds_dwordx4 v[152:153], off
	v_lshl_add_u64 v[152:153], v[222:223], 0, s[44:45]
	s_add_i32 m0, s2, 0x2000
	s_nop 0
	global_load_lds_dwordx4 v[152:153], off
	s_barrier
	s_waitcnt lgkmcnt(0)
	s_setprio 1
	s_waitcnt lgkmcnt(0)
	v_mfma_f32_16x16x32_bf16 v[118:121], v[206:209], v[172:175], v[118:121]
	v_mfma_f32_16x16x32_bf16 v[114:117], v[214:217], v[172:175], v[114:117]
	v_mfma_f32_16x16x32_bf16 v[102:105], v[206:209], v[182:185], v[102:105]
	v_mfma_f32_16x16x32_bf16 v[98:101], v[214:217], v[182:185], v[98:101]
	v_mfma_f32_16x16x32_bf16 v[86:89], v[206:209], v[190:193], v[86:89]
	v_mfma_f32_16x16x32_bf16 v[82:85], v[214:217], v[190:193], v[82:85]
	v_mfma_f32_16x16x32_bf16 v[70:73], v[206:209], v[198:201], v[70:73]
	v_mfma_f32_16x16x32_bf16 v[66:69], v[214:217], v[198:201], v[66:69]
	v_mfma_f32_16x16x32_bf16 v[118:121], v[210:213], v[176:179], v[118:121]
	v_mfma_f32_16x16x32_bf16 v[114:117], v[218:221], v[176:179], v[114:117]
	v_mfma_f32_16x16x32_bf16 v[102:105], v[210:213], v[186:189], v[102:105]
	v_mfma_f32_16x16x32_bf16 v[98:101], v[218:221], v[186:189], v[98:101]
	v_mfma_f32_16x16x32_bf16 v[86:89], v[210:213], v[194:197], v[86:89]
	v_mfma_f32_16x16x32_bf16 v[82:85], v[218:221], v[194:197], v[82:85]
	v_mfma_f32_16x16x32_bf16 v[70:73], v[210:213], v[202:205], v[70:73]
	v_mfma_f32_16x16x32_bf16 v[66:69], v[218:221], v[202:205], v[66:69]
	s_setprio 0
	s_mov_b32 m0, s23
	v_lshl_add_u64 v[152:153], v[224:225], 0, s[44:45]
	s_barrier
	ds_read_b128 v[172:175], v147 offset:49152
	ds_read_b128 v[176:179], v147 offset:50176
	ds_read_b128 v[182:185], v147 offset:51200
	ds_read_b128 v[186:189], v147 offset:52224
	ds_read_b128 v[190:193], v147 offset:53248
	ds_read_b128 v[194:197], v147 offset:54272
	ds_read_b128 v[198:201], v147 offset:55296
	ds_read_b128 v[202:205], v147 offset:56320
	global_load_lds_dwordx4 v[152:153], off
	v_lshl_add_u64 v[152:153], v[226:227], 0, s[44:45]
	s_mov_b32 m0, s28
	s_nop 0
	global_load_lds_dwordx4 v[152:153], off
	s_barrier
	s_waitcnt lgkmcnt(0)
	s_setprio 1
	s_waitcnt lgkmcnt(0)
	v_mfma_f32_16x16x32_bf16 v[62:65], v[140:143], v[172:175], v[62:65]
	v_mfma_f32_16x16x32_bf16 v[58:61], v[164:167], v[172:175], v[58:61]
	v_mfma_f32_16x16x32_bf16 v[46:49], v[140:143], v[182:185], v[46:49]
	v_mfma_f32_16x16x32_bf16 v[42:45], v[164:167], v[182:185], v[42:45]
	v_mfma_f32_16x16x32_bf16 v[30:33], v[140:143], v[190:193], v[30:33]
	v_mfma_f32_16x16x32_bf16 v[26:29], v[164:167], v[190:193], v[26:29]
	v_mfma_f32_16x16x32_bf16 v[14:17], v[140:143], v[198:201], v[14:17]
	v_mfma_f32_16x16x32_bf16 v[10:13], v[164:167], v[198:201], v[10:13]
	v_mfma_f32_16x16x32_bf16 v[62:65], v[148:151], v[176:179], v[62:65]
	v_mfma_f32_16x16x32_bf16 v[58:61], v[168:171], v[176:179], v[58:61]
	v_mfma_f32_16x16x32_bf16 v[46:49], v[148:151], v[186:189], v[46:49]
	v_mfma_f32_16x16x32_bf16 v[42:45], v[168:171], v[186:189], v[42:45]
	v_mfma_f32_16x16x32_bf16 v[30:33], v[148:151], v[194:197], v[30:33]
	v_mfma_f32_16x16x32_bf16 v[26:29], v[168:171], v[194:197], v[26:29]
	v_mfma_f32_16x16x32_bf16 v[14:17], v[148:151], v[202:205], v[14:17]
	v_mfma_f32_16x16x32_bf16 v[10:13], v[168:171], v[202:205], v[10:13]
	s_setprio 0
	s_barrier
	s_add_u32 s2, s18, 0x40080
	s_addc_u32 s3, s19, 0
	s_add_i32 s18, s38, s7
	v_lshl_add_u64 v[140:141], s[2:3], 0, v[154:155]
	s_mov_b32 m0, s18
	s_nop 0
	global_load_lds_dwordx4 v[140:141], off
	v_lshl_add_u64 v[140:141], s[2:3], 0, v[130:131]
	s_add_i32 m0, s18, 0x2000
	s_nop 0
	global_load_lds_dwordx4 v[140:141], off
	s_waitcnt vmcnt(6)
	s_barrier
	s_setprio 1
	v_mfma_f32_16x16x32_bf16 v[54:57], v[206:209], v[172:175], v[54:57]
	v_mfma_f32_16x16x32_bf16 v[50:53], v[214:217], v[172:175], v[50:53]
	v_mfma_f32_16x16x32_bf16 v[38:41], v[206:209], v[182:185], v[38:41]
	v_mfma_f32_16x16x32_bf16 v[34:37], v[214:217], v[182:185], v[34:37]
	v_mfma_f32_16x16x32_bf16 v[22:25], v[206:209], v[190:193], v[22:25]
	v_mfma_f32_16x16x32_bf16 v[18:21], v[214:217], v[190:193], v[18:21]
	v_mfma_f32_16x16x32_bf16 v[6:9], v[206:209], v[198:201], v[6:9]
	v_mfma_f32_16x16x32_bf16 v[2:5], v[214:217], v[198:201], v[2:5]
	v_mfma_f32_16x16x32_bf16 v[54:57], v[210:213], v[176:179], v[54:57]
	v_mfma_f32_16x16x32_bf16 v[50:53], v[218:221], v[176:179], v[50:53]
	v_mfma_f32_16x16x32_bf16 v[38:41], v[210:213], v[186:189], v[38:41]
	v_mfma_f32_16x16x32_bf16 v[34:37], v[218:221], v[186:189], v[34:37]
	v_mfma_f32_16x16x32_bf16 v[22:25], v[210:213], v[194:197], v[22:25]
	v_mfma_f32_16x16x32_bf16 v[18:21], v[218:221], v[194:197], v[18:21]
	v_mfma_f32_16x16x32_bf16 v[6:9], v[210:213], v[202:205], v[6:9]
	v_mfma_f32_16x16x32_bf16 v[2:5], v[218:221], v[202:205], v[2:5]
	s_setprio 0
	s_add_i32 vcc_hi, vcc_hi, 2
	s_add_u32 s12, s12, 0x100
	s_addc_u32 s13, s13, 0
	s_add_u32 s34, s34, 0x100
	s_addc_u32 s35, s35, 0
	s_cmp_gt_u32 vcc_hi, 13
	s_barrier
	s_cbranch_scc0 .LBB0_935
	v_lshl_add_u32 v142, s36, 8, v144
	v_ashrrev_i32_e32 v143, 31, v142
	v_lshl_or_b32 v140, s37, 8, v146
	v_lshlrev_b64 v[150:151], 11, v[142:143]
	v_ashrrev_i32_e32 v141, 31, v140
	v_lshl_add_u64 v[150:151], s[58:59], 0, v[150:151]
	v_lshl_add_u64 v[164:165], v[140:141], 1, v[150:151]
	v_mov_b64_e32 v[238:239], v[164:165]
	global_load_dwordx4 v[150:153], v[164:165], off
	s_nop 0
	global_load_dwordx4 v[164:167], v[164:165], off offset:256
	v_add_co_u32_e32 v240, vcc, 0x8000, v238
	s_nop 1
	v_addc_co_u32_e32 v241, vcc, 0, v239, vcc
	global_load_dwordx4 v[182:185], v[240:241], off
	global_load_dwordx4 v[186:189], v[240:241], off offset:256
	v_add_co_u32_e32 v240, vcc, 0x10000, v238
	s_nop 1
	v_addc_co_u32_e32 v241, vcc, 0, v239, vcc
	global_load_dwordx4 v[190:193], v[240:241], off
	global_load_dwordx4 v[194:197], v[240:241], off offset:256
	v_add_co_u32_e32 v240, vcc, 0x18000, v238
	s_nop 1
	v_addc_co_u32_e32 v241, vcc, 0, v239, vcc
	global_load_dwordx4 v[198:201], v[240:241], off
	global_load_dwordx4 v[202:205], v[240:241], off offset:256
	v_add_co_u32_e32 v240, vcc, 0x40000, v238
	s_nop 1
	v_addc_co_u32_e32 v241, vcc, 0, v239, vcc
	global_load_dwordx4 v[206:209], v[240:241], off
	global_load_dwordx4 v[210:213], v[240:241], off offset:256
	v_add_co_u32_e32 v240, vcc, 0x48000, v238
	s_nop 1
	v_addc_co_u32_e32 v241, vcc, 0, v239, vcc
	global_load_dwordx4 v[214:217], v[240:241], off
	global_load_dwordx4 v[218:221], v[240:241], off offset:256
	v_add_co_u32_e32 v240, vcc, 0x50000, v238
	s_nop 1
	v_addc_co_u32_e32 v241, vcc, 0, v239, vcc
	global_load_dwordx4 v[222:225], v[240:241], off
	global_load_dwordx4 v[226:229], v[240:241], off offset:256
	v_add_co_u32_e32 v240, vcc, 0x58000, v238
	s_nop 1
	v_addc_co_u32_e32 v241, vcc, 0, v239, vcc
	global_load_dwordx4 v[230:233], v[240:241], off
	global_load_dwordx4 v[234:237], v[240:241], off offset:256
	v_lshlrev_b32_e32 v148, 1, v140
	s_waitcnt vmcnt(14)
	v_lshlrev_b32_e32 v149, 16, v150
	v_lshlrev_b32_e32 v171, 16, v164
	v_and_b32_e32 v164, 0xffff0000, v164
	v_and_b32_e32 v150, 0xffff0000, v150
	v_lshlrev_b32_e32 v168, 16, v151
	v_and_b32_e32 v151, 0xffff0000, v151
	v_lshlrev_b32_e32 v173, 16, v166
	v_and_b32_e32 v166, 0xffff0000, v166
	v_lshlrev_b32_e32 v174, 16, v167
	v_and_b32_e32 v167, 0xffff0000, v167
	v_add_f32_e32 v118, v118, v171
	v_add_f32_e32 v119, v119, v164
	v_lshlrev_b32_e32 v172, 16, v165
	v_add_f32_e32 v126, v126, v149
	v_add_f32_e32 v149, v114, v173
	v_add_f32_e32 v114, v127, v150
	v_add_f32_e32 v127, v115, v166
	v_add_f32_e32 v115, v128, v168
	v_add_f32_e32 v128, v116, v174
	v_add_f32_e32 v116, v129, v151
	v_add_f32_e32 v129, v117, v167
	v_mul_f32_e32 v117, v118, v118
	v_mul_f32_e32 v150, v119, v119
	v_add_f32_e32 v120, v120, v172
	v_fmac_f32_e32 v117, v126, v126
	v_fmac_f32_e32 v150, v114, v114
	v_and_b32_e32 v165, 0xffff0000, v165
	v_add_f32_e32 v117, v117, v150
	v_mul_f32_e32 v150, v120, v120
	v_add_f32_e32 v121, v121, v165
	v_fmac_f32_e32 v150, v115, v115
	v_add_f32_e32 v117, v150, v117
	v_mul_f32_e32 v150, v121, v121
	v_lshlrev_b32_e32 v169, 16, v152
	v_fmac_f32_e32 v150, v116, v116
	v_add_f32_e32 v122, v122, v169
	v_add_f32_e32 v117, v150, v117
	v_mul_f32_e32 v150, v149, v149
	v_and_b32_e32 v152, 0xffff0000, v152
	v_fmac_f32_e32 v150, v122, v122
	v_add_f32_e32 v123, v123, v152
	v_add_f32_e32 v117, v150, v117
	v_mul_f32_e32 v150, v127, v127
	v_lshlrev_b32_e32 v170, 16, v153
	v_fmac_f32_e32 v150, v123, v123
	v_add_f32_e32 v124, v124, v170
	v_add_f32_e32 v117, v150, v117
	v_mul_f32_e32 v150, v128, v128
	v_and_b32_e32 v153, 0xffff0000, v153
	v_fmac_f32_e32 v150, v124, v124
	v_add_f32_e32 v125, v125, v153
	v_add_f32_e32 v117, v150, v117
	v_mul_f32_e32 v150, v129, v129
	v_fmac_f32_e32 v150, v125, v125
	v_lshl_add_u32 v151, v142, 11, v148
	v_cvt_pk_bf16_f32 v114, v126, v114
	v_cvt_pk_bf16_f32 v115, v115, v116
	v_add_f32_e32 v150, v150, v117
	v_cvt_pk_bf16_f32 v116, v122, v123
	v_cvt_pk_bf16_f32 v117, v124, v125
	buffer_store_dwordx4 v[114:117], v151, s[64:67], 0 offen sc1
	s_nop 1
	v_cvt_pk_bf16_f32 v114, v118, v119
	v_cvt_pk_bf16_f32 v115, v120, v121
	v_cvt_pk_bf16_f32 v116, v149, v127
	v_cvt_pk_bf16_f32 v117, v128, v129
	buffer_store_dwordx4 v[114:117], v151, s[64:67], 0 offen offset:256 sc1
	s_nop 1
	v_and_b32_e32 v115, 64, v181
	v_xor_b32_e32 v114, 16, v181
	v_add_u32_e32 v115, 64, v115
	v_cmp_lt_i32_e32 vcc, v114, v115
	v_xor_b32_e32 v117, 32, v181
	s_nop 0
	v_cndmask_b32_e32 v114, v181, v114, vcc
	v_lshlrev_b32_e32 v116, 2, v114
	ds_bpermute_b32 v114, v116, v150
	v_cmp_lt_i32_e32 vcc, v117, v115
	s_waitcnt lgkmcnt(0)
	v_add_f32_e32 v114, v150, v114
	v_cndmask_b32_e32 v115, v181, v117, vcc
	v_lshlrev_b32_e32 v117, 2, v115
	ds_bpermute_b32 v115, v117, v114
	s_and_saveexec_b64 s[2:3], s[40:41]
	s_cbranch_execz .LBB0_938
	v_lshl_add_u64 v[118:119], v[142:143], 2, s[0:1]
	s_waitcnt lgkmcnt(0)
	v_add_f32_e32 v114, v114, v115
	global_atomic_add_f32 v[118:119], v114, off
.LBB0_938:
	s_or_b64 exec, exec, s[2:3]
	v_or_b32_e32 v114, 16, v142
	s_waitcnt lgkmcnt(0)
	v_ashrrev_i32_e32 v115, 31, v114
	v_lshlrev_b64 v[118:119], 11, v[114:115]
	v_lshl_add_u64 v[118:119], s[58:59], 0, v[118:119]
	v_lshl_add_u64 v[122:123], v[140:141], 1, v[118:119]
	s_waitcnt vmcnt(15)
	v_mov_b64_e32 v[118:119], v[182:183]
	v_mov_b64_e32 v[120:121], v[184:185]
	s_nop 0
	v_mov_b64_e32 v[122:123], v[186:187]
	v_mov_b64_e32 v[124:125], v[188:189]
	v_lshlrev_b32_e32 v126, 16, v118
	v_and_b32_e32 v118, 0xffff0000, v118
	v_lshlrev_b32_e32 v143, 16, v122
	v_and_b32_e32 v122, 0xffff0000, v122
	v_lshlrev_b32_e32 v127, 16, v119
	v_lshlrev_b32_e32 v128, 16, v120
	v_lshlrev_b32_e32 v150, 16, v124
	v_lshlrev_b32_e32 v151, 16, v125
	v_add_f32_e32 v110, v110, v126
	v_add_f32_e32 v126, v102, v143
	v_add_f32_e32 v102, v111, v118
	v_add_f32_e32 v111, v103, v122
	v_lshlrev_b32_e32 v149, 16, v123
	v_add_f32_e32 v106, v106, v128
	v_add_f32_e32 v128, v98, v150
	v_add_f32_e32 v103, v112, v127
	v_add_f32_e32 v112, v100, v151
	v_mul_f32_e32 v98, v126, v126
	v_mul_f32_e32 v100, v111, v111
	v_add_f32_e32 v104, v104, v149
	v_fmac_f32_e32 v98, v110, v110
	v_fmac_f32_e32 v100, v102, v102
	v_and_b32_e32 v123, 0xffff0000, v123
	v_add_f32_e32 v98, v98, v100
	v_mul_f32_e32 v100, v104, v104
	v_and_b32_e32 v119, 0xffff0000, v119
	v_add_f32_e32 v105, v105, v123
	v_fmac_f32_e32 v100, v103, v103
	v_add_f32_e32 v113, v113, v119
	v_add_f32_e32 v98, v100, v98
	v_mul_f32_e32 v100, v105, v105
	v_fmac_f32_e32 v100, v113, v113
	v_and_b32_e32 v124, 0xffff0000, v124
	v_add_f32_e32 v98, v100, v98
	v_mul_f32_e32 v100, v128, v128
	v_and_b32_e32 v120, 0xffff0000, v120
	v_add_f32_e32 v99, v99, v124
	v_fmac_f32_e32 v100, v106, v106
	v_add_f32_e32 v107, v107, v120
	v_add_f32_e32 v98, v100, v98
	v_mul_f32_e32 v100, v99, v99
	v_lshlrev_b32_e32 v129, 16, v121
	v_fmac_f32_e32 v100, v107, v107
	v_and_b32_e32 v125, 0xffff0000, v125
	v_add_f32_e32 v108, v108, v129
	v_add_f32_e32 v98, v100, v98
	v_mul_f32_e32 v100, v112, v112
	v_and_b32_e32 v121, 0xffff0000, v121
	v_add_f32_e32 v118, v101, v125
	v_fmac_f32_e32 v100, v108, v108
	v_add_f32_e32 v109, v109, v121
	v_add_f32_e32 v98, v100, v98
	v_mul_f32_e32 v100, v118, v118
	v_fmac_f32_e32 v100, v109, v109
	v_add_f32_e32 v98, v100, v98
	v_lshl_add_u32 v119, v114, 11, v148
	v_cvt_pk_bf16_f32 v100, v110, v102
	v_cvt_pk_bf16_f32 v101, v103, v113
	v_cvt_pk_bf16_f32 v102, v106, v107
	v_cvt_pk_bf16_f32 v103, v108, v109
	buffer_store_dwordx4 v[100:103], v119, s[64:67], 0 offen sc1
	s_nop 1
	v_cvt_pk_bf16_f32 v100, v126, v111
	v_cvt_pk_bf16_f32 v101, v104, v105
	v_cvt_pk_bf16_f32 v102, v128, v99
	ds_bpermute_b32 v99, v116, v98
	v_cvt_pk_bf16_f32 v103, v112, v118
	buffer_store_dwordx4 v[100:103], v119, s[64:67], 0 offen offset:256 sc1
	s_waitcnt lgkmcnt(0)
	v_add_f32_e32 v98, v98, v99
	ds_bpermute_b32 v99, v117, v98
	s_and_saveexec_b64 s[2:3], s[40:41]
	s_cbranch_execz .LBB0_940
	v_lshl_add_u64 v[100:101], v[114:115], 2, s[0:1]
	s_waitcnt lgkmcnt(0)
	v_add_f32_e32 v98, v98, v99
	global_atomic_add_f32 v[100:101], v98, off
.LBB0_940:
	s_or_b64 exec, exec, s[2:3]
	v_or_b32_e32 v98, 32, v142
	s_waitcnt lgkmcnt(0)
	v_ashrrev_i32_e32 v99, 31, v98
	v_lshlrev_b64 v[100:101], 11, v[98:99]
	v_lshl_add_u64 v[100:101], s[58:59], 0, v[100:101]
	v_lshl_add_u64 v[104:105], v[140:141], 1, v[100:101]
	s_waitcnt vmcnt(16)
	v_mov_b64_e32 v[100:101], v[190:191]
	v_mov_b64_e32 v[102:103], v[192:193]
	s_nop 0
	v_mov_b64_e32 v[104:105], v[194:195]
	v_mov_b64_e32 v[106:107], v[196:197]
	v_lshlrev_b32_e32 v108, 16, v100
	v_and_b32_e32 v100, 0xffff0000, v100
	v_lshlrev_b32_e32 v112, 16, v104
	v_and_b32_e32 v104, 0xffff0000, v104
	v_lshlrev_b32_e32 v109, 16, v101
	v_lshlrev_b32_e32 v110, 16, v102
	v_lshlrev_b32_e32 v114, 16, v106
	v_lshlrev_b32_e32 v115, 16, v107
	v_add_f32_e32 v94, v94, v108
	v_add_f32_e32 v108, v86, v112
	v_add_f32_e32 v86, v95, v100
	v_add_f32_e32 v95, v87, v104
	v_lshlrev_b32_e32 v113, 16, v105
	v_add_f32_e32 v90, v90, v110
	v_add_f32_e32 v110, v82, v114
	v_add_f32_e32 v87, v96, v109
	v_add_f32_e32 v96, v84, v115
	v_mul_f32_e32 v82, v108, v108
	v_mul_f32_e32 v84, v95, v95
	v_add_f32_e32 v88, v88, v113
	v_fmac_f32_e32 v82, v94, v94
	v_fmac_f32_e32 v84, v86, v86
	v_and_b32_e32 v105, 0xffff0000, v105
	v_add_f32_e32 v82, v82, v84
	v_mul_f32_e32 v84, v88, v88
	v_and_b32_e32 v101, 0xffff0000, v101
	v_add_f32_e32 v89, v89, v105
	v_fmac_f32_e32 v84, v87, v87
	v_add_f32_e32 v97, v97, v101
	v_add_f32_e32 v82, v84, v82
	v_mul_f32_e32 v84, v89, v89
	v_fmac_f32_e32 v84, v97, v97
	v_and_b32_e32 v106, 0xffff0000, v106
	v_add_f32_e32 v82, v84, v82
	v_mul_f32_e32 v84, v110, v110
	v_and_b32_e32 v102, 0xffff0000, v102
	v_add_f32_e32 v83, v83, v106
	v_fmac_f32_e32 v84, v90, v90
	v_add_f32_e32 v91, v91, v102
	v_add_f32_e32 v82, v84, v82
	v_mul_f32_e32 v84, v83, v83
	v_lshlrev_b32_e32 v111, 16, v103
	v_fmac_f32_e32 v84, v91, v91
	v_and_b32_e32 v107, 0xffff0000, v107
	v_add_f32_e32 v92, v92, v111
	v_add_f32_e32 v82, v84, v82
	v_mul_f32_e32 v84, v96, v96
	v_and_b32_e32 v103, 0xffff0000, v103
	v_add_f32_e32 v100, v85, v107
	v_fmac_f32_e32 v84, v92, v92
	v_add_f32_e32 v93, v93, v103
	v_add_f32_e32 v82, v84, v82
	v_mul_f32_e32 v84, v100, v100
	v_fmac_f32_e32 v84, v93, v93
	v_add_f32_e32 v82, v84, v82
	v_lshl_add_u32 v101, v98, 11, v148
	v_cvt_pk_bf16_f32 v84, v94, v86
	v_cvt_pk_bf16_f32 v85, v87, v97
	v_cvt_pk_bf16_f32 v86, v90, v91
	v_cvt_pk_bf16_f32 v87, v92, v93
	buffer_store_dwordx4 v[84:87], v101, s[64:67], 0 offen sc1
	s_nop 1
	v_cvt_pk_bf16_f32 v84, v108, v95
	v_cvt_pk_bf16_f32 v85, v88, v89
	v_cvt_pk_bf16_f32 v86, v110, v83
	ds_bpermute_b32 v83, v116, v82
	v_cvt_pk_bf16_f32 v87, v96, v100
	buffer_store_dwordx4 v[84:87], v101, s[64:67], 0 offen offset:256 sc1
	s_waitcnt lgkmcnt(0)
	v_add_f32_e32 v82, v82, v83
	ds_bpermute_b32 v83, v117, v82
	s_and_saveexec_b64 s[2:3], s[40:41]
	s_cbranch_execz .LBB0_942
	v_lshl_add_u64 v[84:85], v[98:99], 2, s[0:1]
	s_waitcnt lgkmcnt(0)
	v_add_f32_e32 v82, v82, v83
	global_atomic_add_f32 v[84:85], v82, off
.LBB0_942:
	s_or_b64 exec, exec, s[2:3]
	v_or_b32_e32 v82, 48, v142
	s_waitcnt lgkmcnt(0)
	v_ashrrev_i32_e32 v83, 31, v82
	v_lshlrev_b64 v[84:85], 11, v[82:83]
	v_lshl_add_u64 v[84:85], s[58:59], 0, v[84:85]
	v_lshl_add_u64 v[88:89], v[140:141], 1, v[84:85]
	s_waitcnt vmcnt(17)
	v_mov_b64_e32 v[84:85], v[198:199]
	v_mov_b64_e32 v[86:87], v[200:201]
	s_nop 0
	v_mov_b64_e32 v[88:89], v[202:203]
	v_mov_b64_e32 v[90:91], v[204:205]
	v_lshlrev_b32_e32 v92, 16, v84
	v_and_b32_e32 v84, 0xffff0000, v84
	v_lshlrev_b32_e32 v96, 16, v88
	v_and_b32_e32 v88, 0xffff0000, v88
	v_lshlrev_b32_e32 v93, 16, v85
	v_lshlrev_b32_e32 v94, 16, v86
	v_lshlrev_b32_e32 v98, 16, v90
	v_lshlrev_b32_e32 v99, 16, v91
	v_add_f32_e32 v78, v78, v92
	v_add_f32_e32 v92, v70, v96
	v_add_f32_e32 v70, v79, v84
	v_add_f32_e32 v79, v71, v88
	v_lshlrev_b32_e32 v97, 16, v89
	v_add_f32_e32 v74, v74, v94
	v_add_f32_e32 v94, v66, v98
	v_add_f32_e32 v71, v80, v93
	v_add_f32_e32 v80, v68, v99
	v_mul_f32_e32 v66, v92, v92
	v_mul_f32_e32 v68, v79, v79
	v_add_f32_e32 v72, v72, v97
	v_fmac_f32_e32 v66, v78, v78
	v_fmac_f32_e32 v68, v70, v70
	v_and_b32_e32 v89, 0xffff0000, v89
	v_add_f32_e32 v66, v66, v68
	v_mul_f32_e32 v68, v72, v72
	v_and_b32_e32 v85, 0xffff0000, v85
	v_add_f32_e32 v73, v73, v89
	v_fmac_f32_e32 v68, v71, v71
	v_add_f32_e32 v81, v81, v85
	v_add_f32_e32 v66, v68, v66
	v_mul_f32_e32 v68, v73, v73
	v_fmac_f32_e32 v68, v81, v81
	v_and_b32_e32 v90, 0xffff0000, v90
	v_add_f32_e32 v66, v68, v66
	v_mul_f32_e32 v68, v94, v94
	v_and_b32_e32 v86, 0xffff0000, v86
	v_add_f32_e32 v67, v67, v90
	v_fmac_f32_e32 v68, v74, v74
	v_add_f32_e32 v75, v75, v86
	v_add_f32_e32 v66, v68, v66
	v_mul_f32_e32 v68, v67, v67
	v_lshlrev_b32_e32 v95, 16, v87
	v_fmac_f32_e32 v68, v75, v75
	v_and_b32_e32 v91, 0xffff0000, v91
	v_add_f32_e32 v76, v76, v95
	v_add_f32_e32 v66, v68, v66
	v_mul_f32_e32 v68, v80, v80
	v_and_b32_e32 v87, 0xffff0000, v87
	v_add_f32_e32 v84, v69, v91
	v_fmac_f32_e32 v68, v76, v76
	v_add_f32_e32 v77, v77, v87
	v_add_f32_e32 v66, v68, v66
	v_mul_f32_e32 v68, v84, v84
	v_fmac_f32_e32 v68, v77, v77
	v_add_f32_e32 v66, v68, v66
	v_lshl_add_u32 v85, v82, 11, v148
	v_cvt_pk_bf16_f32 v68, v78, v70
	v_cvt_pk_bf16_f32 v69, v71, v81
	v_cvt_pk_bf16_f32 v70, v74, v75
	v_cvt_pk_bf16_f32 v71, v76, v77
	buffer_store_dwordx4 v[68:71], v85, s[64:67], 0 offen sc1
	s_nop 1
	v_cvt_pk_bf16_f32 v68, v92, v79
	v_cvt_pk_bf16_f32 v69, v72, v73
	v_cvt_pk_bf16_f32 v70, v94, v67
	ds_bpermute_b32 v67, v116, v66
	v_cvt_pk_bf16_f32 v71, v80, v84
	buffer_store_dwordx4 v[68:71], v85, s[64:67], 0 offen offset:256 sc1
	s_waitcnt lgkmcnt(0)
	v_add_f32_e32 v66, v66, v67
	ds_bpermute_b32 v67, v117, v66
	s_and_saveexec_b64 s[2:3], s[40:41]
	v_readlane_b32 s24, v244, 11
	v_readlane_b32 s18, v242, 47
	v_readlane_b32 s19, v242, 48
	s_cbranch_execz .LBB0_944
	v_lshl_add_u64 v[68:69], v[82:83], 2, s[0:1]
	s_waitcnt lgkmcnt(0)
	v_add_f32_e32 v66, v66, v67
	global_atomic_add_f32 v[68:69], v66, off
.LBB0_944:
	s_or_b64 exec, exec, s[2:3]
	v_add_u32_e32 v66, 0x80, v142
	s_waitcnt lgkmcnt(0)
	v_ashrrev_i32_e32 v67, 31, v66
	v_lshlrev_b64 v[68:69], 11, v[66:67]
	v_lshl_add_u64 v[68:69], s[58:59], 0, v[68:69]
	v_lshl_add_u64 v[72:73], v[140:141], 1, v[68:69]
	s_waitcnt vmcnt(18)
	v_mov_b64_e32 v[68:69], v[206:207]
	v_mov_b64_e32 v[70:71], v[208:209]
	s_nop 0
	v_mov_b64_e32 v[72:73], v[210:211]
	v_mov_b64_e32 v[74:75], v[212:213]
	v_lshlrev_b32_e32 v76, 16, v68
	v_and_b32_e32 v68, 0xffff0000, v68
	v_lshlrev_b32_e32 v80, 16, v72
	v_and_b32_e32 v72, 0xffff0000, v72
	v_lshlrev_b32_e32 v77, 16, v69
	v_lshlrev_b32_e32 v78, 16, v70
	v_lshlrev_b32_e32 v82, 16, v74
	v_lshlrev_b32_e32 v83, 16, v75
	v_add_f32_e32 v62, v62, v76
	v_add_f32_e32 v76, v54, v80
	v_add_f32_e32 v54, v63, v68
	v_add_f32_e32 v63, v55, v72
	v_lshlrev_b32_e32 v81, 16, v73
	v_add_f32_e32 v58, v58, v78
	v_add_f32_e32 v78, v50, v82
	v_add_f32_e32 v55, v64, v77
	v_add_f32_e32 v64, v52, v83
	v_mul_f32_e32 v50, v76, v76
	v_mul_f32_e32 v52, v63, v63
	v_add_f32_e32 v56, v56, v81
	v_fmac_f32_e32 v50, v62, v62
	v_fmac_f32_e32 v52, v54, v54
	v_and_b32_e32 v73, 0xffff0000, v73
	v_add_f32_e32 v50, v50, v52
	v_mul_f32_e32 v52, v56, v56
	v_and_b32_e32 v69, 0xffff0000, v69
	v_add_f32_e32 v57, v57, v73
	v_fmac_f32_e32 v52, v55, v55
	v_add_f32_e32 v65, v65, v69
	v_add_f32_e32 v50, v52, v50
	v_mul_f32_e32 v52, v57, v57
	v_fmac_f32_e32 v52, v65, v65
	v_and_b32_e32 v74, 0xffff0000, v74
	v_add_f32_e32 v50, v52, v50
	v_mul_f32_e32 v52, v78, v78
	v_and_b32_e32 v70, 0xffff0000, v70
	v_add_f32_e32 v51, v51, v74
	v_fmac_f32_e32 v52, v58, v58
	v_add_f32_e32 v59, v59, v70
	v_add_f32_e32 v50, v52, v50
	v_mul_f32_e32 v52, v51, v51
	v_lshlrev_b32_e32 v79, 16, v71
	v_fmac_f32_e32 v52, v59, v59
	v_and_b32_e32 v75, 0xffff0000, v75
	v_add_f32_e32 v60, v60, v79
	v_add_f32_e32 v50, v52, v50
	v_mul_f32_e32 v52, v64, v64
	v_and_b32_e32 v71, 0xffff0000, v71
	v_add_f32_e32 v68, v53, v75
	v_fmac_f32_e32 v52, v60, v60
	v_add_f32_e32 v61, v61, v71
	v_add_f32_e32 v50, v52, v50
	v_mul_f32_e32 v52, v68, v68
	v_fmac_f32_e32 v52, v61, v61
	v_add_f32_e32 v50, v52, v50
	v_lshl_add_u32 v69, v66, 11, v148
	v_cvt_pk_bf16_f32 v52, v62, v54
	v_cvt_pk_bf16_f32 v53, v55, v65
	v_cvt_pk_bf16_f32 v54, v58, v59
	v_cvt_pk_bf16_f32 v55, v60, v61
	buffer_store_dwordx4 v[52:55], v69, s[64:67], 0 offen sc1
	s_nop 1
	v_cvt_pk_bf16_f32 v52, v76, v63
	v_cvt_pk_bf16_f32 v53, v56, v57
	v_cvt_pk_bf16_f32 v54, v78, v51
	ds_bpermute_b32 v51, v116, v50
	v_cvt_pk_bf16_f32 v55, v64, v68
	buffer_store_dwordx4 v[52:55], v69, s[64:67], 0 offen offset:256 sc1
	s_waitcnt lgkmcnt(0)
	v_add_f32_e32 v50, v50, v51
	ds_bpermute_b32 v51, v117, v50
	s_and_saveexec_b64 s[2:3], s[40:41]
	s_cbranch_execz .LBB0_946
	v_lshl_add_u64 v[52:53], v[66:67], 2, s[0:1]
	s_waitcnt lgkmcnt(0)
	v_add_f32_e32 v50, v50, v51
	global_atomic_add_f32 v[52:53], v50, off
.LBB0_946:
	s_or_b64 exec, exec, s[2:3]
	v_add_u32_e32 v50, 0x90, v142
	s_waitcnt lgkmcnt(0)
	v_ashrrev_i32_e32 v51, 31, v50
	v_lshlrev_b64 v[52:53], 11, v[50:51]
	v_lshl_add_u64 v[52:53], s[58:59], 0, v[52:53]
	v_lshl_add_u64 v[56:57], v[140:141], 1, v[52:53]
	s_waitcnt vmcnt(19)
	v_mov_b64_e32 v[52:53], v[214:215]
	v_mov_b64_e32 v[54:55], v[216:217]
	s_nop 0
	v_mov_b64_e32 v[56:57], v[218:219]
	v_mov_b64_e32 v[58:59], v[220:221]
	v_lshlrev_b32_e32 v60, 16, v52
	v_and_b32_e32 v52, 0xffff0000, v52
	v_lshlrev_b32_e32 v64, 16, v56
	v_and_b32_e32 v56, 0xffff0000, v56
	v_lshlrev_b32_e32 v61, 16, v53
	v_lshlrev_b32_e32 v62, 16, v54
	v_lshlrev_b32_e32 v66, 16, v58
	v_lshlrev_b32_e32 v67, 16, v59
	v_add_f32_e32 v46, v46, v60
	v_add_f32_e32 v60, v38, v64
	v_add_f32_e32 v38, v47, v52
	v_add_f32_e32 v47, v39, v56
	v_lshlrev_b32_e32 v65, 16, v57
	v_add_f32_e32 v42, v42, v62
	v_add_f32_e32 v62, v34, v66
	v_add_f32_e32 v39, v48, v61
	v_add_f32_e32 v48, v36, v67
	v_mul_f32_e32 v34, v60, v60
	v_mul_f32_e32 v36, v47, v47
	v_add_f32_e32 v40, v40, v65
	v_fmac_f32_e32 v34, v46, v46
	v_fmac_f32_e32 v36, v38, v38
	v_and_b32_e32 v57, 0xffff0000, v57
	v_add_f32_e32 v34, v34, v36
	v_mul_f32_e32 v36, v40, v40
	v_and_b32_e32 v53, 0xffff0000, v53
	v_add_f32_e32 v41, v41, v57
	v_fmac_f32_e32 v36, v39, v39
	v_add_f32_e32 v49, v49, v53
	v_add_f32_e32 v34, v36, v34
	v_mul_f32_e32 v36, v41, v41
	v_fmac_f32_e32 v36, v49, v49
	v_and_b32_e32 v58, 0xffff0000, v58
	v_add_f32_e32 v34, v36, v34
	v_mul_f32_e32 v36, v62, v62
	v_and_b32_e32 v54, 0xffff0000, v54
	v_add_f32_e32 v35, v35, v58
	v_fmac_f32_e32 v36, v42, v42
	v_add_f32_e32 v43, v43, v54
	v_add_f32_e32 v34, v36, v34
	v_mul_f32_e32 v36, v35, v35
	v_lshlrev_b32_e32 v63, 16, v55
	v_fmac_f32_e32 v36, v43, v43
	v_and_b32_e32 v59, 0xffff0000, v59
	v_add_f32_e32 v44, v44, v63
	v_add_f32_e32 v34, v36, v34
	v_mul_f32_e32 v36, v48, v48
	v_and_b32_e32 v55, 0xffff0000, v55
	v_add_f32_e32 v52, v37, v59
	v_fmac_f32_e32 v36, v44, v44
	v_add_f32_e32 v45, v45, v55
	v_add_f32_e32 v34, v36, v34
	v_mul_f32_e32 v36, v52, v52
	v_fmac_f32_e32 v36, v45, v45
	v_add_f32_e32 v34, v36, v34
	v_lshl_add_u32 v53, v50, 11, v148
	v_cvt_pk_bf16_f32 v36, v46, v38
	v_cvt_pk_bf16_f32 v37, v39, v49
	v_cvt_pk_bf16_f32 v38, v42, v43
	v_cvt_pk_bf16_f32 v39, v44, v45
	buffer_store_dwordx4 v[36:39], v53, s[64:67], 0 offen sc1
	s_nop 1
	v_cvt_pk_bf16_f32 v36, v60, v47
	v_cvt_pk_bf16_f32 v37, v40, v41
	v_cvt_pk_bf16_f32 v38, v62, v35
	ds_bpermute_b32 v35, v116, v34
	v_cvt_pk_bf16_f32 v39, v48, v52
	buffer_store_dwordx4 v[36:39], v53, s[64:67], 0 offen offset:256 sc1
	s_waitcnt lgkmcnt(0)
	v_add_f32_e32 v34, v34, v35
	ds_bpermute_b32 v35, v117, v34
	s_and_saveexec_b64 s[2:3], s[40:41]
	s_cbranch_execz .LBB0_948
	v_lshl_add_u64 v[36:37], v[50:51], 2, s[0:1]
	s_waitcnt lgkmcnt(0)
	v_add_f32_e32 v34, v34, v35
	global_atomic_add_f32 v[36:37], v34, off
.LBB0_948:
	s_or_b64 exec, exec, s[2:3]
	v_add_u32_e32 v34, 0xa0, v142
	s_waitcnt lgkmcnt(0)
	v_ashrrev_i32_e32 v35, 31, v34
	v_lshlrev_b64 v[36:37], 11, v[34:35]
	v_lshl_add_u64 v[36:37], s[58:59], 0, v[36:37]
	v_lshl_add_u64 v[40:41], v[140:141], 1, v[36:37]
	s_waitcnt vmcnt(20)
	v_mov_b64_e32 v[36:37], v[222:223]
	v_mov_b64_e32 v[38:39], v[224:225]
	s_nop 0
	v_mov_b64_e32 v[40:41], v[226:227]
	v_mov_b64_e32 v[42:43], v[228:229]
	v_lshlrev_b32_e32 v44, 16, v36
	v_and_b32_e32 v36, 0xffff0000, v36
	v_lshlrev_b32_e32 v48, 16, v40
	v_and_b32_e32 v40, 0xffff0000, v40
	v_lshlrev_b32_e32 v45, 16, v37
	v_lshlrev_b32_e32 v46, 16, v38
	v_lshlrev_b32_e32 v50, 16, v42
	v_lshlrev_b32_e32 v51, 16, v43
	v_add_f32_e32 v30, v30, v44
	v_add_f32_e32 v44, v22, v48
	v_add_f32_e32 v22, v31, v36
	v_add_f32_e32 v31, v23, v40
	v_lshlrev_b32_e32 v49, 16, v41
	v_add_f32_e32 v26, v26, v46
	v_add_f32_e32 v46, v18, v50
	v_add_f32_e32 v23, v32, v45
	v_add_f32_e32 v32, v20, v51
	v_mul_f32_e32 v18, v44, v44
	v_mul_f32_e32 v20, v31, v31
	v_add_f32_e32 v24, v24, v49
	v_fmac_f32_e32 v18, v30, v30
	v_fmac_f32_e32 v20, v22, v22
	v_and_b32_e32 v41, 0xffff0000, v41
	v_add_f32_e32 v18, v18, v20
	v_mul_f32_e32 v20, v24, v24
	v_and_b32_e32 v37, 0xffff0000, v37
	v_add_f32_e32 v25, v25, v41
	v_fmac_f32_e32 v20, v23, v23
	v_add_f32_e32 v33, v33, v37
	v_add_f32_e32 v18, v20, v18
	v_mul_f32_e32 v20, v25, v25
	v_fmac_f32_e32 v20, v33, v33
	v_and_b32_e32 v42, 0xffff0000, v42
	v_add_f32_e32 v18, v20, v18
	v_mul_f32_e32 v20, v46, v46
	v_and_b32_e32 v38, 0xffff0000, v38
	v_add_f32_e32 v19, v19, v42
	v_fmac_f32_e32 v20, v26, v26
	v_add_f32_e32 v27, v27, v38
	v_add_f32_e32 v18, v20, v18
	v_mul_f32_e32 v20, v19, v19
	v_lshlrev_b32_e32 v47, 16, v39
	v_fmac_f32_e32 v20, v27, v27
	v_and_b32_e32 v43, 0xffff0000, v43
	v_add_f32_e32 v28, v28, v47
	v_add_f32_e32 v18, v20, v18
	v_mul_f32_e32 v20, v32, v32
	v_and_b32_e32 v39, 0xffff0000, v39
	v_add_f32_e32 v36, v21, v43
	v_fmac_f32_e32 v20, v28, v28
	v_add_f32_e32 v29, v29, v39
	v_add_f32_e32 v18, v20, v18
	v_mul_f32_e32 v20, v36, v36
	v_fmac_f32_e32 v20, v29, v29
	v_add_f32_e32 v18, v20, v18
	v_lshl_add_u32 v37, v34, 11, v148
	v_cvt_pk_bf16_f32 v20, v30, v22
	v_cvt_pk_bf16_f32 v21, v23, v33
	v_cvt_pk_bf16_f32 v22, v26, v27
	v_cvt_pk_bf16_f32 v23, v28, v29
	buffer_store_dwordx4 v[20:23], v37, s[64:67], 0 offen sc1
	s_nop 1
	v_cvt_pk_bf16_f32 v20, v44, v31
	v_cvt_pk_bf16_f32 v21, v24, v25
	v_cvt_pk_bf16_f32 v22, v46, v19
	ds_bpermute_b32 v19, v116, v18
	v_cvt_pk_bf16_f32 v23, v32, v36
	buffer_store_dwordx4 v[20:23], v37, s[64:67], 0 offen offset:256 sc1
	s_waitcnt lgkmcnt(0)
	v_add_f32_e32 v18, v18, v19
	ds_bpermute_b32 v19, v117, v18
	s_and_saveexec_b64 s[2:3], s[40:41]
	s_cbranch_execz .LBB0_950
	v_lshl_add_u64 v[20:21], v[34:35], 2, s[0:1]
	s_waitcnt lgkmcnt(0)
	v_add_f32_e32 v18, v18, v19
	global_atomic_add_f32 v[20:21], v18, off
.LBB0_950:
	s_or_b64 exec, exec, s[2:3]
	v_add_u32_e32 v18, 0xb0, v142
	s_waitcnt lgkmcnt(0)
	v_ashrrev_i32_e32 v19, 31, v18
	v_lshlrev_b64 v[20:21], 11, v[18:19]
	v_lshl_add_u64 v[20:21], s[58:59], 0, v[20:21]
	v_lshl_add_u64 v[24:25], v[140:141], 1, v[20:21]
	s_waitcnt vmcnt(21)
	v_mov_b64_e32 v[20:21], v[230:231]
	v_mov_b64_e32 v[22:23], v[232:233]
	s_nop 0
	v_mov_b64_e32 v[24:25], v[234:235]
	v_mov_b64_e32 v[26:27], v[236:237]
	v_lshl_add_u32 v28, v18, 11, v148
	v_lshlrev_b32_e32 v29, 16, v20
	v_lshlrev_b32_e32 v33, 16, v24
	v_and_b32_e32 v24, 0xffff0000, v24
	v_and_b32_e32 v20, 0xffff0000, v20
	v_lshlrev_b32_e32 v30, 16, v21
	v_and_b32_e32 v21, 0xffff0000, v21
	v_lshlrev_b32_e32 v34, 16, v25
	v_lshlrev_b32_e32 v35, 16, v26
	v_and_b32_e32 v26, 0xffff0000, v26
	v_lshlrev_b32_e32 v36, 16, v27
	v_and_b32_e32 v27, 0xffff0000, v27
	v_add_f32_e32 v6, v6, v33
	v_add_f32_e32 v7, v7, v24
	v_lshlrev_b32_e32 v31, 16, v22
	v_and_b32_e32 v22, 0xffff0000, v22
	v_and_b32_e32 v25, 0xffff0000, v25
	v_add_f32_e32 v14, v14, v29
	v_add_f32_e32 v15, v15, v20
	v_add_f32_e32 v20, v3, v26
	v_add_f32_e32 v3, v16, v30
	v_add_f32_e32 v8, v8, v34
	v_add_f32_e32 v16, v4, v36
	v_add_f32_e32 v4, v17, v21
	v_add_f32_e32 v17, v5, v27
	v_mul_f32_e32 v5, v6, v6
	v_mul_f32_e32 v21, v7, v7
	v_lshlrev_b32_e32 v32, 16, v23
	v_and_b32_e32 v23, 0xffff0000, v23
	v_add_f32_e32 v11, v11, v22
	v_add_f32_e32 v9, v9, v25
	v_mul_f32_e32 v22, v8, v8
	v_fmac_f32_e32 v5, v14, v14
	v_fmac_f32_e32 v21, v15, v15
	v_add_f32_e32 v29, v2, v35
	v_add_f32_e32 v13, v13, v23
	v_mul_f32_e32 v23, v9, v9
	v_fmac_f32_e32 v22, v3, v3
	v_add_f32_e32 v5, v5, v21
	v_add_f32_e32 v10, v10, v31
	v_mul_f32_e32 v24, v29, v29
	v_fmac_f32_e32 v23, v4, v4
	v_add_f32_e32 v5, v22, v5
	v_mul_f32_e32 v25, v20, v20
	v_fmac_f32_e32 v24, v10, v10
	v_add_f32_e32 v5, v23, v5
	v_add_f32_e32 v12, v12, v32
	v_mul_f32_e32 v26, v16, v16
	v_fmac_f32_e32 v25, v11, v11
	v_add_f32_e32 v5, v24, v5
	v_mul_f32_e32 v27, v17, v17
	v_fmac_f32_e32 v26, v12, v12
	v_add_f32_e32 v5, v25, v5
	v_fmac_f32_e32 v27, v13, v13
	v_add_f32_e32 v5, v26, v5
	v_cvt_pk_bf16_f32 v2, v14, v15
	v_add_f32_e32 v14, v27, v5
	ds_bpermute_b32 v15, v116, v14
	v_cvt_pk_bf16_f32 v3, v3, v4
	v_cvt_pk_bf16_f32 v4, v10, v11
	v_cvt_pk_bf16_f32 v5, v12, v13
	buffer_store_dwordx4 v[2:5], v28, s[64:67], 0 offen sc1
	s_waitcnt lgkmcnt(0)
	s_nop 0
	v_add_f32_e32 v2, v14, v15
	ds_bpermute_b32 v3, v117, v2
	v_cvt_pk_bf16_f32 v4, v6, v7
	v_cvt_pk_bf16_f32 v5, v8, v9
	v_cvt_pk_bf16_f32 v6, v29, v20
	v_cvt_pk_bf16_f32 v7, v16, v17
	buffer_store_dwordx4 v[4:7], v28, s[64:67], 0 offen offset:256 sc1
	s_and_saveexec_b64 s[2:3], s[40:41]
	s_cbranch_execz .LBB0_927
	v_lshl_add_u64 v[4:5], v[18:19], 2, s[0:1]
	s_waitcnt lgkmcnt(0)
	v_add_f32_e32 v2, v2, v3
	global_atomic_add_f32 v[4:5], v2, off
	s_branch .LBB0_927

	.amdhsa_kernel _Z14fwd_megakernel6Params
		.amdhsa_group_segment_fixed_size 32
		.amdhsa_private_segment_fixed_size 0
		.amdhsa_kernarg_size 472
		.amdhsa_user_sgpr_count 2
		.amdhsa_user_sgpr_dispatch_ptr 0
		.amdhsa_user_sgpr_queue_ptr 0
		.amdhsa_user_sgpr_kernarg_segment_ptr 1
		.amdhsa_user_sgpr_dispatch_id 0
		.amdhsa_user_sgpr_kernarg_preload_length 0
		.amdhsa_user_sgpr_kernarg_preload_offset 0
		.amdhsa_user_sgpr_private_segment_size 0
		.amdhsa_uses_dynamic_stack 0
		.amdhsa_enable_private_segment 0
		.amdhsa_system_sgpr_workgroup_id_x 1
		.amdhsa_system_sgpr_workgroup_id_y 0
		.amdhsa_system_sgpr_workgroup_id_z 0
		.amdhsa_system_sgpr_workgroup_info 0
		.amdhsa_system_vgpr_workitem_id 0
		.amdhsa_next_free_vgpr 245
		.amdhsa_next_free_sgpr 102
		.amdhsa_accum_offset 248
		.amdhsa_reserve_vcc 1
		.amdhsa_float_round_mode_32 0
		.amdhsa_float_round_mode_16_64 0
		.amdhsa_float_denorm_mode_32 3
		.amdhsa_float_denorm_mode_16_64 3
		.amdhsa_dx10_clamp 1
		.amdhsa_ieee_mode 1
		.amdhsa_fp16_overflow 0
		.amdhsa_tg_split 0
		.amdhsa_exception_fp_ieee_invalid_op 0
		.amdhsa_exception_fp_denorm_src 0
		.amdhsa_exception_fp_ieee_div_zero 0
		.amdhsa_exception_fp_ieee_overflow 0
		.amdhsa_exception_fp_ieee_underflow 0
		.amdhsa_exception_fp_ieee_inexact 0
		.amdhsa_exception_int_div_zero 0
	.end_amdhsa_kernel

amdhsa.kernels:
  - .agpr_count:     0
    .args:
      - .offset:         0
        .size:           216
        .value_kind:     by_value
      - .offset:         216
        .size:           4
        .value_kind:     hidden_block_count_x
      - .offset:         220
        .size:           4
        .value_kind:     hidden_block_count_y
      - .offset:         224
        .size:           4
        .value_kind:     hidden_block_count_z
      - .offset:         228
        .size:           2
        .value_kind:     hidden_group_size_x
      - .offset:         230
        .size:           2
        .value_kind:     hidden_group_size_y
      - .offset:         232
        .size:           2
        .value_kind:     hidden_group_size_z
      - .offset:         234
        .size:           2
        .value_kind:     hidden_remainder_x
      - .offset:         236
        .size:           2
        .value_kind:     hidden_remainder_y
      - .offset:         238
        .size:           2
        .value_kind:     hidden_remainder_z
      - .offset:         256
        .size:           8
        .value_kind:     hidden_global_offset_x
      - .offset:         264
        .size:           8
        .value_kind:     hidden_global_offset_y
      - .offset:         272
        .size:           8
        .value_kind:     hidden_global_offset_z
      - .offset:         280
        .size:           2
        .value_kind:     hidden_grid_dims
      - .offset:         336
        .size:           4
        .value_kind:     hidden_dynamic_lds_size
    .group_segment_fixed_size: 32
    .kernarg_segment_align: 8
    .kernarg_segment_size: 472
    .language:       OpenCL C
    .language_version:
      - 2
      - 0
    .max_flat_workgroup_size: 512
    .name:           _Z14fwd_megakernel6Params
    .private_segment_fixed_size: 0
    .sgpr_count:     108
    .sgpr_spill_count: 192
    .symbol:         _Z14fwd_megakernel6Params.kd
    .uniform_work_group_size: 1
    .uses_dynamic_stack: false
    .vgpr_count:     245
    .vgpr_spill_count: 0
    .wavefront_size: 64
